# Resid GEMM epilogues (5 phases): bf16 dwordx2 stores of adjacent 16-col blocks merged into dwordx4 via v_permlane16_swap_b32
# speedup vs baseline: 1.0216x; 1.0094x over previous
.LBB0_397:
	ds_read_b128 v[128:131], v187
	ds_read_b128 v[132:135], v188
	ds_read_b128 v[136:139], v189
	ds_read_b128 v[140:143], v190
	s_add_u32 s20, s16, 0xfff50080
	s_addc_u32 s21, s17, -1
	s_cmp_eq_u32 s19, 40
	s_cselect_b32 s57, s13, s21
	s_cselect_b32 s56, s12, s20
	s_cselect_b32 s39, s15, s18
	s_cselect_b32 s38, s14, s37
	s_mov_b32 m0, s90
	v_lshl_add_u64 v[228:229], s[16:17], 0, v[158:159]
	ds_read_b128 v[164:167], v145
	ds_read_b128 v[168:171], v145 offset:1024
	ds_read_b128 v[204:207], v145 offset:2048
	ds_read_b128 v[208:211], v145 offset:3072
	ds_read_b128 v[212:215], v145 offset:4096
	ds_read_b128 v[216:219], v145 offset:5120
	ds_read_b128 v[220:223], v145 offset:6144
	ds_read_b128 v[224:227], v145 offset:7168
	global_load_lds_dwordx4 v[228:229], off
	v_lshl_add_u64 v[228:229], s[16:17], 0, v[156:157]
	s_mov_b32 m0, s91
	s_nop 0
	global_load_lds_dwordx4 v[228:229], off
	s_waitcnt lgkmcnt(8)
	s_barrier
	s_waitcnt lgkmcnt(0)
	s_setprio 1
	s_waitcnt lgkmcnt(0)
	v_mfma_f32_16x16x32_bf16 v[124:127], v[128:131], v[164:167], v[124:127]
	v_mfma_f32_16x16x32_bf16 v[120:123], v[136:139], v[164:167], v[120:123]
	v_mfma_f32_16x16x32_bf16 v[108:111], v[128:131], v[204:207], v[108:111]
	v_mfma_f32_16x16x32_bf16 v[104:107], v[136:139], v[204:207], v[104:107]
	v_mfma_f32_16x16x32_bf16 v[92:95], v[128:131], v[212:215], v[92:95]
	v_mfma_f32_16x16x32_bf16 v[88:91], v[136:139], v[212:215], v[88:91]
	v_mfma_f32_16x16x32_bf16 v[76:79], v[128:131], v[220:223], v[76:79]
	v_mfma_f32_16x16x32_bf16 v[72:75], v[136:139], v[220:223], v[72:75]
	v_mfma_f32_16x16x32_bf16 v[124:127], v[132:135], v[168:171], v[124:127]
	v_mfma_f32_16x16x32_bf16 v[120:123], v[140:143], v[168:171], v[120:123]
	v_mfma_f32_16x16x32_bf16 v[108:111], v[132:135], v[208:211], v[108:111]
	v_mfma_f32_16x16x32_bf16 v[104:107], v[140:143], v[208:211], v[104:107]
	v_mfma_f32_16x16x32_bf16 v[92:95], v[132:135], v[216:219], v[92:95]
	v_mfma_f32_16x16x32_bf16 v[88:91], v[140:143], v[216:219], v[88:91]
	v_mfma_f32_16x16x32_bf16 v[76:79], v[132:135], v[224:227], v[76:79]
	v_mfma_f32_16x16x32_bf16 v[72:75], v[140:143], v[224:227], v[72:75]
	s_setprio 0
	s_barrier
	s_mov_b32 m0, s68
	v_lshl_add_u64 v[244:245], s[38:39], 0, v[146:147]
	ds_read_b128 v[228:231], v191
	ds_read_b128 v[232:235], v192
	ds_read_b128 v[236:239], v193
	ds_read_b128 v[240:243], v194
	global_load_lds_dwordx4 v[244:245], off
	v_lshl_add_u64 v[246:247], s[38:39], 0, v[148:149]
	s_mov_b32 m0, s69
	s_nop 0
	global_load_lds_dwordx4 v[246:247], off
	s_barrier
	s_waitcnt lgkmcnt(0)
	s_setprio 1
	s_waitcnt lgkmcnt(0)
	v_mfma_f32_16x16x32_bf16 v[116:119], v[228:231], v[164:167], v[116:119]
	v_mfma_f32_16x16x32_bf16 v[112:115], v[236:239], v[164:167], v[112:115]
	v_mfma_f32_16x16x32_bf16 v[100:103], v[228:231], v[204:207], v[100:103]
	v_mfma_f32_16x16x32_bf16 v[96:99], v[236:239], v[204:207], v[96:99]
	v_mfma_f32_16x16x32_bf16 v[84:87], v[228:231], v[212:215], v[84:87]
	v_mfma_f32_16x16x32_bf16 v[80:83], v[236:239], v[212:215], v[80:83]
	v_mfma_f32_16x16x32_bf16 v[68:71], v[228:231], v[220:223], v[68:71]
	v_mfma_f32_16x16x32_bf16 v[64:67], v[236:239], v[220:223], v[64:67]
	v_mfma_f32_16x16x32_bf16 v[116:119], v[232:235], v[168:171], v[116:119]
	v_mfma_f32_16x16x32_bf16 v[112:115], v[240:243], v[168:171], v[112:115]
	v_mfma_f32_16x16x32_bf16 v[100:103], v[232:235], v[208:211], v[100:103]
	v_mfma_f32_16x16x32_bf16 v[96:99], v[240:243], v[208:211], v[96:99]
	v_mfma_f32_16x16x32_bf16 v[84:87], v[232:235], v[216:219], v[84:87]
	v_mfma_f32_16x16x32_bf16 v[80:83], v[240:243], v[216:219], v[80:83]
	v_mfma_f32_16x16x32_bf16 v[68:71], v[232:235], v[224:227], v[68:71]
	v_mfma_f32_16x16x32_bf16 v[64:67], v[240:243], v[224:227], v[64:67]
	s_setprio 0
	s_mov_b32 m0, s67
	v_lshl_add_u64 v[248:249], s[56:57], 0, v[146:147]
	s_barrier
	ds_read_b128 v[164:167], v145 offset:16384
	ds_read_b128 v[168:171], v145 offset:17408
	ds_read_b128 v[204:207], v145 offset:18432
	ds_read_b128 v[208:211], v145 offset:19456
	ds_read_b128 v[212:215], v145 offset:20480
	ds_read_b128 v[216:219], v145 offset:21504
	ds_read_b128 v[220:223], v145 offset:22528
	ds_read_b128 v[224:227], v145 offset:23552
	global_load_lds_dwordx4 v[248:249], off
	v_lshl_add_u64 v[250:251], s[56:57], 0, v[148:149]
	s_mov_b32 m0, s70
	s_nop 0
	global_load_lds_dwordx4 v[250:251], off
	s_barrier
	s_waitcnt lgkmcnt(0)
	s_setprio 1
	s_waitcnt lgkmcnt(0)
	v_mfma_f32_16x16x32_bf16 v[60:63], v[128:131], v[164:167], v[60:63]
	v_mfma_f32_16x16x32_bf16 v[56:59], v[136:139], v[164:167], v[56:59]
	v_mfma_f32_16x16x32_bf16 v[44:47], v[128:131], v[204:207], v[44:47]
	v_mfma_f32_16x16x32_bf16 v[40:43], v[136:139], v[204:207], v[40:43]
	v_mfma_f32_16x16x32_bf16 v[28:31], v[128:131], v[212:215], v[28:31]
	v_mfma_f32_16x16x32_bf16 v[24:27], v[136:139], v[212:215], v[24:27]
	v_mfma_f32_16x16x32_bf16 v[12:15], v[128:131], v[220:223], v[12:15]
	v_mfma_f32_16x16x32_bf16 v[8:11], v[136:139], v[220:223], v[8:11]
	v_mfma_f32_16x16x32_bf16 v[60:63], v[132:135], v[168:171], v[60:63]
	v_mfma_f32_16x16x32_bf16 v[56:59], v[140:143], v[168:171], v[56:59]
	v_mfma_f32_16x16x32_bf16 v[44:47], v[132:135], v[208:211], v[44:47]
	v_mfma_f32_16x16x32_bf16 v[40:43], v[140:143], v[208:211], v[40:43]
	v_mfma_f32_16x16x32_bf16 v[28:31], v[132:135], v[216:219], v[28:31]
	v_mfma_f32_16x16x32_bf16 v[24:27], v[140:143], v[216:219], v[24:27]
	v_mfma_f32_16x16x32_bf16 v[12:15], v[132:135], v[224:227], v[12:15]
	v_mfma_f32_16x16x32_bf16 v[8:11], v[140:143], v[224:227], v[8:11]
	s_setprio 0
	s_barrier
	s_add_u32 s20, s38, 0xb0000
	s_addc_u32 s21, s39, 0
	s_mov_b32 m0, s71
	v_lshl_add_u64 v[128:129], s[20:21], 0, v[146:147]
	global_load_lds_dwordx4 v[128:129], off
	v_lshl_add_u64 v[128:129], s[20:21], 0, v[148:149]
	s_mov_b32 m0, s80
	s_nop 0
	global_load_lds_dwordx4 v[128:129], off
	s_waitcnt vmcnt(6)
	s_barrier
	s_setprio 1
	v_mfma_f32_16x16x32_bf16 v[52:55], v[228:231], v[164:167], v[52:55]
	v_mfma_f32_16x16x32_bf16 v[48:51], v[236:239], v[164:167], v[48:51]
	v_mfma_f32_16x16x32_bf16 v[36:39], v[228:231], v[204:207], v[36:39]
	v_mfma_f32_16x16x32_bf16 v[32:35], v[236:239], v[204:207], v[32:35]
	v_mfma_f32_16x16x32_bf16 v[20:23], v[228:231], v[212:215], v[20:23]
	v_mfma_f32_16x16x32_bf16 v[16:19], v[236:239], v[212:215], v[16:19]
	v_mfma_f32_16x16x32_bf16 v[4:7], v[228:231], v[220:223], v[4:7]
	v_mfma_f32_16x16x32_bf16 v[0:3], v[236:239], v[220:223], v[0:3]
	v_mfma_f32_16x16x32_bf16 v[52:55], v[232:235], v[168:171], v[52:55]
	v_mfma_f32_16x16x32_bf16 v[48:51], v[240:243], v[168:171], v[48:51]
	v_mfma_f32_16x16x32_bf16 v[36:39], v[232:235], v[208:211], v[36:39]
	v_mfma_f32_16x16x32_bf16 v[32:35], v[240:243], v[208:211], v[32:35]
	v_mfma_f32_16x16x32_bf16 v[20:23], v[232:235], v[216:219], v[20:23]
	v_mfma_f32_16x16x32_bf16 v[16:19], v[240:243], v[216:219], v[16:19]
	v_mfma_f32_16x16x32_bf16 v[4:7], v[232:235], v[224:227], v[4:7]
	v_mfma_f32_16x16x32_bf16 v[0:3], v[240:243], v[224:227], v[0:3]
	s_setprio 0
	s_barrier
	ds_read_b128 v[128:131], v195
	ds_read_b128 v[132:135], v196
	ds_read_b128 v[136:139], v197
	ds_read_b128 v[140:143], v198
	s_add_u32 s20, s56, 0xb0000
	s_addc_u32 s21, s57, 0
	s_mov_b32 m0, s81
	v_lshl_add_u64 v[228:229], s[20:21], 0, v[146:147]
	ds_read_b128 v[164:167], v145 offset:32768
	ds_read_b128 v[168:171], v145 offset:33792
	ds_read_b128 v[204:207], v145 offset:34816
	ds_read_b128 v[208:211], v145 offset:35840
	ds_read_b128 v[212:215], v145 offset:36864
	ds_read_b128 v[216:219], v145 offset:37888
	ds_read_b128 v[220:223], v145 offset:38912
	ds_read_b128 v[224:227], v145 offset:39936
	global_load_lds_dwordx4 v[228:229], off
	v_lshl_add_u64 v[228:229], s[20:21], 0, v[148:149]
	s_mov_b32 m0, s82
	s_nop 0
	global_load_lds_dwordx4 v[228:229], off
	s_waitcnt lgkmcnt(8)
	s_barrier
	s_waitcnt lgkmcnt(0)
	s_setprio 1
	s_waitcnt lgkmcnt(0)
	v_mfma_f32_16x16x32_bf16 v[124:127], v[128:131], v[164:167], v[124:127]
	v_mfma_f32_16x16x32_bf16 v[120:123], v[136:139], v[164:167], v[120:123]
	v_mfma_f32_16x16x32_bf16 v[108:111], v[128:131], v[204:207], v[108:111]
	v_mfma_f32_16x16x32_bf16 v[104:107], v[136:139], v[204:207], v[104:107]
	v_mfma_f32_16x16x32_bf16 v[92:95], v[128:131], v[212:215], v[92:95]
	v_mfma_f32_16x16x32_bf16 v[88:91], v[136:139], v[212:215], v[88:91]
	v_mfma_f32_16x16x32_bf16 v[76:79], v[128:131], v[220:223], v[76:79]
	v_mfma_f32_16x16x32_bf16 v[72:75], v[136:139], v[220:223], v[72:75]
	v_mfma_f32_16x16x32_bf16 v[124:127], v[132:135], v[168:171], v[124:127]
	v_mfma_f32_16x16x32_bf16 v[120:123], v[140:143], v[168:171], v[120:123]
	v_mfma_f32_16x16x32_bf16 v[108:111], v[132:135], v[208:211], v[108:111]
	v_mfma_f32_16x16x32_bf16 v[104:107], v[140:143], v[208:211], v[104:107]
	v_mfma_f32_16x16x32_bf16 v[92:95], v[132:135], v[216:219], v[92:95]
	v_mfma_f32_16x16x32_bf16 v[88:91], v[140:143], v[216:219], v[88:91]
	v_mfma_f32_16x16x32_bf16 v[76:79], v[132:135], v[224:227], v[76:79]
	v_mfma_f32_16x16x32_bf16 v[72:75], v[140:143], v[224:227], v[72:75]
	s_setprio 0
	s_barrier
	s_mov_b32 m0, s84
	v_lshl_add_u64 v[244:245], v[244:245], 0, s[4:5]
	ds_read_b128 v[228:231], v199
	ds_read_b128 v[232:235], v200
	ds_read_b128 v[236:239], v201
	ds_read_b128 v[240:243], v202
	global_load_lds_dwordx4 v[244:245], off
	v_lshl_add_u64 v[244:245], v[246:247], 0, s[4:5]
	s_mov_b32 m0, s85
	s_nop 0
	global_load_lds_dwordx4 v[244:245], off
	s_barrier
	s_waitcnt lgkmcnt(0)
	s_setprio 1
	s_waitcnt lgkmcnt(0)
	v_mfma_f32_16x16x32_bf16 v[116:119], v[228:231], v[164:167], v[116:119]
	v_mfma_f32_16x16x32_bf16 v[112:115], v[236:239], v[164:167], v[112:115]
	v_mfma_f32_16x16x32_bf16 v[100:103], v[228:231], v[204:207], v[100:103]
	v_mfma_f32_16x16x32_bf16 v[96:99], v[236:239], v[204:207], v[96:99]
	v_mfma_f32_16x16x32_bf16 v[84:87], v[228:231], v[212:215], v[84:87]
	v_mfma_f32_16x16x32_bf16 v[80:83], v[236:239], v[212:215], v[80:83]
	v_mfma_f32_16x16x32_bf16 v[68:71], v[228:231], v[220:223], v[68:71]
	v_mfma_f32_16x16x32_bf16 v[64:67], v[236:239], v[220:223], v[64:67]
	v_mfma_f32_16x16x32_bf16 v[116:119], v[232:235], v[168:171], v[116:119]
	v_mfma_f32_16x16x32_bf16 v[112:115], v[240:243], v[168:171], v[112:115]
	v_mfma_f32_16x16x32_bf16 v[100:103], v[232:235], v[208:211], v[100:103]
	v_mfma_f32_16x16x32_bf16 v[96:99], v[240:243], v[208:211], v[96:99]
	v_mfma_f32_16x16x32_bf16 v[84:87], v[232:235], v[216:219], v[84:87]
	v_mfma_f32_16x16x32_bf16 v[80:83], v[240:243], v[216:219], v[80:83]
	v_mfma_f32_16x16x32_bf16 v[68:71], v[232:235], v[224:227], v[68:71]
	v_mfma_f32_16x16x32_bf16 v[64:67], v[240:243], v[224:227], v[64:67]
	s_setprio 0
	s_mov_b32 m0, s86
	v_lshl_add_u64 v[244:245], v[248:249], 0, s[4:5]
	s_barrier
	ds_read_b128 v[164:167], v145 offset:49152
	ds_read_b128 v[168:171], v145 offset:50176
	ds_read_b128 v[204:207], v145 offset:51200
	ds_read_b128 v[208:211], v145 offset:52224
	ds_read_b128 v[212:215], v145 offset:53248
	ds_read_b128 v[216:219], v145 offset:54272
	ds_read_b128 v[220:223], v145 offset:55296
	ds_read_b128 v[224:227], v145 offset:56320
	global_load_lds_dwordx4 v[244:245], off
	v_lshl_add_u64 v[244:245], v[250:251], 0, s[4:5]
	s_mov_b32 m0, s87
	s_nop 0
	global_load_lds_dwordx4 v[244:245], off
	s_barrier
	s_waitcnt lgkmcnt(0)
	s_setprio 1
	s_waitcnt lgkmcnt(0)
	v_mfma_f32_16x16x32_bf16 v[60:63], v[128:131], v[164:167], v[60:63]
	v_mfma_f32_16x16x32_bf16 v[56:59], v[136:139], v[164:167], v[56:59]
	v_mfma_f32_16x16x32_bf16 v[44:47], v[128:131], v[204:207], v[44:47]
	v_mfma_f32_16x16x32_bf16 v[40:43], v[136:139], v[204:207], v[40:43]
	v_mfma_f32_16x16x32_bf16 v[28:31], v[128:131], v[212:215], v[28:31]
	v_mfma_f32_16x16x32_bf16 v[24:27], v[136:139], v[212:215], v[24:27]
	v_mfma_f32_16x16x32_bf16 v[12:15], v[128:131], v[220:223], v[12:15]
	v_mfma_f32_16x16x32_bf16 v[8:11], v[136:139], v[220:223], v[8:11]
	v_mfma_f32_16x16x32_bf16 v[60:63], v[132:135], v[168:171], v[60:63]
	v_mfma_f32_16x16x32_bf16 v[56:59], v[140:143], v[168:171], v[56:59]
	v_mfma_f32_16x16x32_bf16 v[44:47], v[132:135], v[208:211], v[44:47]
	v_mfma_f32_16x16x32_bf16 v[40:43], v[140:143], v[208:211], v[40:43]
	v_mfma_f32_16x16x32_bf16 v[28:31], v[132:135], v[216:219], v[28:31]
	v_mfma_f32_16x16x32_bf16 v[24:27], v[140:143], v[216:219], v[24:27]
	v_mfma_f32_16x16x32_bf16 v[12:15], v[132:135], v[224:227], v[12:15]
	v_mfma_f32_16x16x32_bf16 v[8:11], v[140:143], v[224:227], v[8:11]
	s_setprio 0
	s_barrier
	s_add_u32 s20, s38, 0xb0080
	s_addc_u32 s21, s39, 0
	s_mov_b32 m0, s88
	v_lshl_add_u64 v[128:129], s[20:21], 0, v[146:147]
	global_load_lds_dwordx4 v[128:129], off
	v_lshl_add_u64 v[128:129], s[20:21], 0, v[148:149]
	s_mov_b32 m0, s89
	s_nop 0
	global_load_lds_dwordx4 v[128:129], off
	s_waitcnt vmcnt(6)
	s_barrier
	s_setprio 1
	v_mfma_f32_16x16x32_bf16 v[52:55], v[228:231], v[164:167], v[52:55]
	v_mfma_f32_16x16x32_bf16 v[48:51], v[236:239], v[164:167], v[48:51]
	v_mfma_f32_16x16x32_bf16 v[36:39], v[228:231], v[204:207], v[36:39]
	v_mfma_f32_16x16x32_bf16 v[32:35], v[236:239], v[204:207], v[32:35]
	v_mfma_f32_16x16x32_bf16 v[20:23], v[228:231], v[212:215], v[20:23]
	v_mfma_f32_16x16x32_bf16 v[16:19], v[236:239], v[212:215], v[16:19]
	v_mfma_f32_16x16x32_bf16 v[4:7], v[228:231], v[220:223], v[4:7]
	v_mfma_f32_16x16x32_bf16 v[0:3], v[236:239], v[220:223], v[0:3]
	v_mfma_f32_16x16x32_bf16 v[52:55], v[232:235], v[168:171], v[52:55]
	v_mfma_f32_16x16x32_bf16 v[48:51], v[240:243], v[168:171], v[48:51]
	v_mfma_f32_16x16x32_bf16 v[36:39], v[232:235], v[208:211], v[36:39]
	v_mfma_f32_16x16x32_bf16 v[32:35], v[240:243], v[208:211], v[32:35]
	v_mfma_f32_16x16x32_bf16 v[20:23], v[232:235], v[216:219], v[20:23]
	v_mfma_f32_16x16x32_bf16 v[16:19], v[240:243], v[216:219], v[16:19]
	v_mfma_f32_16x16x32_bf16 v[4:7], v[232:235], v[224:227], v[4:7]
	v_mfma_f32_16x16x32_bf16 v[0:3], v[240:243], v[224:227], v[0:3]
	s_setprio 0
	s_add_i32 s19, s19, 2
	s_add_u32 s37, s37, 0x100
	s_addc_u32 s18, s18, 0
	s_add_u32 s16, s16, 0x100
	s_addc_u32 s17, s17, 0
	s_cmp_gt_u32 s19, 41
	s_barrier
	s_cbranch_scc0 .LBB0_397
	s_ashr_i32 s37, s36, 31
	s_lshl_b64 s[16:17], s[36:37], 8
	s_lshl_b32 s18, s6, 8
	v_lshl_add_u64 v[166:167], s[16:17], 0, v[150:151]
	s_ashr_i32 s19, s18, 31
	v_lshl_add_u64 v[168:169], s[18:19], 2, v[154:155]
	v_lshlrev_b64 v[128:129], 12, v[166:167]
	v_lshl_add_u64 v[128:129], v[168:169], 0, v[128:129]
	global_load_dwordx4 v[204:207], v[128:129], off
	global_load_dwordx4 v[208:211], v[128:129], off offset:64
	global_load_dwordx4 v[212:215], v[128:129], off offset:512
	global_load_dwordx4 v[216:219], v[128:129], off offset:576
	v_or_b32_e32 v170, 16, v166
	v_mov_b32_e32 v171, v167
	v_lshlrev_b64 v[128:129], 12, v[170:171]
	v_lshl_add_u64 v[128:129], v[168:169], 0, v[128:129]
	global_load_dwordx4 v[140:143], v[128:129], off
	global_load_dwordx4 v[136:139], v[128:129], off offset:64
	global_load_dwordx4 v[132:135], v[128:129], off offset:512
	s_nop 0
	global_load_dwordx4 v[128:131], v[128:129], off offset:576
	v_mov_b32_e32 v165, s19
	v_or_b32_e32 v164, s18, v152
	v_lshlrev_b64 v[220:221], 10, v[166:167]
	v_lshl_add_u64 v[220:221], v[220:221], 0, v[164:165]
	s_waitcnt vmcnt(0)
	s_lshl_b32 s16, s6, 2
	s_ashr_i32 s17, s16, 31
	s_waitcnt vmcnt(0)
	v_pk_fma_f32 v[126:127], v[126:127], 0.5, v[206:207] op_sel_hi:[1,0,1]
	v_lshlrev_b64 v[206:207], 1, v[220:221]
	v_pk_fma_f32 v[124:125], v[124:125], 0.5, v[204:205] op_sel_hi:[1,0,1]
	v_lshl_add_u64 v[204:205], v[220:221], 2, s[78:79]
	v_lshl_add_u64 v[220:221], s[0:1], 0, v[206:207]
	global_store_dwordx4 v[204:205], v[124:127], off
	v_cvt_pk_bf16_f32 v222, v124, v125
	v_cvt_pk_bf16_f32 v223, v126, v127
	v_bfe_u32 v246, v176, 4, 1
	v_mul_u32_u24_e32 v246, 24, v246
	v_mov_b32_e32 v247, 0
	s_nop 1
	v_mov_b32_e32 v240, v222
	v_mov_b32_e32 v241, v223
	v_lshl_add_u64 v[244:245], v[220:221], 0, v[246:247]
	v_mul_f32_e32 v220, v124, v124
	v_fmac_f32_e32 v220, v125, v125
	v_pk_fma_f32 v[122:123], v[122:123], 0.5, v[210:211] op_sel_hi:[1,0,1]
	v_pk_fma_f32 v[120:121], v[120:121], 0.5, v[208:209] op_sel_hi:[1,0,1]
	v_fmac_f32_e32 v220, v126, v126
	global_store_dwordx4 v[204:205], v[120:123], off offset:64
	v_cvt_pk_bf16_f32 v126, v120, v121
	v_or_b32_e32 v124, 32, v206
	v_mov_b32_e32 v125, v207
	v_mul_f32_e32 v120, v120, v120
	v_fmac_f32_e32 v120, v121, v121
	v_fmac_f32_e32 v120, v122, v122
	v_fmac_f32_e32 v220, v127, v127
	v_lshl_add_u64 v[124:125], s[0:1], 0, v[124:125]
	v_fmac_f32_e32 v120, v123, v123
	v_pk_fma_f32 v[118:119], v[118:119], 0.5, v[214:215] op_sel_hi:[1,0,1]
	v_pk_fma_f32 v[116:117], v[116:117], 0.5, v[212:213] op_sel_hi:[1,0,1]
	v_cvt_pk_bf16_f32 v127, v122, v123
	v_mov_b32_e32 v242, v126
	v_mov_b32_e32 v243, v127
	s_nop 1
	v_permlane16_swap_b32 v240, v242
	v_permlane16_swap_b32 v241, v243
	global_store_dwordx4 v[244:245], v[240:243], off
	v_add_f32_e32 v124, v220, v120
	global_store_dwordx4 v[204:205], v[116:119], off offset:512
	v_or_b32_e32 v120, 0x100, v206
	v_mov_b32_e32 v121, v207
	v_cvt_pk_bf16_f32 v122, v116, v117
	v_mul_f32_e32 v116, v116, v116
	v_lshl_add_u64 v[120:121], s[0:1], 0, v[120:121]
	v_fmac_f32_e32 v116, v117, v117
	v_pk_fma_f32 v[114:115], v[114:115], 0.5, v[218:219] op_sel_hi:[1,0,1]
	v_pk_fma_f32 v[112:113], v[112:113], 0.5, v[216:217] op_sel_hi:[1,0,1]
	v_cvt_pk_bf16_f32 v123, v118, v119
	s_nop 1
	v_mov_b32_e32 v240, v122
	v_mov_b32_e32 v241, v123
	v_lshl_add_u64 v[244:245], v[120:121], 0, v[246:247]
	v_fmac_f32_e32 v116, v118, v118
	global_store_dwordx4 v[204:205], v[112:115], off offset:576
	v_cvt_pk_bf16_f32 v118, v112, v113
	v_fmac_f32_e32 v116, v119, v119
	v_cvt_pk_bf16_f32 v119, v114, v115
	v_or_b32_e32 v206, 0x120, v206
	v_mul_f32_e32 v112, v112, v112
	v_fmac_f32_e32 v112, v113, v113
	v_fmac_f32_e32 v112, v114, v114
	v_and_b32_e32 v114, 64, v203
	v_xor_b32_e32 v113, 16, v203
	v_add_u32_e32 v114, 64, v114
	v_cmp_lt_i32_e32 vcc, v113, v114
	v_add_f32_e32 v120, v124, v116
	v_lshl_add_u64 v[116:117], s[0:1], 0, v[206:207]
	v_fmac_f32_e32 v112, v115, v115
	v_cndmask_b32_e32 v113, v203, v113, vcc
	v_mov_b32_e32 v242, v118
	v_mov_b32_e32 v243, v119
	s_nop 1
	v_permlane16_swap_b32 v240, v242
	v_permlane16_swap_b32 v241, v243
	global_store_dwordx4 v[244:245], v[240:243], off
	v_add_f32_e32 v112, v120, v112
	v_lshlrev_b32_e32 v116, 2, v113
	ds_bpermute_b32 v113, v116, v112
	s_waitcnt lgkmcnt(0)
	v_add_f32_e32 v112, v112, v113
	v_xor_b32_e32 v113, 32, v203
	v_cmp_lt_i32_e32 vcc, v113, v114
	s_nop 1
	v_cndmask_b32_e32 v113, v203, v113, vcc
	v_lshlrev_b32_e32 v117, 2, v113
	ds_bpermute_b32 v113, v117, v112
	s_and_saveexec_b64 s[36:37], s[8:9]
	s_cbranch_execz .LBB0_400
	v_lshlrev_b64 v[114:115], 6, v[166:167]
	v_lshl_add_u64 v[114:115], s[2:3], 0, v[114:115]
	v_lshl_add_u64 v[114:115], s[16:17], 2, v[114:115]
	s_lshl_b32 s6, s83, 2
	v_lshl_add_u64 v[114:115], v[114:115], 0, s[6:7]
	s_waitcnt lgkmcnt(0)
	v_add_f32_e32 v112, v112, v113
	flat_store_dword v[114:115], v112
.LBB0_400:
	s_or_b64 exec, exec, s[36:37]
	s_waitcnt lgkmcnt(0)
	v_lshlrev_b64 v[112:113], 10, v[170:171]
	v_lshl_add_u64 v[112:113], v[112:113], 0, v[164:165]
	v_lshl_add_u64 v[114:115], v[112:113], 2, s[78:79]
	v_lshlrev_b64 v[112:113], 1, v[112:113]
	v_pk_fma_f32 v[110:111], v[110:111], 0.5, v[142:143] op_sel_hi:[1,0,1]
	v_pk_fma_f32 v[108:109], v[108:109], 0.5, v[140:141] op_sel_hi:[1,0,1]
	v_lshl_add_u64 v[118:119], s[0:1], 0, v[112:113]
	global_store_dwordx4 v[114:115], v[108:111], off
	v_cvt_pk_bf16_f32 v120, v108, v109
	v_cvt_pk_bf16_f32 v121, v110, v111
	s_nop 1
	v_mov_b32_e32 v240, v120
	v_mov_b32_e32 v241, v121
	v_lshl_add_u64 v[244:245], v[118:119], 0, v[246:247]
	v_mul_f32_e32 v118, v108, v108
	v_fmac_f32_e32 v118, v109, v109
	v_pk_fma_f32 v[106:107], v[106:107], 0.5, v[138:139] op_sel_hi:[1,0,1]
	v_pk_fma_f32 v[104:105], v[104:105], 0.5, v[136:137] op_sel_hi:[1,0,1]
	v_fmac_f32_e32 v118, v110, v110
	global_store_dwordx4 v[114:115], v[104:107], off offset:64
	v_or_b32_e32 v108, 32, v112
	v_mov_b32_e32 v109, v113
	v_cvt_pk_bf16_f32 v110, v104, v105
	v_mul_f32_e32 v104, v104, v104
	v_lshl_add_u64 v[108:109], s[0:1], 0, v[108:109]
	v_fmac_f32_e32 v104, v105, v105
	v_pk_fma_f32 v[102:103], v[102:103], 0.5, v[134:135] op_sel_hi:[1,0,1]
	v_pk_fma_f32 v[100:101], v[100:101], 0.5, v[132:133] op_sel_hi:[1,0,1]
	v_fmac_f32_e32 v118, v111, v111
	v_cvt_pk_bf16_f32 v111, v106, v107
	v_mov_b32_e32 v242, v110
	v_mov_b32_e32 v243, v111
	s_nop 1
	v_permlane16_swap_b32 v240, v242
	v_permlane16_swap_b32 v241, v243
	global_store_dwordx4 v[244:245], v[240:243], off
	v_fmac_f32_e32 v104, v106, v106
	global_store_dwordx4 v[114:115], v[100:103], off offset:512
	v_cvt_pk_bf16_f32 v106, v100, v101
	v_fmac_f32_e32 v104, v107, v107
	v_add_f32_e32 v107, v118, v104
	v_mul_f32_e32 v100, v100, v100
	v_fmac_f32_e32 v100, v101, v101
	v_fmac_f32_e32 v100, v102, v102
	v_fmac_f32_e32 v100, v103, v103
	v_add_f32_e32 v107, v107, v100
	v_pk_fma_f32 v[100:101], v[98:99], 0.5, v[130:131] op_sel_hi:[1,0,1]
	v_pk_fma_f32 v[98:99], v[96:97], 0.5, v[128:129] op_sel_hi:[1,0,1]
	v_or_b32_e32 v104, 0x100, v112
	v_mul_f32_e32 v96, v98, v98
	v_fmac_f32_e32 v96, v99, v99
	v_fmac_f32_e32 v96, v100, v100
	v_fmac_f32_e32 v96, v101, v101
	v_add_f32_e32 v96, v107, v96
	ds_bpermute_b32 v97, v116, v96
	v_mov_b32_e32 v105, v113
	v_or_b32_e32 v112, 0x120, v112
	v_lshl_add_u64 v[104:105], s[0:1], 0, v[104:105]
	v_cvt_pk_bf16_f32 v107, v102, v103
	s_waitcnt lgkmcnt(0)
	v_add_f32_e32 v96, v96, v97
	ds_bpermute_b32 v97, v117, v96
	v_lshl_add_u64 v[102:103], s[0:1], 0, v[112:113]
	s_nop 1
	v_mov_b32_e32 v240, v106
	v_mov_b32_e32 v241, v107
	v_lshl_add_u64 v[244:245], v[104:105], 0, v[246:247]
	global_store_dwordx4 v[114:115], v[98:101], off offset:576
	s_nop 1
	v_cvt_pk_bf16_f32 v98, v98, v99
	v_cvt_pk_bf16_f32 v99, v100, v101
	v_mov_b32_e32 v242, v98
	v_mov_b32_e32 v243, v99
	s_nop 1
	v_permlane16_swap_b32 v240, v242
	v_permlane16_swap_b32 v241, v243
	global_store_dwordx4 v[244:245], v[240:243], off
	s_and_saveexec_b64 s[36:37], s[8:9]
	s_cbranch_execz .LBB0_402
	v_lshlrev_b64 v[98:99], 6, v[170:171]
	v_lshl_add_u64 v[98:99], s[2:3], 0, v[98:99]
	v_lshl_add_u64 v[98:99], s[16:17], 2, v[98:99]
	s_lshl_b32 s6, s83, 2
	v_lshl_add_u64 v[98:99], v[98:99], 0, s[6:7]
	s_waitcnt lgkmcnt(0)
	v_add_f32_e32 v96, v96, v97
	flat_store_dword v[98:99], v96
.LBB0_402:
	s_or_b64 exec, exec, s[36:37]
	v_or_b32_e32 v114, 32, v166
	v_mov_b32_e32 v115, v167
	s_waitcnt lgkmcnt(0)
	v_lshlrev_b64 v[96:97], 12, v[114:115]
	v_lshl_add_u64 v[96:97], v[168:169], 0, v[96:97]
	global_load_dwordx4 v[118:121], v[96:97], off
	global_load_dwordx4 v[122:125], v[96:97], off offset:64
	global_load_dwordx4 v[126:129], v[96:97], off offset:512
	global_load_dwordx4 v[130:133], v[96:97], off offset:576
	v_or_b32_e32 v112, 48, v166
	v_mov_b32_e32 v113, v167
	v_lshlrev_b64 v[96:97], 12, v[112:113]
	v_lshl_add_u64 v[96:97], v[168:169], 0, v[96:97]
	global_load_dwordx4 v[108:111], v[96:97], off
	global_load_dwordx4 v[104:107], v[96:97], off offset:64
	global_load_dwordx4 v[100:103], v[96:97], off offset:512
	s_nop 0
	global_load_dwordx4 v[96:99], v[96:97], off offset:576
	v_lshlrev_b64 v[134:135], 10, v[114:115]
	v_lshl_add_u64 v[134:135], v[134:135], 0, v[164:165]
	s_waitcnt vmcnt(0)
	s_waitcnt vmcnt(0)
	v_pk_fma_f32 v[94:95], v[94:95], 0.5, v[120:121] op_sel_hi:[1,0,1]
	v_lshlrev_b64 v[120:121], 1, v[134:135]
	v_pk_fma_f32 v[92:93], v[92:93], 0.5, v[118:119] op_sel_hi:[1,0,1]
	v_lshl_add_u64 v[118:119], v[134:135], 2, s[78:79]
	v_lshl_add_u64 v[134:135], s[0:1], 0, v[120:121]
	global_store_dwordx4 v[118:119], v[92:95], off
	v_cvt_pk_bf16_f32 v136, v92, v93
	v_cvt_pk_bf16_f32 v137, v94, v95
	s_nop 1
	v_mov_b32_e32 v240, v136
	v_mov_b32_e32 v241, v137
	v_lshl_add_u64 v[244:245], v[134:135], 0, v[246:247]
	v_mul_f32_e32 v134, v92, v92
	v_fmac_f32_e32 v134, v93, v93
	v_pk_fma_f32 v[90:91], v[90:91], 0.5, v[124:125] op_sel_hi:[1,0,1]
	v_pk_fma_f32 v[88:89], v[88:89], 0.5, v[122:123] op_sel_hi:[1,0,1]
	v_fmac_f32_e32 v134, v94, v94
	global_store_dwordx4 v[118:119], v[88:91], off offset:64
	v_cvt_pk_bf16_f32 v94, v88, v89
	v_or_b32_e32 v92, 32, v120
	v_mov_b32_e32 v93, v121
	v_mul_f32_e32 v88, v88, v88
	v_fmac_f32_e32 v88, v89, v89
	v_fmac_f32_e32 v88, v90, v90
	v_fmac_f32_e32 v134, v95, v95
	v_lshl_add_u64 v[92:93], s[0:1], 0, v[92:93]
	v_fmac_f32_e32 v88, v91, v91
	v_pk_fma_f32 v[86:87], v[86:87], 0.5, v[128:129] op_sel_hi:[1,0,1]
	v_pk_fma_f32 v[84:85], v[84:85], 0.5, v[126:127] op_sel_hi:[1,0,1]
	v_cvt_pk_bf16_f32 v95, v90, v91
	v_mov_b32_e32 v242, v94
	v_mov_b32_e32 v243, v95
	s_nop 1
	v_permlane16_swap_b32 v240, v242
	v_permlane16_swap_b32 v241, v243
	global_store_dwordx4 v[244:245], v[240:243], off
	v_add_f32_e32 v92, v134, v88
	global_store_dwordx4 v[118:119], v[84:87], off offset:512
	v_or_b32_e32 v88, 0x100, v120
	v_mov_b32_e32 v89, v121
	v_cvt_pk_bf16_f32 v90, v84, v85
	v_mul_f32_e32 v84, v84, v84
	v_lshl_add_u64 v[88:89], s[0:1], 0, v[88:89]
	v_fmac_f32_e32 v84, v85, v85
	v_pk_fma_f32 v[82:83], v[82:83], 0.5, v[132:133] op_sel_hi:[1,0,1]
	v_pk_fma_f32 v[80:81], v[80:81], 0.5, v[130:131] op_sel_hi:[1,0,1]
	v_cvt_pk_bf16_f32 v91, v86, v87
	s_nop 1
	v_mov_b32_e32 v240, v90
	v_mov_b32_e32 v241, v91
	v_lshl_add_u64 v[244:245], v[88:89], 0, v[246:247]
	v_fmac_f32_e32 v84, v86, v86
	global_store_dwordx4 v[118:119], v[80:83], off offset:576
	v_cvt_pk_bf16_f32 v86, v80, v81
	v_fmac_f32_e32 v84, v87, v87
	v_add_f32_e32 v88, v92, v84
	v_mul_f32_e32 v80, v80, v80
	v_fmac_f32_e32 v80, v81, v81
	v_fmac_f32_e32 v80, v82, v82
	v_fmac_f32_e32 v80, v83, v83
	v_add_f32_e32 v80, v88, v80
	ds_bpermute_b32 v81, v116, v80
	v_or_b32_e32 v120, 0x120, v120
	v_lshl_add_u64 v[84:85], s[0:1], 0, v[120:121]
	v_cvt_pk_bf16_f32 v87, v82, v83
	v_mov_b32_e32 v242, v86
	v_mov_b32_e32 v243, v87
	s_nop 1
	v_permlane16_swap_b32 v240, v242
	v_permlane16_swap_b32 v241, v243
	global_store_dwordx4 v[244:245], v[240:243], off
	s_waitcnt lgkmcnt(0)
	v_add_f32_e32 v80, v80, v81
	ds_bpermute_b32 v81, v117, v80
	s_and_saveexec_b64 s[36:37], s[8:9]
	s_cbranch_execz .LBB0_404
	v_lshlrev_b64 v[82:83], 6, v[114:115]
	v_lshl_add_u64 v[82:83], s[2:3], 0, v[82:83]
	v_lshl_add_u64 v[82:83], s[16:17], 2, v[82:83]
	s_lshl_b32 s6, s83, 2
	v_lshl_add_u64 v[82:83], v[82:83], 0, s[6:7]
	s_waitcnt lgkmcnt(0)
	v_add_f32_e32 v80, v80, v81
	flat_store_dword v[82:83], v80
.LBB0_404:
	s_or_b64 exec, exec, s[36:37]
	s_waitcnt lgkmcnt(0)
	v_lshlrev_b64 v[80:81], 10, v[112:113]
	v_lshl_add_u64 v[80:81], v[80:81], 0, v[164:165]
	v_lshl_add_u64 v[82:83], v[80:81], 2, s[78:79]
	v_lshlrev_b64 v[80:81], 1, v[80:81]
	v_pk_fma_f32 v[78:79], v[78:79], 0.5, v[110:111] op_sel_hi:[1,0,1]
	v_pk_fma_f32 v[76:77], v[76:77], 0.5, v[108:109] op_sel_hi:[1,0,1]
	v_lshl_add_u64 v[84:85], s[0:1], 0, v[80:81]
	global_store_dwordx4 v[82:83], v[76:79], off
	v_cvt_pk_bf16_f32 v86, v76, v77
	v_cvt_pk_bf16_f32 v87, v78, v79
	s_nop 1
	v_mov_b32_e32 v240, v86
	v_mov_b32_e32 v241, v87
	v_lshl_add_u64 v[244:245], v[84:85], 0, v[246:247]
	v_mul_f32_e32 v84, v76, v76
	v_fmac_f32_e32 v84, v77, v77
	v_pk_fma_f32 v[74:75], v[74:75], 0.5, v[106:107] op_sel_hi:[1,0,1]
	v_pk_fma_f32 v[72:73], v[72:73], 0.5, v[104:105] op_sel_hi:[1,0,1]
	v_fmac_f32_e32 v84, v78, v78
	global_store_dwordx4 v[82:83], v[72:75], off offset:64
	v_or_b32_e32 v76, 32, v80
	v_mov_b32_e32 v77, v81
	v_cvt_pk_bf16_f32 v78, v72, v73
	v_mul_f32_e32 v72, v72, v72
	v_lshl_add_u64 v[76:77], s[0:1], 0, v[76:77]
	v_fmac_f32_e32 v72, v73, v73
	v_pk_fma_f32 v[70:71], v[70:71], 0.5, v[102:103] op_sel_hi:[1,0,1]
	v_pk_fma_f32 v[68:69], v[68:69], 0.5, v[100:101] op_sel_hi:[1,0,1]
	v_fmac_f32_e32 v84, v79, v79
	v_cvt_pk_bf16_f32 v79, v74, v75
	v_mov_b32_e32 v242, v78
	v_mov_b32_e32 v243, v79
	s_nop 1
	v_permlane16_swap_b32 v240, v242
	v_permlane16_swap_b32 v241, v243
	global_store_dwordx4 v[244:245], v[240:243], off
	v_fmac_f32_e32 v72, v74, v74
	global_store_dwordx4 v[82:83], v[68:71], off offset:512
	v_cvt_pk_bf16_f32 v74, v68, v69
	v_fmac_f32_e32 v72, v75, v75
	v_add_f32_e32 v75, v84, v72
	v_mul_f32_e32 v68, v68, v68
	v_fmac_f32_e32 v68, v69, v69
	v_fmac_f32_e32 v68, v70, v70
	v_fmac_f32_e32 v68, v71, v71
	v_add_f32_e32 v75, v75, v68
	v_pk_fma_f32 v[68:69], v[66:67], 0.5, v[98:99] op_sel_hi:[1,0,1]
	v_pk_fma_f32 v[66:67], v[64:65], 0.5, v[96:97] op_sel_hi:[1,0,1]
	v_or_b32_e32 v72, 0x100, v80
	v_mul_f32_e32 v64, v66, v66
	v_fmac_f32_e32 v64, v67, v67
	v_fmac_f32_e32 v64, v68, v68
	v_fmac_f32_e32 v64, v69, v69
	v_add_f32_e32 v64, v75, v64
	ds_bpermute_b32 v65, v116, v64
	v_mov_b32_e32 v73, v81
	v_or_b32_e32 v80, 0x120, v80
	v_lshl_add_u64 v[72:73], s[0:1], 0, v[72:73]
	v_cvt_pk_bf16_f32 v75, v70, v71
	s_waitcnt lgkmcnt(0)
	v_add_f32_e32 v64, v64, v65
	ds_bpermute_b32 v65, v117, v64
	v_lshl_add_u64 v[70:71], s[0:1], 0, v[80:81]
	s_nop 1
	v_mov_b32_e32 v240, v74
	v_mov_b32_e32 v241, v75
	v_lshl_add_u64 v[244:245], v[72:73], 0, v[246:247]
	global_store_dwordx4 v[82:83], v[66:69], off offset:576
	s_nop 1
	v_cvt_pk_bf16_f32 v66, v66, v67
	v_cvt_pk_bf16_f32 v67, v68, v69
	v_mov_b32_e32 v242, v66
	v_mov_b32_e32 v243, v67
	s_nop 1
	v_permlane16_swap_b32 v240, v242
	v_permlane16_swap_b32 v241, v243
	global_store_dwordx4 v[244:245], v[240:243], off
	s_and_saveexec_b64 s[36:37], s[8:9]
	s_cbranch_execz .LBB0_406
	v_lshlrev_b64 v[66:67], 6, v[112:113]
	v_lshl_add_u64 v[66:67], s[2:3], 0, v[66:67]
	v_lshl_add_u64 v[66:67], s[16:17], 2, v[66:67]
	s_lshl_b32 s6, s83, 2
	v_lshl_add_u64 v[66:67], v[66:67], 0, s[6:7]
	s_waitcnt lgkmcnt(0)
	v_add_f32_e32 v64, v64, v65
	flat_store_dword v[66:67], v64
.LBB0_406:
	s_or_b64 exec, exec, s[36:37]
	v_lshl_add_u64 v[82:83], v[166:167], 0, s[4:5]
	s_waitcnt lgkmcnt(0)
	v_lshlrev_b64 v[64:65], 12, v[82:83]
	v_lshl_add_u64 v[64:65], v[168:169], 0, v[64:65]
	global_load_dwordx4 v[84:87], v[64:65], off
	global_load_dwordx4 v[88:91], v[64:65], off offset:64
	global_load_dwordx4 v[92:95], v[64:65], off offset:512
	global_load_dwordx4 v[96:99], v[64:65], off offset:576
	s_mov_b64 s[18:19], 0x90
	v_lshl_add_u64 v[80:81], v[166:167], 0, s[18:19]
	v_lshlrev_b64 v[64:65], 12, v[80:81]
	v_lshl_add_u64 v[64:65], v[168:169], 0, v[64:65]
	global_load_dwordx4 v[76:79], v[64:65], off
	global_load_dwordx4 v[72:75], v[64:65], off offset:64
	global_load_dwordx4 v[68:71], v[64:65], off offset:512
	s_nop 0
	global_load_dwordx4 v[64:67], v[64:65], off offset:576
	v_lshlrev_b64 v[100:101], 10, v[82:83]
	v_lshl_add_u64 v[100:101], v[100:101], 0, v[164:165]
	s_waitcnt vmcnt(0)
	s_waitcnt vmcnt(0)
	v_pk_fma_f32 v[62:63], v[62:63], 0.5, v[86:87] op_sel_hi:[1,0,1]
	v_lshlrev_b64 v[86:87], 1, v[100:101]
	v_pk_fma_f32 v[60:61], v[60:61], 0.5, v[84:85] op_sel_hi:[1,0,1]
	v_lshl_add_u64 v[84:85], v[100:101], 2, s[78:79]
	v_lshl_add_u64 v[100:101], s[0:1], 0, v[86:87]
	global_store_dwordx4 v[84:85], v[60:63], off
	v_cvt_pk_bf16_f32 v102, v60, v61
	v_cvt_pk_bf16_f32 v103, v62, v63
	s_nop 1
	v_mov_b32_e32 v240, v102
	v_mov_b32_e32 v241, v103
	v_lshl_add_u64 v[244:245], v[100:101], 0, v[246:247]
	v_mul_f32_e32 v100, v60, v60
	v_fmac_f32_e32 v100, v61, v61
	v_pk_fma_f32 v[58:59], v[58:59], 0.5, v[90:91] op_sel_hi:[1,0,1]
	v_pk_fma_f32 v[56:57], v[56:57], 0.5, v[88:89] op_sel_hi:[1,0,1]
	v_fmac_f32_e32 v100, v62, v62
	global_store_dwordx4 v[84:85], v[56:59], off offset:64
	v_cvt_pk_bf16_f32 v62, v56, v57
	v_or_b32_e32 v60, 32, v86
	v_mov_b32_e32 v61, v87
	v_mul_f32_e32 v56, v56, v56
	v_fmac_f32_e32 v56, v57, v57
	v_fmac_f32_e32 v56, v58, v58
	v_fmac_f32_e32 v100, v63, v63
	v_lshl_add_u64 v[60:61], s[0:1], 0, v[60:61]
	v_fmac_f32_e32 v56, v59, v59
	v_pk_fma_f32 v[54:55], v[54:55], 0.5, v[94:95] op_sel_hi:[1,0,1]
	v_pk_fma_f32 v[52:53], v[52:53], 0.5, v[92:93] op_sel_hi:[1,0,1]
	v_cvt_pk_bf16_f32 v63, v58, v59
	v_mov_b32_e32 v242, v62
	v_mov_b32_e32 v243, v63
	s_nop 1
	v_permlane16_swap_b32 v240, v242
	v_permlane16_swap_b32 v241, v243
	global_store_dwordx4 v[244:245], v[240:243], off
	v_add_f32_e32 v60, v100, v56
	global_store_dwordx4 v[84:85], v[52:55], off offset:512
	v_or_b32_e32 v56, 0x100, v86
	v_mov_b32_e32 v57, v87
	v_cvt_pk_bf16_f32 v58, v52, v53
	v_mul_f32_e32 v52, v52, v52
	v_lshl_add_u64 v[56:57], s[0:1], 0, v[56:57]
	v_fmac_f32_e32 v52, v53, v53
	v_pk_fma_f32 v[50:51], v[50:51], 0.5, v[98:99] op_sel_hi:[1,0,1]
	v_pk_fma_f32 v[48:49], v[48:49], 0.5, v[96:97] op_sel_hi:[1,0,1]
	v_cvt_pk_bf16_f32 v59, v54, v55
	s_nop 1
	v_mov_b32_e32 v240, v58
	v_mov_b32_e32 v241, v59
	v_lshl_add_u64 v[244:245], v[56:57], 0, v[246:247]
	v_fmac_f32_e32 v52, v54, v54
	global_store_dwordx4 v[84:85], v[48:51], off offset:576
	v_cvt_pk_bf16_f32 v54, v48, v49
	v_fmac_f32_e32 v52, v55, v55
	v_add_f32_e32 v56, v60, v52
	v_mul_f32_e32 v48, v48, v48
	v_fmac_f32_e32 v48, v49, v49
	v_fmac_f32_e32 v48, v50, v50
	v_fmac_f32_e32 v48, v51, v51
	v_add_f32_e32 v48, v56, v48
	ds_bpermute_b32 v49, v116, v48
	v_or_b32_e32 v86, 0x120, v86
	v_lshl_add_u64 v[52:53], s[0:1], 0, v[86:87]
	v_cvt_pk_bf16_f32 v55, v50, v51
	v_mov_b32_e32 v242, v54
	v_mov_b32_e32 v243, v55
	s_nop 1
	v_permlane16_swap_b32 v240, v242
	v_permlane16_swap_b32 v241, v243
	global_store_dwordx4 v[244:245], v[240:243], off
	s_waitcnt lgkmcnt(0)
	v_add_f32_e32 v48, v48, v49
	ds_bpermute_b32 v49, v117, v48
	s_and_saveexec_b64 s[36:37], s[8:9]
	s_cbranch_execz .LBB0_408
	v_lshlrev_b64 v[50:51], 6, v[82:83]
	v_lshl_add_u64 v[50:51], s[2:3], 0, v[50:51]
	v_lshl_add_u64 v[50:51], s[16:17], 2, v[50:51]
	s_lshl_b32 s6, s83, 2
	v_lshl_add_u64 v[50:51], v[50:51], 0, s[6:7]
	s_waitcnt lgkmcnt(0)
	v_add_f32_e32 v48, v48, v49
	flat_store_dword v[50:51], v48
.LBB0_408:
	s_or_b64 exec, exec, s[36:37]
	s_waitcnt lgkmcnt(0)
	v_lshlrev_b64 v[48:49], 10, v[80:81]
	v_lshl_add_u64 v[48:49], v[48:49], 0, v[164:165]
	v_lshl_add_u64 v[50:51], v[48:49], 2, s[78:79]
	v_lshlrev_b64 v[48:49], 1, v[48:49]
	v_pk_fma_f32 v[46:47], v[46:47], 0.5, v[78:79] op_sel_hi:[1,0,1]
	v_pk_fma_f32 v[44:45], v[44:45], 0.5, v[76:77] op_sel_hi:[1,0,1]
	v_lshl_add_u64 v[52:53], s[0:1], 0, v[48:49]
	global_store_dwordx4 v[50:51], v[44:47], off
	v_cvt_pk_bf16_f32 v54, v44, v45
	v_cvt_pk_bf16_f32 v55, v46, v47
	s_nop 1
	v_mov_b32_e32 v240, v54
	v_mov_b32_e32 v241, v55
	v_lshl_add_u64 v[244:245], v[52:53], 0, v[246:247]
	v_mul_f32_e32 v52, v44, v44
	v_fmac_f32_e32 v52, v45, v45
	v_pk_fma_f32 v[42:43], v[42:43], 0.5, v[74:75] op_sel_hi:[1,0,1]
	v_pk_fma_f32 v[40:41], v[40:41], 0.5, v[72:73] op_sel_hi:[1,0,1]
	v_fmac_f32_e32 v52, v46, v46
	global_store_dwordx4 v[50:51], v[40:43], off offset:64
	v_or_b32_e32 v44, 32, v48
	v_mov_b32_e32 v45, v49
	v_cvt_pk_bf16_f32 v46, v40, v41
	v_mul_f32_e32 v40, v40, v40
	v_lshl_add_u64 v[44:45], s[0:1], 0, v[44:45]
	v_fmac_f32_e32 v40, v41, v41
	v_pk_fma_f32 v[38:39], v[38:39], 0.5, v[70:71] op_sel_hi:[1,0,1]
	v_pk_fma_f32 v[36:37], v[36:37], 0.5, v[68:69] op_sel_hi:[1,0,1]
	v_fmac_f32_e32 v52, v47, v47
	v_cvt_pk_bf16_f32 v47, v42, v43
	v_mov_b32_e32 v242, v46
	v_mov_b32_e32 v243, v47
	s_nop 1
	v_permlane16_swap_b32 v240, v242
	v_permlane16_swap_b32 v241, v243
	global_store_dwordx4 v[244:245], v[240:243], off
	v_fmac_f32_e32 v40, v42, v42
	global_store_dwordx4 v[50:51], v[36:39], off offset:512
	v_cvt_pk_bf16_f32 v42, v36, v37
	v_fmac_f32_e32 v40, v43, v43
	v_add_f32_e32 v43, v52, v40
	v_mul_f32_e32 v36, v36, v36
	v_fmac_f32_e32 v36, v37, v37
	v_fmac_f32_e32 v36, v38, v38
	v_fmac_f32_e32 v36, v39, v39
	v_add_f32_e32 v43, v43, v36
	v_pk_fma_f32 v[36:37], v[34:35], 0.5, v[66:67] op_sel_hi:[1,0,1]
	v_pk_fma_f32 v[34:35], v[32:33], 0.5, v[64:65] op_sel_hi:[1,0,1]
	v_or_b32_e32 v40, 0x100, v48
	v_mul_f32_e32 v32, v34, v34
	v_fmac_f32_e32 v32, v35, v35
	v_fmac_f32_e32 v32, v36, v36
	v_fmac_f32_e32 v32, v37, v37
	v_add_f32_e32 v32, v43, v32
	ds_bpermute_b32 v33, v116, v32
	v_mov_b32_e32 v41, v49
	v_or_b32_e32 v48, 0x120, v48
	v_lshl_add_u64 v[40:41], s[0:1], 0, v[40:41]
	v_cvt_pk_bf16_f32 v43, v38, v39
	s_waitcnt lgkmcnt(0)
	v_add_f32_e32 v32, v32, v33
	ds_bpermute_b32 v33, v117, v32
	v_lshl_add_u64 v[38:39], s[0:1], 0, v[48:49]
	s_nop 1
	v_mov_b32_e32 v240, v42
	v_mov_b32_e32 v241, v43
	v_lshl_add_u64 v[244:245], v[40:41], 0, v[246:247]
	global_store_dwordx4 v[50:51], v[34:37], off offset:576
	s_nop 1
	v_cvt_pk_bf16_f32 v34, v34, v35
	v_cvt_pk_bf16_f32 v35, v36, v37
	v_mov_b32_e32 v242, v34
	v_mov_b32_e32 v243, v35
	s_nop 1
	v_permlane16_swap_b32 v240, v242
	v_permlane16_swap_b32 v241, v243
	global_store_dwordx4 v[244:245], v[240:243], off
	s_and_saveexec_b64 s[36:37], s[8:9]
	s_cbranch_execz .LBB0_410
	v_lshlrev_b64 v[34:35], 6, v[80:81]
	v_lshl_add_u64 v[34:35], s[2:3], 0, v[34:35]
	v_lshl_add_u64 v[34:35], s[16:17], 2, v[34:35]
	s_lshl_b32 s6, s83, 2
	v_lshl_add_u64 v[34:35], v[34:35], 0, s[6:7]
	s_waitcnt lgkmcnt(0)
	v_add_f32_e32 v32, v32, v33
	flat_store_dword v[34:35], v32
.LBB0_410:
	s_or_b64 exec, exec, s[36:37]
	s_mov_b64 s[18:19], 0xa0
	v_lshl_add_u64 v[50:51], v[166:167], 0, s[18:19]
	s_waitcnt lgkmcnt(0)
	v_lshlrev_b64 v[32:33], 12, v[50:51]
	v_lshl_add_u64 v[32:33], v[168:169], 0, v[32:33]
	global_load_dwordx4 v[52:55], v[32:33], off
	global_load_dwordx4 v[56:59], v[32:33], off offset:64
	global_load_dwordx4 v[60:63], v[32:33], off offset:512
	global_load_dwordx4 v[64:67], v[32:33], off offset:576
	s_mov_b64 s[18:19], 0xb0
	v_lshl_add_u64 v[48:49], v[166:167], 0, s[18:19]
	v_lshlrev_b64 v[32:33], 12, v[48:49]
	v_lshl_add_u64 v[32:33], v[168:169], 0, v[32:33]
	global_load_dwordx4 v[44:47], v[32:33], off
	global_load_dwordx4 v[40:43], v[32:33], off offset:64
	global_load_dwordx4 v[36:39], v[32:33], off offset:512
	s_nop 0
	global_load_dwordx4 v[32:35], v[32:33], off offset:576
	v_lshlrev_b64 v[68:69], 10, v[50:51]
	v_lshl_add_u64 v[68:69], v[68:69], 0, v[164:165]
	s_waitcnt vmcnt(0)
	s_waitcnt vmcnt(0)
	v_pk_fma_f32 v[30:31], v[30:31], 0.5, v[54:55] op_sel_hi:[1,0,1]
	v_lshlrev_b64 v[54:55], 1, v[68:69]
	v_pk_fma_f32 v[28:29], v[28:29], 0.5, v[52:53] op_sel_hi:[1,0,1]
	v_lshl_add_u64 v[52:53], v[68:69], 2, s[78:79]
	v_lshl_add_u64 v[68:69], s[0:1], 0, v[54:55]
	global_store_dwordx4 v[52:53], v[28:31], off
	v_cvt_pk_bf16_f32 v70, v28, v29
	v_cvt_pk_bf16_f32 v71, v30, v31
	s_nop 1
	v_mov_b32_e32 v240, v70
	v_mov_b32_e32 v241, v71
	v_lshl_add_u64 v[244:245], v[68:69], 0, v[246:247]
	v_mul_f32_e32 v68, v28, v28
	v_fmac_f32_e32 v68, v29, v29
	v_pk_fma_f32 v[26:27], v[26:27], 0.5, v[58:59] op_sel_hi:[1,0,1]
	v_pk_fma_f32 v[24:25], v[24:25], 0.5, v[56:57] op_sel_hi:[1,0,1]
	v_fmac_f32_e32 v68, v30, v30
	global_store_dwordx4 v[52:53], v[24:27], off offset:64
	v_cvt_pk_bf16_f32 v30, v24, v25
	v_or_b32_e32 v28, 32, v54
	v_mov_b32_e32 v29, v55
	v_mul_f32_e32 v24, v24, v24
	v_fmac_f32_e32 v24, v25, v25
	v_fmac_f32_e32 v24, v26, v26
	v_fmac_f32_e32 v68, v31, v31
	v_lshl_add_u64 v[28:29], s[0:1], 0, v[28:29]
	v_fmac_f32_e32 v24, v27, v27
	v_pk_fma_f32 v[22:23], v[22:23], 0.5, v[62:63] op_sel_hi:[1,0,1]
	v_pk_fma_f32 v[20:21], v[20:21], 0.5, v[60:61] op_sel_hi:[1,0,1]
	v_cvt_pk_bf16_f32 v31, v26, v27
	v_mov_b32_e32 v242, v30
	v_mov_b32_e32 v243, v31
	s_nop 1
	v_permlane16_swap_b32 v240, v242
	v_permlane16_swap_b32 v241, v243
	global_store_dwordx4 v[244:245], v[240:243], off
	v_add_f32_e32 v28, v68, v24
	global_store_dwordx4 v[52:53], v[20:23], off offset:512
	v_or_b32_e32 v24, 0x100, v54
	v_mov_b32_e32 v25, v55
	v_cvt_pk_bf16_f32 v26, v20, v21
	v_mul_f32_e32 v20, v20, v20
	v_lshl_add_u64 v[24:25], s[0:1], 0, v[24:25]
	v_fmac_f32_e32 v20, v21, v21
	v_pk_fma_f32 v[18:19], v[18:19], 0.5, v[66:67] op_sel_hi:[1,0,1]
	v_pk_fma_f32 v[16:17], v[16:17], 0.5, v[64:65] op_sel_hi:[1,0,1]
	v_cvt_pk_bf16_f32 v27, v22, v23
	s_nop 1
	v_mov_b32_e32 v240, v26
	v_mov_b32_e32 v241, v27
	v_lshl_add_u64 v[244:245], v[24:25], 0, v[246:247]
	v_fmac_f32_e32 v20, v22, v22
	global_store_dwordx4 v[52:53], v[16:19], off offset:576
	v_cvt_pk_bf16_f32 v22, v16, v17
	v_fmac_f32_e32 v20, v23, v23
	v_add_f32_e32 v24, v28, v20
	v_mul_f32_e32 v16, v16, v16
	v_fmac_f32_e32 v16, v17, v17
	v_fmac_f32_e32 v16, v18, v18
	v_fmac_f32_e32 v16, v19, v19
	v_add_f32_e32 v16, v24, v16
	ds_bpermute_b32 v17, v116, v16
	v_or_b32_e32 v54, 0x120, v54
	v_lshl_add_u64 v[20:21], s[0:1], 0, v[54:55]
	v_cvt_pk_bf16_f32 v23, v18, v19
	v_mov_b32_e32 v242, v22
	v_mov_b32_e32 v243, v23
	s_nop 1
	v_permlane16_swap_b32 v240, v242
	v_permlane16_swap_b32 v241, v243
	global_store_dwordx4 v[244:245], v[240:243], off
	s_waitcnt lgkmcnt(0)
	v_add_f32_e32 v16, v16, v17
	ds_bpermute_b32 v17, v117, v16
	s_and_saveexec_b64 s[36:37], s[8:9]
	s_cbranch_execz .LBB0_412
	v_lshlrev_b64 v[18:19], 6, v[50:51]
	v_lshl_add_u64 v[18:19], s[2:3], 0, v[18:19]
	v_lshl_add_u64 v[18:19], s[16:17], 2, v[18:19]
	s_lshl_b32 s6, s83, 2
	v_lshl_add_u64 v[18:19], v[18:19], 0, s[6:7]
	s_waitcnt lgkmcnt(0)
	v_add_f32_e32 v16, v16, v17
	flat_store_dword v[18:19], v16
.LBB0_412:
	s_or_b64 exec, exec, s[36:37]
	s_waitcnt lgkmcnt(0)
	v_lshlrev_b64 v[16:17], 10, v[48:49]
	v_lshl_add_u64 v[16:17], v[16:17], 0, v[164:165]
	v_lshl_add_u64 v[18:19], v[16:17], 2, s[78:79]
	v_lshlrev_b64 v[16:17], 1, v[16:17]
	v_pk_fma_f32 v[14:15], v[14:15], 0.5, v[46:47] op_sel_hi:[1,0,1]
	v_pk_fma_f32 v[12:13], v[12:13], 0.5, v[44:45] op_sel_hi:[1,0,1]
	v_lshl_add_u64 v[20:21], s[0:1], 0, v[16:17]
	global_store_dwordx4 v[18:19], v[12:15], off
	v_cvt_pk_bf16_f32 v22, v12, v13
	v_cvt_pk_bf16_f32 v23, v14, v15
	s_nop 1
	v_mov_b32_e32 v240, v22
	v_mov_b32_e32 v241, v23
	v_lshl_add_u64 v[244:245], v[20:21], 0, v[246:247]
	v_mul_f32_e32 v20, v12, v12
	v_fmac_f32_e32 v20, v13, v13
	v_pk_fma_f32 v[10:11], v[10:11], 0.5, v[42:43] op_sel_hi:[1,0,1]
	v_pk_fma_f32 v[8:9], v[8:9], 0.5, v[40:41] op_sel_hi:[1,0,1]
	v_fmac_f32_e32 v20, v14, v14
	global_store_dwordx4 v[18:19], v[8:11], off offset:64
	v_or_b32_e32 v12, 32, v16
	v_mov_b32_e32 v13, v17
	v_cvt_pk_bf16_f32 v14, v8, v9
	v_mul_f32_e32 v8, v8, v8
	v_lshl_add_u64 v[12:13], s[0:1], 0, v[12:13]
	v_fmac_f32_e32 v8, v9, v9
	v_pk_fma_f32 v[6:7], v[6:7], 0.5, v[38:39] op_sel_hi:[1,0,1]
	v_pk_fma_f32 v[4:5], v[4:5], 0.5, v[36:37] op_sel_hi:[1,0,1]
	v_fmac_f32_e32 v20, v15, v15
	v_cvt_pk_bf16_f32 v15, v10, v11
	v_mov_b32_e32 v242, v14
	v_mov_b32_e32 v243, v15
	s_nop 1
	v_permlane16_swap_b32 v240, v242
	v_permlane16_swap_b32 v241, v243
	global_store_dwordx4 v[244:245], v[240:243], off
	v_fmac_f32_e32 v8, v10, v10
	global_store_dwordx4 v[18:19], v[4:7], off offset:512
	v_cvt_pk_bf16_f32 v10, v4, v5
	v_fmac_f32_e32 v8, v11, v11
	v_add_f32_e32 v11, v20, v8
	v_mul_f32_e32 v4, v4, v4
	v_fmac_f32_e32 v4, v5, v5
	v_fmac_f32_e32 v4, v6, v6
	v_fmac_f32_e32 v4, v7, v7
	v_add_f32_e32 v11, v11, v4
	v_pk_fma_f32 v[4:5], v[2:3], 0.5, v[34:35] op_sel_hi:[1,0,1]
	v_pk_fma_f32 v[2:3], v[0:1], 0.5, v[32:33] op_sel_hi:[1,0,1]
	v_or_b32_e32 v8, 0x100, v16
	v_mul_f32_e32 v0, v2, v2
	v_fmac_f32_e32 v0, v3, v3
	v_fmac_f32_e32 v0, v4, v4
	v_fmac_f32_e32 v0, v5, v5
	v_add_f32_e32 v0, v11, v0
	ds_bpermute_b32 v1, v116, v0
	v_mov_b32_e32 v9, v17
	v_or_b32_e32 v16, 0x120, v16
	v_lshl_add_u64 v[8:9], s[0:1], 0, v[8:9]
	v_cvt_pk_bf16_f32 v11, v6, v7
	s_waitcnt lgkmcnt(0)
	v_add_f32_e32 v0, v0, v1
	ds_bpermute_b32 v1, v117, v0
	v_lshl_add_u64 v[6:7], s[0:1], 0, v[16:17]
	s_nop 1
	v_mov_b32_e32 v240, v10
	v_mov_b32_e32 v241, v11
	v_lshl_add_u64 v[244:245], v[8:9], 0, v[246:247]
	global_store_dwordx4 v[18:19], v[2:5], off offset:576
	s_nop 1
	v_cvt_pk_bf16_f32 v2, v2, v3
	v_cvt_pk_bf16_f32 v3, v4, v5
	v_mov_b32_e32 v242, v2
	v_mov_b32_e32 v243, v3
	s_nop 1
	v_permlane16_swap_b32 v240, v242
	v_permlane16_swap_b32 v241, v243
	global_store_dwordx4 v[244:245], v[240:243], off
	s_and_saveexec_b64 s[36:37], s[8:9]
	s_cbranch_execz .LBB0_385
	v_lshlrev_b64 v[2:3], 6, v[48:49]
	v_lshl_add_u64 v[2:3], s[2:3], 0, v[2:3]
	v_lshl_add_u64 v[2:3], s[16:17], 2, v[2:3]
	s_lshl_b32 s6, s83, 2
	v_lshl_add_u64 v[2:3], v[2:3], 0, s[6:7]
	s_waitcnt lgkmcnt(0)
	v_add_f32_e32 v0, v0, v1
	flat_store_dword v[2:3], v0
	s_branch .LBB0_385

.LBB0_1480:
	ds_read_b128 v[128:131], v170
	ds_read_b128 v[132:135], v171
	ds_read_b128 v[136:139], v172
	ds_read_b128 v[140:143], v173
	s_add_u32 s34, s30, 0xfffc0080
	s_addc_u32 s35, s31, -1
	s_cmp_eq_u32 s69, 12
	s_cselect_b32 s37, s23, s35
	s_cselect_b32 s36, s29, s34
	s_cselect_b32 s35, s21, s68
	s_cselect_b32 s34, s66, s67
	s_mov_b32 m0, s63
	v_lshl_add_u64 v[214:215], s[30:31], 0, v[156:157]
	ds_read_b128 v[162:165], v151
	ds_read_b128 v[166:169], v151 offset:1024
	ds_read_b128 v[190:193], v151 offset:2048
	ds_read_b128 v[194:197], v151 offset:3072
	ds_read_b128 v[198:201], v151 offset:4096
	ds_read_b128 v[202:205], v151 offset:5120
	ds_read_b128 v[206:209], v151 offset:6144
	ds_read_b128 v[210:213], v151 offset:7168
	global_load_lds_dwordx4 v[214:215], off
	v_lshl_add_u64 v[214:215], s[30:31], 0, v[154:155]
	s_mov_b32 m0, s64
	s_nop 0
	global_load_lds_dwordx4 v[214:215], off
	s_waitcnt lgkmcnt(8)
	s_barrier
	s_waitcnt lgkmcnt(0)
	s_setprio 1
	s_waitcnt lgkmcnt(0)
	v_mfma_f32_16x16x32_bf16 v[124:127], v[128:131], v[162:165], v[124:127]
	v_mfma_f32_16x16x32_bf16 v[120:123], v[136:139], v[162:165], v[120:123]
	v_mfma_f32_16x16x32_bf16 v[108:111], v[128:131], v[190:193], v[108:111]
	v_mfma_f32_16x16x32_bf16 v[104:107], v[136:139], v[190:193], v[104:107]
	v_mfma_f32_16x16x32_bf16 v[92:95], v[128:131], v[198:201], v[92:95]
	v_mfma_f32_16x16x32_bf16 v[88:91], v[136:139], v[198:201], v[88:91]
	v_mfma_f32_16x16x32_bf16 v[76:79], v[128:131], v[206:209], v[76:79]
	v_mfma_f32_16x16x32_bf16 v[72:75], v[136:139], v[206:209], v[72:75]
	v_mfma_f32_16x16x32_bf16 v[124:127], v[132:135], v[166:169], v[124:127]
	v_mfma_f32_16x16x32_bf16 v[120:123], v[140:143], v[166:169], v[120:123]
	v_mfma_f32_16x16x32_bf16 v[108:111], v[132:135], v[194:197], v[108:111]
	v_mfma_f32_16x16x32_bf16 v[104:107], v[140:143], v[194:197], v[104:107]
	v_mfma_f32_16x16x32_bf16 v[92:95], v[132:135], v[202:205], v[92:95]
	v_mfma_f32_16x16x32_bf16 v[88:91], v[140:143], v[202:205], v[88:91]
	v_mfma_f32_16x16x32_bf16 v[76:79], v[132:135], v[210:213], v[76:79]
	v_mfma_f32_16x16x32_bf16 v[72:75], v[140:143], v[210:213], v[72:75]
	s_setprio 0
	s_barrier
	s_mov_b32 m0, s46
	v_lshl_add_u64 v[230:231], s[34:35], 0, v[144:145]
	ds_read_b128 v[214:217], v174
	ds_read_b128 v[218:221], v175
	ds_read_b128 v[222:225], v177
	ds_read_b128 v[226:229], v178
	global_load_lds_dwordx4 v[230:231], off
	v_lshl_add_u64 v[232:233], s[34:35], 0, v[146:147]
	s_mov_b32 m0, s47
	s_nop 0
	global_load_lds_dwordx4 v[232:233], off
	s_barrier
	s_waitcnt lgkmcnt(0)
	s_setprio 1
	s_waitcnt lgkmcnt(0)
	v_mfma_f32_16x16x32_bf16 v[116:119], v[214:217], v[162:165], v[116:119]
	v_mfma_f32_16x16x32_bf16 v[112:115], v[222:225], v[162:165], v[112:115]
	v_mfma_f32_16x16x32_bf16 v[100:103], v[214:217], v[190:193], v[100:103]
	v_mfma_f32_16x16x32_bf16 v[96:99], v[222:225], v[190:193], v[96:99]
	v_mfma_f32_16x16x32_bf16 v[84:87], v[214:217], v[198:201], v[84:87]
	v_mfma_f32_16x16x32_bf16 v[80:83], v[222:225], v[198:201], v[80:83]
	v_mfma_f32_16x16x32_bf16 v[68:71], v[214:217], v[206:209], v[68:71]
	v_mfma_f32_16x16x32_bf16 v[64:67], v[222:225], v[206:209], v[64:67]
	v_mfma_f32_16x16x32_bf16 v[116:119], v[218:221], v[166:169], v[116:119]
	v_mfma_f32_16x16x32_bf16 v[112:115], v[226:229], v[166:169], v[112:115]
	v_mfma_f32_16x16x32_bf16 v[100:103], v[218:221], v[194:197], v[100:103]
	v_mfma_f32_16x16x32_bf16 v[96:99], v[226:229], v[194:197], v[96:99]
	v_mfma_f32_16x16x32_bf16 v[84:87], v[218:221], v[202:205], v[84:87]
	v_mfma_f32_16x16x32_bf16 v[80:83], v[226:229], v[202:205], v[80:83]
	v_mfma_f32_16x16x32_bf16 v[68:71], v[218:221], v[210:213], v[68:71]
	v_mfma_f32_16x16x32_bf16 v[64:67], v[226:229], v[210:213], v[64:67]
	s_setprio 0
	s_mov_b32 m0, s45
	v_lshl_add_u64 v[234:235], s[36:37], 0, v[144:145]
	s_barrier
	ds_read_b128 v[162:165], v151 offset:16384
	ds_read_b128 v[166:169], v151 offset:17408
	ds_read_b128 v[190:193], v151 offset:18432
	ds_read_b128 v[194:197], v151 offset:19456
	ds_read_b128 v[198:201], v151 offset:20480
	ds_read_b128 v[202:205], v151 offset:21504
	ds_read_b128 v[206:209], v151 offset:22528
	ds_read_b128 v[210:213], v151 offset:23552
	global_load_lds_dwordx4 v[234:235], off
	v_lshl_add_u64 v[236:237], s[36:37], 0, v[146:147]
	s_mov_b32 m0, s48
	s_nop 0
	global_load_lds_dwordx4 v[236:237], off
	s_barrier
	s_waitcnt lgkmcnt(0)
	s_setprio 1
	s_waitcnt lgkmcnt(0)
	v_mfma_f32_16x16x32_bf16 v[60:63], v[128:131], v[162:165], v[60:63]
	v_mfma_f32_16x16x32_bf16 v[56:59], v[136:139], v[162:165], v[56:59]
	v_mfma_f32_16x16x32_bf16 v[44:47], v[128:131], v[190:193], v[44:47]
	v_mfma_f32_16x16x32_bf16 v[40:43], v[136:139], v[190:193], v[40:43]
	v_mfma_f32_16x16x32_bf16 v[28:31], v[128:131], v[198:201], v[28:31]
	v_mfma_f32_16x16x32_bf16 v[24:27], v[136:139], v[198:201], v[24:27]
	v_mfma_f32_16x16x32_bf16 v[12:15], v[128:131], v[206:209], v[12:15]
	v_mfma_f32_16x16x32_bf16 v[8:11], v[136:139], v[206:209], v[8:11]
	v_mfma_f32_16x16x32_bf16 v[60:63], v[132:135], v[166:169], v[60:63]
	v_mfma_f32_16x16x32_bf16 v[56:59], v[140:143], v[166:169], v[56:59]
	v_mfma_f32_16x16x32_bf16 v[44:47], v[132:135], v[194:197], v[44:47]
	v_mfma_f32_16x16x32_bf16 v[40:43], v[140:143], v[194:197], v[40:43]
	v_mfma_f32_16x16x32_bf16 v[28:31], v[132:135], v[202:205], v[28:31]
	v_mfma_f32_16x16x32_bf16 v[24:27], v[140:143], v[202:205], v[24:27]
	v_mfma_f32_16x16x32_bf16 v[12:15], v[132:135], v[210:213], v[12:15]
	v_mfma_f32_16x16x32_bf16 v[8:11], v[140:143], v[210:213], v[8:11]
	s_setprio 0
	s_barrier
	s_add_u32 s70, s34, 0x40000
	s_addc_u32 s71, s35, 0
	s_mov_b32 m0, s49
	v_lshl_add_u64 v[128:129], s[70:71], 0, v[144:145]
	global_load_lds_dwordx4 v[128:129], off
	v_lshl_add_u64 v[128:129], s[70:71], 0, v[146:147]
	s_mov_b32 m0, s52
	s_nop 0
	global_load_lds_dwordx4 v[128:129], off
	s_waitcnt vmcnt(6)
	s_barrier
	s_setprio 1
	v_mfma_f32_16x16x32_bf16 v[52:55], v[214:217], v[162:165], v[52:55]
	v_mfma_f32_16x16x32_bf16 v[48:51], v[222:225], v[162:165], v[48:51]
	v_mfma_f32_16x16x32_bf16 v[36:39], v[214:217], v[190:193], v[36:39]
	v_mfma_f32_16x16x32_bf16 v[32:35], v[222:225], v[190:193], v[32:35]
	v_mfma_f32_16x16x32_bf16 v[20:23], v[214:217], v[198:201], v[20:23]
	v_mfma_f32_16x16x32_bf16 v[16:19], v[222:225], v[198:201], v[16:19]
	v_mfma_f32_16x16x32_bf16 v[4:7], v[214:217], v[206:209], v[4:7]
	v_mfma_f32_16x16x32_bf16 v[0:3], v[222:225], v[206:209], v[0:3]
	v_mfma_f32_16x16x32_bf16 v[52:55], v[218:221], v[166:169], v[52:55]
	v_mfma_f32_16x16x32_bf16 v[48:51], v[226:229], v[166:169], v[48:51]
	v_mfma_f32_16x16x32_bf16 v[36:39], v[218:221], v[194:197], v[36:39]
	v_mfma_f32_16x16x32_bf16 v[32:35], v[226:229], v[194:197], v[32:35]
	v_mfma_f32_16x16x32_bf16 v[20:23], v[218:221], v[202:205], v[20:23]
	v_mfma_f32_16x16x32_bf16 v[16:19], v[226:229], v[202:205], v[16:19]
	v_mfma_f32_16x16x32_bf16 v[4:7], v[218:221], v[210:213], v[4:7]
	v_mfma_f32_16x16x32_bf16 v[0:3], v[226:229], v[210:213], v[0:3]
	s_setprio 0
	s_barrier
	ds_read_b128 v[128:131], v180
	ds_read_b128 v[132:135], v181
	ds_read_b128 v[136:139], v182
	ds_read_b128 v[140:143], v183
	s_add_u32 s36, s36, 0x40000
	s_addc_u32 s37, s37, 0
	s_mov_b32 m0, s53
	v_lshl_add_u64 v[214:215], s[36:37], 0, v[144:145]
	ds_read_b128 v[162:165], v151 offset:32768
	ds_read_b128 v[166:169], v151 offset:33792
	ds_read_b128 v[190:193], v151 offset:34816
	ds_read_b128 v[194:197], v151 offset:35840
	ds_read_b128 v[198:201], v151 offset:36864
	ds_read_b128 v[202:205], v151 offset:37888
	ds_read_b128 v[206:209], v151 offset:38912
	ds_read_b128 v[210:213], v151 offset:39936
	global_load_lds_dwordx4 v[214:215], off
	v_lshl_add_u64 v[214:215], s[36:37], 0, v[146:147]
	s_mov_b32 m0, s54
	s_nop 0
	global_load_lds_dwordx4 v[214:215], off
	s_waitcnt lgkmcnt(8)
	s_barrier
	s_waitcnt lgkmcnt(0)
	s_setprio 1
	s_waitcnt lgkmcnt(0)
	v_mfma_f32_16x16x32_bf16 v[124:127], v[128:131], v[162:165], v[124:127]
	v_mfma_f32_16x16x32_bf16 v[120:123], v[136:139], v[162:165], v[120:123]
	v_mfma_f32_16x16x32_bf16 v[108:111], v[128:131], v[190:193], v[108:111]
	v_mfma_f32_16x16x32_bf16 v[104:107], v[136:139], v[190:193], v[104:107]
	v_mfma_f32_16x16x32_bf16 v[92:95], v[128:131], v[198:201], v[92:95]
	v_mfma_f32_16x16x32_bf16 v[88:91], v[136:139], v[198:201], v[88:91]
	v_mfma_f32_16x16x32_bf16 v[76:79], v[128:131], v[206:209], v[76:79]
	v_mfma_f32_16x16x32_bf16 v[72:75], v[136:139], v[206:209], v[72:75]
	v_mfma_f32_16x16x32_bf16 v[124:127], v[132:135], v[166:169], v[124:127]
	v_mfma_f32_16x16x32_bf16 v[120:123], v[140:143], v[166:169], v[120:123]
	v_mfma_f32_16x16x32_bf16 v[108:111], v[132:135], v[194:197], v[108:111]
	v_mfma_f32_16x16x32_bf16 v[104:107], v[140:143], v[194:197], v[104:107]
	v_mfma_f32_16x16x32_bf16 v[92:95], v[132:135], v[202:205], v[92:95]
	v_mfma_f32_16x16x32_bf16 v[88:91], v[140:143], v[202:205], v[88:91]
	v_mfma_f32_16x16x32_bf16 v[76:79], v[132:135], v[210:213], v[76:79]
	v_mfma_f32_16x16x32_bf16 v[72:75], v[140:143], v[210:213], v[72:75]
	s_setprio 0
	s_barrier
	s_mov_b32 m0, s56
	v_lshl_add_u64 v[230:231], v[230:231], 0, s[10:11]
	ds_read_b128 v[214:217], v184
	ds_read_b128 v[218:221], v185
	ds_read_b128 v[222:225], v186
	ds_read_b128 v[226:229], v187
	global_load_lds_dwordx4 v[230:231], off
	v_lshl_add_u64 v[230:231], v[232:233], 0, s[10:11]
	s_mov_b32 m0, s57
	s_nop 0
	global_load_lds_dwordx4 v[230:231], off
	s_barrier
	s_waitcnt lgkmcnt(0)
	s_setprio 1
	s_waitcnt lgkmcnt(0)
	v_mfma_f32_16x16x32_bf16 v[116:119], v[214:217], v[162:165], v[116:119]
	v_mfma_f32_16x16x32_bf16 v[112:115], v[222:225], v[162:165], v[112:115]
	v_mfma_f32_16x16x32_bf16 v[100:103], v[214:217], v[190:193], v[100:103]
	v_mfma_f32_16x16x32_bf16 v[96:99], v[222:225], v[190:193], v[96:99]
	v_mfma_f32_16x16x32_bf16 v[84:87], v[214:217], v[198:201], v[84:87]
	v_mfma_f32_16x16x32_bf16 v[80:83], v[222:225], v[198:201], v[80:83]
	v_mfma_f32_16x16x32_bf16 v[68:71], v[214:217], v[206:209], v[68:71]
	v_mfma_f32_16x16x32_bf16 v[64:67], v[222:225], v[206:209], v[64:67]
	v_mfma_f32_16x16x32_bf16 v[116:119], v[218:221], v[166:169], v[116:119]
	v_mfma_f32_16x16x32_bf16 v[112:115], v[226:229], v[166:169], v[112:115]
	v_mfma_f32_16x16x32_bf16 v[100:103], v[218:221], v[194:197], v[100:103]
	v_mfma_f32_16x16x32_bf16 v[96:99], v[226:229], v[194:197], v[96:99]
	v_mfma_f32_16x16x32_bf16 v[84:87], v[218:221], v[202:205], v[84:87]
	v_mfma_f32_16x16x32_bf16 v[80:83], v[226:229], v[202:205], v[80:83]
	v_mfma_f32_16x16x32_bf16 v[68:71], v[218:221], v[210:213], v[68:71]
	v_mfma_f32_16x16x32_bf16 v[64:67], v[226:229], v[210:213], v[64:67]
	s_setprio 0
	s_mov_b32 m0, s58
	v_lshl_add_u64 v[230:231], v[234:235], 0, s[10:11]
	s_barrier
	ds_read_b128 v[162:165], v151 offset:49152
	ds_read_b128 v[166:169], v151 offset:50176
	ds_read_b128 v[190:193], v151 offset:51200
	ds_read_b128 v[194:197], v151 offset:52224
	ds_read_b128 v[198:201], v151 offset:53248
	ds_read_b128 v[202:205], v151 offset:54272
	ds_read_b128 v[206:209], v151 offset:55296
	ds_read_b128 v[210:213], v151 offset:56320
	global_load_lds_dwordx4 v[230:231], off
	v_lshl_add_u64 v[230:231], v[236:237], 0, s[10:11]
	s_mov_b32 m0, s59
	s_nop 0
	global_load_lds_dwordx4 v[230:231], off
	s_barrier
	s_waitcnt lgkmcnt(0)
	s_setprio 1
	s_waitcnt lgkmcnt(0)
	v_mfma_f32_16x16x32_bf16 v[60:63], v[128:131], v[162:165], v[60:63]
	v_mfma_f32_16x16x32_bf16 v[56:59], v[136:139], v[162:165], v[56:59]
	v_mfma_f32_16x16x32_bf16 v[44:47], v[128:131], v[190:193], v[44:47]
	v_mfma_f32_16x16x32_bf16 v[40:43], v[136:139], v[190:193], v[40:43]
	v_mfma_f32_16x16x32_bf16 v[28:31], v[128:131], v[198:201], v[28:31]
	v_mfma_f32_16x16x32_bf16 v[24:27], v[136:139], v[198:201], v[24:27]
	v_mfma_f32_16x16x32_bf16 v[12:15], v[128:131], v[206:209], v[12:15]
	v_mfma_f32_16x16x32_bf16 v[8:11], v[136:139], v[206:209], v[8:11]
	v_mfma_f32_16x16x32_bf16 v[60:63], v[132:135], v[166:169], v[60:63]
	v_mfma_f32_16x16x32_bf16 v[56:59], v[140:143], v[166:169], v[56:59]
	v_mfma_f32_16x16x32_bf16 v[44:47], v[132:135], v[194:197], v[44:47]
	v_mfma_f32_16x16x32_bf16 v[40:43], v[140:143], v[194:197], v[40:43]
	v_mfma_f32_16x16x32_bf16 v[28:31], v[132:135], v[202:205], v[28:31]
	v_mfma_f32_16x16x32_bf16 v[24:27], v[140:143], v[202:205], v[24:27]
	v_mfma_f32_16x16x32_bf16 v[12:15], v[132:135], v[210:213], v[12:15]
	v_mfma_f32_16x16x32_bf16 v[8:11], v[140:143], v[210:213], v[8:11]
	s_setprio 0
	s_barrier
	s_add_u32 s34, s34, 0x40080
	s_addc_u32 s35, s35, 0
	s_mov_b32 m0, s60
	v_lshl_add_u64 v[128:129], s[34:35], 0, v[144:145]
	global_load_lds_dwordx4 v[128:129], off
	v_lshl_add_u64 v[128:129], s[34:35], 0, v[146:147]
	s_mov_b32 m0, s61
	s_nop 0
	global_load_lds_dwordx4 v[128:129], off
	s_waitcnt vmcnt(6)
	s_barrier
	s_setprio 1
	v_mfma_f32_16x16x32_bf16 v[52:55], v[214:217], v[162:165], v[52:55]
	v_mfma_f32_16x16x32_bf16 v[48:51], v[222:225], v[162:165], v[48:51]
	v_mfma_f32_16x16x32_bf16 v[36:39], v[214:217], v[190:193], v[36:39]
	v_mfma_f32_16x16x32_bf16 v[32:35], v[222:225], v[190:193], v[32:35]
	v_mfma_f32_16x16x32_bf16 v[20:23], v[214:217], v[198:201], v[20:23]
	v_mfma_f32_16x16x32_bf16 v[16:19], v[222:225], v[198:201], v[16:19]
	v_mfma_f32_16x16x32_bf16 v[4:7], v[214:217], v[206:209], v[4:7]
	v_mfma_f32_16x16x32_bf16 v[0:3], v[222:225], v[206:209], v[0:3]
	v_mfma_f32_16x16x32_bf16 v[52:55], v[218:221], v[166:169], v[52:55]
	v_mfma_f32_16x16x32_bf16 v[48:51], v[226:229], v[166:169], v[48:51]
	v_mfma_f32_16x16x32_bf16 v[36:39], v[218:221], v[194:197], v[36:39]
	v_mfma_f32_16x16x32_bf16 v[32:35], v[226:229], v[194:197], v[32:35]
	v_mfma_f32_16x16x32_bf16 v[20:23], v[218:221], v[202:205], v[20:23]
	v_mfma_f32_16x16x32_bf16 v[16:19], v[226:229], v[202:205], v[16:19]
	v_mfma_f32_16x16x32_bf16 v[4:7], v[218:221], v[210:213], v[4:7]
	v_mfma_f32_16x16x32_bf16 v[0:3], v[226:229], v[210:213], v[0:3]
	s_setprio 0
	s_add_i32 s69, s69, 2
	s_add_u32 s67, s67, 0x100
	s_addc_u32 s68, s68, 0
	s_add_u32 s30, s30, 0x100
	s_addc_u32 s31, s31, 0
	s_cmp_gt_u32 s69, 13
	s_barrier
	s_cbranch_scc0 .LBB0_1480
	s_ashr_i32 s29, s28, 31
	s_lshl_b64 s[28:29], s[28:29], 8
	s_lshl_b32 s30, s12, 8
	v_lshl_add_u64 v[164:165], s[28:29], 0, v[148:149]
	s_ashr_i32 s31, s30, 31
	v_lshl_add_u64 v[166:167], s[30:31], 2, v[152:153]
	v_lshlrev_b64 v[128:129], 12, v[164:165]
	v_lshl_add_u64 v[128:129], v[166:167], 0, v[128:129]
	global_load_dwordx4 v[190:193], v[128:129], off
	global_load_dwordx4 v[194:197], v[128:129], off offset:64
	global_load_dwordx4 v[198:201], v[128:129], off offset:512
	global_load_dwordx4 v[202:205], v[128:129], off offset:576
	v_or_b32_e32 v168, 16, v164
	v_mov_b32_e32 v169, v165
	v_lshlrev_b64 v[128:129], 12, v[168:169]
	v_lshl_add_u64 v[128:129], v[166:167], 0, v[128:129]
	global_load_dwordx4 v[140:143], v[128:129], off
	global_load_dwordx4 v[136:139], v[128:129], off offset:64
	global_load_dwordx4 v[132:135], v[128:129], off offset:512
	s_nop 0
	global_load_dwordx4 v[128:131], v[128:129], off offset:576
	v_and_b32_e32 v163, 64, v188
	v_xor_b32_e32 v189, 16, v188
	v_add_u32_e32 v207, 64, v163
	v_xor_b32_e32 v206, 32, v188
	v_cmp_lt_i32_e32 vcc, v189, v207
	v_or_b32_e32 v162, s30, v150
	v_mov_b32_e32 v163, s31
	v_cndmask_b32_e32 v189, v188, v189, vcc
	v_cmp_lt_i32_e32 vcc, v206, v207
	s_waitcnt vmcnt(0)
	v_lshlrev_b32_e32 v189, 2, v189
	s_lshl_b32 s28, s12, 2
	v_cndmask_b32_e32 v216, v188, v206, vcc
	v_lshlrev_b64 v[206:207], 10, v[164:165]
	v_lshl_add_u64 v[206:207], v[206:207], 0, v[162:163]
	v_lshl_add_u64 v[208:209], v[206:207], 2, s[78:79]
	v_lshlrev_b64 v[206:207], 1, v[206:207]
	v_lshl_add_u64 v[210:211], s[2:3], 0, v[206:207]
	v_or_b32_e32 v212, 32, v206
	v_mov_b32_e32 v213, v207
	v_or_b32_e32 v214, 0x100, v206
	v_mov_b32_e32 v215, v207
	v_lshl_add_u64 v[212:213], s[2:3], 0, v[212:213]
	v_lshl_add_u64 v[214:215], s[2:3], 0, v[214:215]
	v_or_b32_e32 v206, 0x120, v206
	s_ashr_i32 s29, s28, 31
	s_waitcnt vmcnt(0)
	v_pk_add_f32 v[126:127], v[126:127], v[192:193]
	v_pk_add_f32 v[124:125], v[124:125], v[190:191]
	v_pk_add_f32 v[120:121], v[120:121], v[194:195]
	v_pk_add_f32 v[122:123], v[122:123], v[196:197]
	v_pk_add_f32 v[116:117], v[116:117], v[198:199]
	v_pk_add_f32 v[190:191], v[112:113], v[202:203]
	global_store_dwordx4 v[208:209], v[124:127], off
	v_cvt_pk_bf16_f32 v112, v124, v125
	v_mul_f32_e32 v196, v120, v120
	v_mul_f32_e32 v197, v116, v116
	v_mul_f32_e32 v124, v124, v124
	v_fmac_f32_e32 v124, v125, v125
	v_fmac_f32_e32 v196, v121, v121
	v_pk_add_f32 v[118:119], v[118:119], v[200:201]
	v_mul_f32_e32 v198, v190, v190
	v_fmac_f32_e32 v197, v117, v117
	v_fmac_f32_e32 v124, v126, v126
	v_fmac_f32_e32 v196, v122, v122
	v_pk_add_f32 v[192:193], v[114:115], v[204:205]
	v_fmac_f32_e32 v198, v191, v191
	v_fmac_f32_e32 v197, v118, v118
	v_fmac_f32_e32 v124, v127, v127
	v_fmac_f32_e32 v196, v123, v123
	v_cvt_pk_bf16_f32 v113, v126, v127
	v_bfe_u32 v246, v176, 4, 1
	v_mul_u32_u24_e32 v246, 24, v246
	v_mov_b32_e32 v247, 0
	s_nop 1
	v_mov_b32_e32 v240, v112
	v_mov_b32_e32 v241, v113
	v_lshl_add_u64 v[244:245], v[210:211], 0, v[246:247]
	v_fmac_f32_e32 v198, v192, v192
	v_fmac_f32_e32 v197, v119, v119
	v_add_f32_e32 v112, v124, v196
	v_fmac_f32_e32 v198, v193, v193
	v_add_f32_e32 v112, v112, v197
	v_add_f32_e32 v112, v112, v198
	ds_bpermute_b32 v113, v189, v112
	v_cvt_pk_bf16_f32 v114, v120, v121
	v_cvt_pk_bf16_f32 v115, v122, v123
	v_cvt_pk_bf16_f32 v194, v116, v117
	v_cvt_pk_bf16_f32 v195, v118, v119
	global_store_dwordx4 v[208:209], v[120:123], off offset:64
	v_mov_b32_e32 v242, v114
	v_mov_b32_e32 v243, v115
	s_nop 1
	v_permlane16_swap_b32 v240, v242
	v_permlane16_swap_b32 v241, v243
	global_store_dwordx4 v[244:245], v[240:243], off
	global_store_dwordx4 v[208:209], v[116:119], off offset:512
	s_nop 1
	v_mov_b32_e32 v240, v194
	v_mov_b32_e32 v241, v195
	v_lshl_add_u64 v[244:245], v[214:215], 0, v[246:247]
	global_store_dwordx4 v[208:209], v[190:193], off offset:576
	s_waitcnt lgkmcnt(0)
	v_add_f32_e32 v112, v112, v113
	v_lshlrev_b32_e32 v116, 2, v216
	ds_bpermute_b32 v113, v116, v112
	v_lshl_add_u64 v[114:115], s[2:3], 0, v[206:207]
	v_cvt_pk_bf16_f32 v118, v190, v191
	v_cvt_pk_bf16_f32 v119, v192, v193
	v_mov_b32_e32 v242, v118
	v_mov_b32_e32 v243, v119
	s_nop 1
	v_permlane16_swap_b32 v240, v242
	v_permlane16_swap_b32 v241, v243
	global_store_dwordx4 v[244:245], v[240:243], off
	s_and_saveexec_b64 s[30:31], s[6:7]
	s_cbranch_execz .LBB0_1483
	v_lshlrev_b64 v[114:115], 6, v[164:165]
	v_lshl_add_u64 v[114:115], s[4:5], 0, v[114:115]
	v_lshl_add_u64 v[114:115], s[28:29], 2, v[114:115]
	s_lshl_b32 s12, s55, 2
	v_lshl_add_u64 v[114:115], v[114:115], 0, s[12:13]
	s_waitcnt lgkmcnt(0)
	v_add_f32_e32 v112, v112, v113
	flat_store_dword v[114:115], v112
.LBB0_1483:
	s_or_b64 exec, exec, s[30:31]
	s_waitcnt lgkmcnt(0)
	v_lshlrev_b64 v[112:113], 10, v[168:169]
	v_lshl_add_u64 v[112:113], v[112:113], 0, v[162:163]
	v_pk_add_f32 v[108:109], v[108:109], v[140:141]
	v_lshl_add_u64 v[114:115], v[112:113], 2, s[78:79]
	v_lshlrev_b64 v[112:113], 1, v[112:113]
	v_mul_f32_e32 v117, v108, v108
	v_pk_add_f32 v[110:111], v[110:111], v[142:143]
	v_lshl_add_u64 v[118:119], s[2:3], 0, v[112:113]
	v_fmac_f32_e32 v117, v109, v109
	v_pk_add_f32 v[106:107], v[106:107], v[138:139]
	v_pk_add_f32 v[104:105], v[104:105], v[136:137]
	global_store_dwordx4 v[114:115], v[108:111], off
	v_cvt_pk_bf16_f32 v120, v108, v109
	v_cvt_pk_bf16_f32 v121, v110, v111
	s_nop 1
	v_mov_b32_e32 v240, v120
	v_mov_b32_e32 v241, v121
	v_lshl_add_u64 v[244:245], v[118:119], 0, v[246:247]
	v_fmac_f32_e32 v117, v110, v110
	global_store_dwordx4 v[114:115], v[104:107], off offset:64
	v_or_b32_e32 v108, 32, v112
	v_mov_b32_e32 v109, v113
	v_cvt_pk_bf16_f32 v110, v104, v105
	v_mul_f32_e32 v104, v104, v104
	v_lshl_add_u64 v[108:109], s[2:3], 0, v[108:109]
	v_fmac_f32_e32 v104, v105, v105
	v_pk_add_f32 v[102:103], v[102:103], v[134:135]
	v_pk_add_f32 v[100:101], v[100:101], v[132:133]
	v_fmac_f32_e32 v117, v111, v111
	v_cvt_pk_bf16_f32 v111, v106, v107
	v_mov_b32_e32 v242, v110
	v_mov_b32_e32 v243, v111
	s_nop 1
	v_permlane16_swap_b32 v240, v242
	v_permlane16_swap_b32 v241, v243
	global_store_dwordx4 v[244:245], v[240:243], off
	v_fmac_f32_e32 v104, v106, v106
	global_store_dwordx4 v[114:115], v[100:103], off offset:512
	v_cvt_pk_bf16_f32 v106, v100, v101
	v_fmac_f32_e32 v104, v107, v107
	v_add_f32_e32 v107, v117, v104
	v_mul_f32_e32 v100, v100, v100
	v_fmac_f32_e32 v100, v101, v101
	v_fmac_f32_e32 v100, v102, v102
	v_fmac_f32_e32 v100, v103, v103
	v_add_f32_e32 v107, v107, v100
	v_pk_add_f32 v[100:101], v[98:99], v[130:131]
	v_pk_add_f32 v[98:99], v[96:97], v[128:129]
	v_or_b32_e32 v104, 0x100, v112
	v_mul_f32_e32 v96, v98, v98
	v_fmac_f32_e32 v96, v99, v99
	v_fmac_f32_e32 v96, v100, v100
	v_fmac_f32_e32 v96, v101, v101
	v_add_f32_e32 v96, v107, v96
	ds_bpermute_b32 v97, v189, v96
	v_mov_b32_e32 v105, v113
	v_or_b32_e32 v112, 0x120, v112
	v_lshl_add_u64 v[104:105], s[2:3], 0, v[104:105]
	v_cvt_pk_bf16_f32 v107, v102, v103
	s_waitcnt lgkmcnt(0)
	v_add_f32_e32 v96, v96, v97
	ds_bpermute_b32 v97, v116, v96
	v_lshl_add_u64 v[102:103], s[2:3], 0, v[112:113]
	s_nop 1
	v_mov_b32_e32 v240, v106
	v_mov_b32_e32 v241, v107
	v_lshl_add_u64 v[244:245], v[104:105], 0, v[246:247]
	global_store_dwordx4 v[114:115], v[98:101], off offset:576
	s_nop 1
	v_cvt_pk_bf16_f32 v98, v98, v99
	v_cvt_pk_bf16_f32 v99, v100, v101
	v_mov_b32_e32 v242, v98
	v_mov_b32_e32 v243, v99
	s_nop 1
	v_permlane16_swap_b32 v240, v242
	v_permlane16_swap_b32 v241, v243
	global_store_dwordx4 v[244:245], v[240:243], off
	s_and_saveexec_b64 s[30:31], s[6:7]
	s_cbranch_execz .LBB0_1485
	v_lshlrev_b64 v[98:99], 6, v[168:169]
	v_lshl_add_u64 v[98:99], s[4:5], 0, v[98:99]
	v_lshl_add_u64 v[98:99], s[28:29], 2, v[98:99]
	s_lshl_b32 s12, s55, 2
	v_lshl_add_u64 v[98:99], v[98:99], 0, s[12:13]
	s_waitcnt lgkmcnt(0)
	v_add_f32_e32 v96, v96, v97
	flat_store_dword v[98:99], v96
.LBB0_1485:
	s_or_b64 exec, exec, s[30:31]
	v_or_b32_e32 v114, 32, v164
	v_mov_b32_e32 v115, v165
	s_waitcnt lgkmcnt(0)
	v_lshlrev_b64 v[96:97], 12, v[114:115]
	v_lshl_add_u64 v[96:97], v[166:167], 0, v[96:97]
	global_load_dwordx4 v[118:121], v[96:97], off
	global_load_dwordx4 v[122:125], v[96:97], off offset:64
	global_load_dwordx4 v[126:129], v[96:97], off offset:512
	global_load_dwordx4 v[130:133], v[96:97], off offset:576
	v_or_b32_e32 v112, 48, v164
	v_mov_b32_e32 v113, v165
	v_lshlrev_b64 v[96:97], 12, v[112:113]
	v_lshl_add_u64 v[96:97], v[166:167], 0, v[96:97]
	global_load_dwordx4 v[108:111], v[96:97], off
	global_load_dwordx4 v[104:107], v[96:97], off offset:64
	global_load_dwordx4 v[100:103], v[96:97], off offset:512
	s_nop 0
	global_load_dwordx4 v[96:99], v[96:97], off offset:576
	v_lshlrev_b64 v[134:135], 10, v[114:115]
	v_lshl_add_u64 v[134:135], v[134:135], 0, v[162:163]
	v_lshl_add_u64 v[136:137], v[134:135], 2, s[78:79]
	v_lshlrev_b64 v[134:135], 1, v[134:135]
	v_lshl_add_u64 v[138:139], s[2:3], 0, v[134:135]
	s_waitcnt vmcnt(0)
	v_or_b32_e32 v140, 32, v134
	v_mov_b32_e32 v141, v135
	v_or_b32_e32 v142, 0x100, v134
	v_mov_b32_e32 v143, v135
	v_or_b32_e32 v134, 0x120, v134
	v_lshl_add_u64 v[140:141], s[2:3], 0, v[140:141]
	v_lshl_add_u64 v[142:143], s[2:3], 0, v[142:143]
	s_waitcnt vmcnt(0)
	v_pk_add_f32 v[92:93], v[92:93], v[118:119]
	v_pk_add_f32 v[88:89], v[88:89], v[122:123]
	v_pk_add_f32 v[84:85], v[84:85], v[126:127]
	v_mul_f32_e32 v117, v92, v92
	v_mul_f32_e32 v122, v88, v88
	v_pk_add_f32 v[94:95], v[94:95], v[120:121]
	v_pk_add_f32 v[90:91], v[90:91], v[124:125]
	v_pk_add_f32 v[118:119], v[80:81], v[130:131]
	v_mul_f32_e32 v123, v84, v84
	v_fmac_f32_e32 v117, v93, v93
	v_fmac_f32_e32 v122, v89, v89
	v_pk_add_f32 v[86:87], v[86:87], v[128:129]
	v_mul_f32_e32 v124, v118, v118
	v_fmac_f32_e32 v123, v85, v85
	v_fmac_f32_e32 v117, v94, v94
	v_fmac_f32_e32 v122, v90, v90
	v_pk_add_f32 v[120:121], v[82:83], v[132:133]
	v_cvt_pk_bf16_f32 v80, v92, v93
	v_fmac_f32_e32 v124, v119, v119
	v_fmac_f32_e32 v123, v86, v86
	v_fmac_f32_e32 v117, v95, v95
	v_fmac_f32_e32 v122, v91, v91
	global_store_dwordx4 v[136:137], v[92:95], off
	v_cvt_pk_bf16_f32 v81, v94, v95
	s_nop 1
	v_mov_b32_e32 v240, v80
	v_mov_b32_e32 v241, v81
	v_lshl_add_u64 v[244:245], v[138:139], 0, v[246:247]
	v_fmac_f32_e32 v124, v120, v120
	v_fmac_f32_e32 v123, v87, v87
	v_add_f32_e32 v80, v117, v122
	v_add_f32_e32 v80, v80, v123
	v_fmac_f32_e32 v124, v121, v121
	v_add_f32_e32 v80, v80, v124
	ds_bpermute_b32 v81, v189, v80
	v_cvt_pk_bf16_f32 v82, v88, v89
	v_cvt_pk_bf16_f32 v83, v90, v91
	v_cvt_pk_bf16_f32 v92, v84, v85
	global_store_dwordx4 v[136:137], v[88:91], off offset:64
	v_mov_b32_e32 v242, v82
	v_mov_b32_e32 v243, v83
	s_nop 1
	v_permlane16_swap_b32 v240, v242
	v_permlane16_swap_b32 v241, v243
	global_store_dwordx4 v[244:245], v[240:243], off
	s_waitcnt lgkmcnt(0)
	v_add_f32_e32 v80, v80, v81
	ds_bpermute_b32 v81, v116, v80
	v_cvt_pk_bf16_f32 v93, v86, v87
	v_lshl_add_u64 v[82:83], s[2:3], 0, v[134:135]
	global_store_dwordx4 v[136:137], v[84:87], off offset:512
	s_nop 1
	v_mov_b32_e32 v240, v92
	v_mov_b32_e32 v241, v93
	v_lshl_add_u64 v[244:245], v[142:143], 0, v[246:247]
	global_store_dwordx4 v[136:137], v[118:121], off offset:576
	v_cvt_pk_bf16_f32 v84, v118, v119
	v_cvt_pk_bf16_f32 v85, v120, v121
	v_mov_b32_e32 v242, v84
	v_mov_b32_e32 v243, v85
	s_nop 1
	v_permlane16_swap_b32 v240, v242
	v_permlane16_swap_b32 v241, v243
	global_store_dwordx4 v[244:245], v[240:243], off
	s_and_saveexec_b64 s[30:31], s[6:7]
	s_cbranch_execz .LBB0_1487
	v_lshlrev_b64 v[82:83], 6, v[114:115]
	v_lshl_add_u64 v[82:83], s[4:5], 0, v[82:83]
	v_lshl_add_u64 v[82:83], s[28:29], 2, v[82:83]
	s_lshl_b32 s12, s55, 2
	v_lshl_add_u64 v[82:83], v[82:83], 0, s[12:13]
	s_waitcnt lgkmcnt(0)
	v_add_f32_e32 v80, v80, v81
	flat_store_dword v[82:83], v80
.LBB0_1487:
	s_or_b64 exec, exec, s[30:31]
	s_waitcnt lgkmcnt(0)
	v_lshlrev_b64 v[80:81], 10, v[112:113]
	v_lshl_add_u64 v[80:81], v[80:81], 0, v[162:163]
	v_lshl_add_u64 v[82:83], v[80:81], 2, s[78:79]
	v_lshlrev_b64 v[80:81], 1, v[80:81]
	v_pk_add_f32 v[78:79], v[78:79], v[110:111]
	v_pk_add_f32 v[76:77], v[76:77], v[108:109]
	v_lshl_add_u64 v[84:85], s[2:3], 0, v[80:81]
	global_store_dwordx4 v[82:83], v[76:79], off
	v_cvt_pk_bf16_f32 v86, v76, v77
	v_cvt_pk_bf16_f32 v87, v78, v79
	s_nop 1
	v_mov_b32_e32 v240, v86
	v_mov_b32_e32 v241, v87
	v_lshl_add_u64 v[244:245], v[84:85], 0, v[246:247]
	v_mul_f32_e32 v84, v76, v76
	v_fmac_f32_e32 v84, v77, v77
	v_pk_add_f32 v[74:75], v[74:75], v[106:107]
	v_pk_add_f32 v[72:73], v[72:73], v[104:105]
	v_fmac_f32_e32 v84, v78, v78
	global_store_dwordx4 v[82:83], v[72:75], off offset:64
	v_or_b32_e32 v76, 32, v80
	v_mov_b32_e32 v77, v81
	v_cvt_pk_bf16_f32 v78, v72, v73
	v_mul_f32_e32 v72, v72, v72
	v_lshl_add_u64 v[76:77], s[2:3], 0, v[76:77]
	v_fmac_f32_e32 v72, v73, v73
	v_pk_add_f32 v[70:71], v[70:71], v[102:103]
	v_pk_add_f32 v[68:69], v[68:69], v[100:101]
	v_fmac_f32_e32 v84, v79, v79
	v_cvt_pk_bf16_f32 v79, v74, v75
	v_mov_b32_e32 v242, v78
	v_mov_b32_e32 v243, v79
	s_nop 1
	v_permlane16_swap_b32 v240, v242
	v_permlane16_swap_b32 v241, v243
	global_store_dwordx4 v[244:245], v[240:243], off
	v_fmac_f32_e32 v72, v74, v74
	global_store_dwordx4 v[82:83], v[68:71], off offset:512
	v_cvt_pk_bf16_f32 v74, v68, v69
	v_fmac_f32_e32 v72, v75, v75
	v_add_f32_e32 v75, v84, v72
	v_mul_f32_e32 v68, v68, v68
	v_fmac_f32_e32 v68, v69, v69
	v_fmac_f32_e32 v68, v70, v70
	v_fmac_f32_e32 v68, v71, v71
	v_add_f32_e32 v75, v75, v68
	v_pk_add_f32 v[68:69], v[66:67], v[98:99]
	v_pk_add_f32 v[66:67], v[64:65], v[96:97]
	v_or_b32_e32 v72, 0x100, v80
	v_mul_f32_e32 v64, v66, v66
	v_fmac_f32_e32 v64, v67, v67
	v_fmac_f32_e32 v64, v68, v68
	v_fmac_f32_e32 v64, v69, v69
	v_add_f32_e32 v64, v75, v64
	ds_bpermute_b32 v65, v189, v64
	v_mov_b32_e32 v73, v81
	v_or_b32_e32 v80, 0x120, v80
	v_lshl_add_u64 v[72:73], s[2:3], 0, v[72:73]
	v_cvt_pk_bf16_f32 v75, v70, v71
	s_waitcnt lgkmcnt(0)
	v_add_f32_e32 v64, v64, v65
	ds_bpermute_b32 v65, v116, v64
	v_lshl_add_u64 v[70:71], s[2:3], 0, v[80:81]
	s_nop 1
	v_mov_b32_e32 v240, v74
	v_mov_b32_e32 v241, v75
	v_lshl_add_u64 v[244:245], v[72:73], 0, v[246:247]
	global_store_dwordx4 v[82:83], v[66:69], off offset:576
	s_nop 1
	v_cvt_pk_bf16_f32 v66, v66, v67
	v_cvt_pk_bf16_f32 v67, v68, v69
	v_mov_b32_e32 v242, v66
	v_mov_b32_e32 v243, v67
	s_nop 1
	v_permlane16_swap_b32 v240, v242
	v_permlane16_swap_b32 v241, v243
	global_store_dwordx4 v[244:245], v[240:243], off
	s_and_saveexec_b64 s[30:31], s[6:7]
	s_cbranch_execz .LBB0_1489
	v_lshlrev_b64 v[66:67], 6, v[112:113]
	v_lshl_add_u64 v[66:67], s[4:5], 0, v[66:67]
	v_lshl_add_u64 v[66:67], s[28:29], 2, v[66:67]
	s_lshl_b32 s12, s55, 2
	v_lshl_add_u64 v[66:67], v[66:67], 0, s[12:13]
	s_waitcnt lgkmcnt(0)
	v_add_f32_e32 v64, v64, v65
	flat_store_dword v[66:67], v64
.LBB0_1489:
	s_or_b64 exec, exec, s[30:31]
	v_lshl_add_u64 v[82:83], v[164:165], 0, s[10:11]
	s_waitcnt lgkmcnt(0)
	v_lshlrev_b64 v[64:65], 12, v[82:83]
	v_lshl_add_u64 v[64:65], v[166:167], 0, v[64:65]
	global_load_dwordx4 v[84:87], v[64:65], off
	global_load_dwordx4 v[88:91], v[64:65], off offset:64
	global_load_dwordx4 v[92:95], v[64:65], off offset:512
	global_load_dwordx4 v[96:99], v[64:65], off offset:576
	v_lshl_add_u64 v[80:81], v[164:165], 0, s[14:15]
	v_lshlrev_b64 v[64:65], 12, v[80:81]
	v_lshl_add_u64 v[64:65], v[166:167], 0, v[64:65]
	global_load_dwordx4 v[76:79], v[64:65], off
	global_load_dwordx4 v[72:75], v[64:65], off offset:64
	global_load_dwordx4 v[68:71], v[64:65], off offset:512
	s_nop 0
	global_load_dwordx4 v[64:67], v[64:65], off offset:576
	v_lshlrev_b64 v[100:101], 10, v[82:83]
	v_lshl_add_u64 v[100:101], v[100:101], 0, v[162:163]
	v_lshl_add_u64 v[102:103], v[100:101], 2, s[78:79]
	v_lshlrev_b64 v[100:101], 1, v[100:101]
	v_lshl_add_u64 v[104:105], s[2:3], 0, v[100:101]
	s_waitcnt vmcnt(0)
	v_or_b32_e32 v106, 32, v100
	v_mov_b32_e32 v107, v101
	v_or_b32_e32 v108, 0x100, v100
	v_mov_b32_e32 v109, v101
	v_or_b32_e32 v100, 0x120, v100
	v_lshl_add_u64 v[106:107], s[2:3], 0, v[106:107]
	v_lshl_add_u64 v[108:109], s[2:3], 0, v[108:109]
	s_waitcnt vmcnt(0)
	v_pk_add_f32 v[60:61], v[60:61], v[84:85]
	v_pk_add_f32 v[56:57], v[56:57], v[88:89]
	v_pk_add_f32 v[52:53], v[52:53], v[92:93]
	v_mul_f32_e32 v88, v60, v60
	v_mul_f32_e32 v89, v56, v56
	v_pk_add_f32 v[62:63], v[62:63], v[86:87]
	v_pk_add_f32 v[58:59], v[58:59], v[90:91]
	v_pk_add_f32 v[84:85], v[48:49], v[96:97]
	v_mul_f32_e32 v90, v52, v52
	v_fmac_f32_e32 v88, v61, v61
	v_fmac_f32_e32 v89, v57, v57
	v_pk_add_f32 v[54:55], v[54:55], v[94:95]
	v_mul_f32_e32 v91, v84, v84
	v_fmac_f32_e32 v90, v53, v53
	v_fmac_f32_e32 v88, v62, v62
	v_fmac_f32_e32 v89, v58, v58
	v_pk_add_f32 v[86:87], v[50:51], v[98:99]
	v_cvt_pk_bf16_f32 v48, v60, v61
	v_fmac_f32_e32 v91, v85, v85
	v_fmac_f32_e32 v90, v54, v54
	v_fmac_f32_e32 v88, v63, v63
	v_fmac_f32_e32 v89, v59, v59
	global_store_dwordx4 v[102:103], v[60:63], off
	v_cvt_pk_bf16_f32 v49, v62, v63
	s_nop 1
	v_mov_b32_e32 v240, v48
	v_mov_b32_e32 v241, v49
	v_lshl_add_u64 v[244:245], v[104:105], 0, v[246:247]
	v_fmac_f32_e32 v91, v86, v86
	v_fmac_f32_e32 v90, v55, v55
	v_add_f32_e32 v48, v88, v89
	v_add_f32_e32 v48, v48, v90
	v_fmac_f32_e32 v91, v87, v87
	v_add_f32_e32 v48, v48, v91
	ds_bpermute_b32 v49, v189, v48
	v_cvt_pk_bf16_f32 v50, v56, v57
	v_cvt_pk_bf16_f32 v51, v58, v59
	v_cvt_pk_bf16_f32 v60, v52, v53
	global_store_dwordx4 v[102:103], v[56:59], off offset:64
	v_mov_b32_e32 v242, v50
	v_mov_b32_e32 v243, v51
	s_nop 1
	v_permlane16_swap_b32 v240, v242
	v_permlane16_swap_b32 v241, v243
	global_store_dwordx4 v[244:245], v[240:243], off
	s_waitcnt lgkmcnt(0)
	v_add_f32_e32 v48, v48, v49
	ds_bpermute_b32 v49, v116, v48
	v_cvt_pk_bf16_f32 v61, v54, v55
	v_lshl_add_u64 v[50:51], s[2:3], 0, v[100:101]
	global_store_dwordx4 v[102:103], v[52:55], off offset:512
	s_nop 1
	v_mov_b32_e32 v240, v60
	v_mov_b32_e32 v241, v61
	v_lshl_add_u64 v[244:245], v[108:109], 0, v[246:247]
	global_store_dwordx4 v[102:103], v[84:87], off offset:576
	v_cvt_pk_bf16_f32 v52, v84, v85
	v_cvt_pk_bf16_f32 v53, v86, v87
	v_mov_b32_e32 v242, v52
	v_mov_b32_e32 v243, v53
	s_nop 1
	v_permlane16_swap_b32 v240, v242
	v_permlane16_swap_b32 v241, v243
	global_store_dwordx4 v[244:245], v[240:243], off
	s_and_saveexec_b64 s[30:31], s[6:7]
	s_cbranch_execz .LBB0_1491
	v_lshlrev_b64 v[50:51], 6, v[82:83]
	v_lshl_add_u64 v[50:51], s[4:5], 0, v[50:51]
	v_lshl_add_u64 v[50:51], s[28:29], 2, v[50:51]
	s_lshl_b32 s12, s55, 2
	v_lshl_add_u64 v[50:51], v[50:51], 0, s[12:13]
	s_waitcnt lgkmcnt(0)
	v_add_f32_e32 v48, v48, v49
	flat_store_dword v[50:51], v48
.LBB0_1491:
	s_or_b64 exec, exec, s[30:31]
	s_waitcnt lgkmcnt(0)
	v_lshlrev_b64 v[48:49], 10, v[80:81]
	v_lshl_add_u64 v[48:49], v[48:49], 0, v[162:163]
	v_lshl_add_u64 v[50:51], v[48:49], 2, s[78:79]
	v_lshlrev_b64 v[48:49], 1, v[48:49]
	v_pk_add_f32 v[46:47], v[46:47], v[78:79]
	v_pk_add_f32 v[44:45], v[44:45], v[76:77]
	v_lshl_add_u64 v[52:53], s[2:3], 0, v[48:49]
	global_store_dwordx4 v[50:51], v[44:47], off
	v_cvt_pk_bf16_f32 v54, v44, v45
	v_cvt_pk_bf16_f32 v55, v46, v47
	s_nop 1
	v_mov_b32_e32 v240, v54
	v_mov_b32_e32 v241, v55
	v_lshl_add_u64 v[244:245], v[52:53], 0, v[246:247]
	v_mul_f32_e32 v52, v44, v44
	v_fmac_f32_e32 v52, v45, v45
	v_pk_add_f32 v[42:43], v[42:43], v[74:75]
	v_pk_add_f32 v[40:41], v[40:41], v[72:73]
	v_fmac_f32_e32 v52, v46, v46
	global_store_dwordx4 v[50:51], v[40:43], off offset:64
	v_or_b32_e32 v44, 32, v48
	v_mov_b32_e32 v45, v49
	v_cvt_pk_bf16_f32 v46, v40, v41
	v_mul_f32_e32 v40, v40, v40
	v_lshl_add_u64 v[44:45], s[2:3], 0, v[44:45]
	v_fmac_f32_e32 v40, v41, v41
	v_pk_add_f32 v[38:39], v[38:39], v[70:71]
	v_pk_add_f32 v[36:37], v[36:37], v[68:69]
	v_fmac_f32_e32 v52, v47, v47
	v_cvt_pk_bf16_f32 v47, v42, v43
	v_mov_b32_e32 v242, v46
	v_mov_b32_e32 v243, v47
	s_nop 1
	v_permlane16_swap_b32 v240, v242
	v_permlane16_swap_b32 v241, v243
	global_store_dwordx4 v[244:245], v[240:243], off
	v_fmac_f32_e32 v40, v42, v42
	global_store_dwordx4 v[50:51], v[36:39], off offset:512
	v_cvt_pk_bf16_f32 v42, v36, v37
	v_fmac_f32_e32 v40, v43, v43
	v_add_f32_e32 v43, v52, v40
	v_mul_f32_e32 v36, v36, v36
	v_fmac_f32_e32 v36, v37, v37
	v_fmac_f32_e32 v36, v38, v38
	v_fmac_f32_e32 v36, v39, v39
	v_add_f32_e32 v43, v43, v36
	v_pk_add_f32 v[36:37], v[34:35], v[66:67]
	v_pk_add_f32 v[34:35], v[32:33], v[64:65]
	v_or_b32_e32 v40, 0x100, v48
	v_mul_f32_e32 v32, v34, v34
	v_fmac_f32_e32 v32, v35, v35
	v_fmac_f32_e32 v32, v36, v36
	v_fmac_f32_e32 v32, v37, v37
	v_add_f32_e32 v32, v43, v32
	ds_bpermute_b32 v33, v189, v32
	v_mov_b32_e32 v41, v49
	v_or_b32_e32 v48, 0x120, v48
	v_lshl_add_u64 v[40:41], s[2:3], 0, v[40:41]
	v_cvt_pk_bf16_f32 v43, v38, v39
	s_waitcnt lgkmcnt(0)
	v_add_f32_e32 v32, v32, v33
	ds_bpermute_b32 v33, v116, v32
	v_lshl_add_u64 v[38:39], s[2:3], 0, v[48:49]
	s_nop 1
	v_mov_b32_e32 v240, v42
	v_mov_b32_e32 v241, v43
	v_lshl_add_u64 v[244:245], v[40:41], 0, v[246:247]
	global_store_dwordx4 v[50:51], v[34:37], off offset:576
	s_nop 1
	v_cvt_pk_bf16_f32 v34, v34, v35
	v_cvt_pk_bf16_f32 v35, v36, v37
	v_mov_b32_e32 v242, v34
	v_mov_b32_e32 v243, v35
	s_nop 1
	v_permlane16_swap_b32 v240, v242
	v_permlane16_swap_b32 v241, v243
	global_store_dwordx4 v[244:245], v[240:243], off
	s_and_saveexec_b64 s[30:31], s[6:7]
	s_cbranch_execz .LBB0_1493
	v_lshlrev_b64 v[34:35], 6, v[80:81]
	v_lshl_add_u64 v[34:35], s[4:5], 0, v[34:35]
	v_lshl_add_u64 v[34:35], s[28:29], 2, v[34:35]
	s_lshl_b32 s12, s55, 2
	v_lshl_add_u64 v[34:35], v[34:35], 0, s[12:13]
	s_waitcnt lgkmcnt(0)
	v_add_f32_e32 v32, v32, v33
	flat_store_dword v[34:35], v32
.LBB0_1493:
	s_or_b64 exec, exec, s[30:31]
	v_lshl_add_u64 v[50:51], v[164:165], 0, s[16:17]
	s_waitcnt lgkmcnt(0)
	v_lshlrev_b64 v[32:33], 12, v[50:51]
	v_lshl_add_u64 v[32:33], v[166:167], 0, v[32:33]
	global_load_dwordx4 v[52:55], v[32:33], off
	global_load_dwordx4 v[56:59], v[32:33], off offset:64
	global_load_dwordx4 v[60:63], v[32:33], off offset:512
	global_load_dwordx4 v[64:67], v[32:33], off offset:576
	v_lshl_add_u64 v[48:49], v[164:165], 0, s[18:19]
	v_lshlrev_b64 v[32:33], 12, v[48:49]
	v_lshl_add_u64 v[32:33], v[166:167], 0, v[32:33]
	global_load_dwordx4 v[44:47], v[32:33], off
	global_load_dwordx4 v[40:43], v[32:33], off offset:64
	global_load_dwordx4 v[36:39], v[32:33], off offset:512
	s_nop 0
	global_load_dwordx4 v[32:35], v[32:33], off offset:576
	v_lshlrev_b64 v[68:69], 10, v[50:51]
	v_lshl_add_u64 v[68:69], v[68:69], 0, v[162:163]
	v_lshl_add_u64 v[70:71], v[68:69], 2, s[78:79]
	v_lshlrev_b64 v[68:69], 1, v[68:69]
	v_lshl_add_u64 v[72:73], s[2:3], 0, v[68:69]
	s_waitcnt vmcnt(0)
	v_or_b32_e32 v74, 32, v68
	v_mov_b32_e32 v75, v69
	v_or_b32_e32 v76, 0x100, v68
	v_mov_b32_e32 v77, v69
	v_or_b32_e32 v68, 0x120, v68
	v_lshl_add_u64 v[74:75], s[2:3], 0, v[74:75]
	v_lshl_add_u64 v[76:77], s[2:3], 0, v[76:77]
	s_waitcnt vmcnt(0)
	v_pk_add_f32 v[28:29], v[28:29], v[52:53]
	v_pk_add_f32 v[24:25], v[24:25], v[56:57]
	v_pk_add_f32 v[20:21], v[20:21], v[60:61]
	v_mul_f32_e32 v56, v28, v28
	v_mul_f32_e32 v57, v24, v24
	v_pk_add_f32 v[30:31], v[30:31], v[54:55]
	v_pk_add_f32 v[26:27], v[26:27], v[58:59]
	v_pk_add_f32 v[52:53], v[16:17], v[64:65]
	v_mul_f32_e32 v58, v20, v20
	v_fmac_f32_e32 v56, v29, v29
	v_fmac_f32_e32 v57, v25, v25
	v_pk_add_f32 v[22:23], v[22:23], v[62:63]
	v_mul_f32_e32 v59, v52, v52
	v_fmac_f32_e32 v58, v21, v21
	v_fmac_f32_e32 v56, v30, v30
	v_fmac_f32_e32 v57, v26, v26
	v_pk_add_f32 v[54:55], v[18:19], v[66:67]
	v_cvt_pk_bf16_f32 v16, v28, v29
	v_fmac_f32_e32 v59, v53, v53
	v_fmac_f32_e32 v58, v22, v22
	v_fmac_f32_e32 v56, v31, v31
	v_fmac_f32_e32 v57, v27, v27
	global_store_dwordx4 v[70:71], v[28:31], off
	v_cvt_pk_bf16_f32 v17, v30, v31
	s_nop 1
	v_mov_b32_e32 v240, v16
	v_mov_b32_e32 v241, v17
	v_lshl_add_u64 v[244:245], v[72:73], 0, v[246:247]
	v_fmac_f32_e32 v59, v54, v54
	v_fmac_f32_e32 v58, v23, v23
	v_add_f32_e32 v16, v56, v57
	v_add_f32_e32 v16, v16, v58
	v_fmac_f32_e32 v59, v55, v55
	v_add_f32_e32 v16, v16, v59
	ds_bpermute_b32 v17, v189, v16
	v_cvt_pk_bf16_f32 v18, v24, v25
	v_cvt_pk_bf16_f32 v19, v26, v27
	v_cvt_pk_bf16_f32 v28, v20, v21
	global_store_dwordx4 v[70:71], v[24:27], off offset:64
	v_mov_b32_e32 v242, v18
	v_mov_b32_e32 v243, v19
	s_nop 1
	v_permlane16_swap_b32 v240, v242
	v_permlane16_swap_b32 v241, v243
	global_store_dwordx4 v[244:245], v[240:243], off
	s_waitcnt lgkmcnt(0)
	v_add_f32_e32 v16, v16, v17
	ds_bpermute_b32 v17, v116, v16
	v_cvt_pk_bf16_f32 v29, v22, v23
	v_lshl_add_u64 v[18:19], s[2:3], 0, v[68:69]
	global_store_dwordx4 v[70:71], v[20:23], off offset:512
	s_nop 1
	v_mov_b32_e32 v240, v28
	v_mov_b32_e32 v241, v29
	v_lshl_add_u64 v[244:245], v[76:77], 0, v[246:247]
	global_store_dwordx4 v[70:71], v[52:55], off offset:576
	v_cvt_pk_bf16_f32 v20, v52, v53
	v_cvt_pk_bf16_f32 v21, v54, v55
	v_mov_b32_e32 v242, v20
	v_mov_b32_e32 v243, v21
	s_nop 1
	v_permlane16_swap_b32 v240, v242
	v_permlane16_swap_b32 v241, v243
	global_store_dwordx4 v[244:245], v[240:243], off
	s_and_saveexec_b64 s[30:31], s[6:7]
	s_cbranch_execz .LBB0_1495
	v_lshlrev_b64 v[18:19], 6, v[50:51]
	v_lshl_add_u64 v[18:19], s[4:5], 0, v[18:19]
	v_lshl_add_u64 v[18:19], s[28:29], 2, v[18:19]
	s_lshl_b32 s12, s55, 2
	v_lshl_add_u64 v[18:19], v[18:19], 0, s[12:13]
	s_waitcnt lgkmcnt(0)
	v_add_f32_e32 v16, v16, v17
	flat_store_dword v[18:19], v16
.LBB0_1495:
	s_or_b64 exec, exec, s[30:31]
	s_waitcnt lgkmcnt(0)
	v_lshlrev_b64 v[16:17], 10, v[48:49]
	v_lshl_add_u64 v[16:17], v[16:17], 0, v[162:163]
	v_lshl_add_u64 v[18:19], v[16:17], 2, s[78:79]
	v_lshlrev_b64 v[16:17], 1, v[16:17]
	v_pk_add_f32 v[14:15], v[14:15], v[46:47]
	v_pk_add_f32 v[12:13], v[12:13], v[44:45]
	v_lshl_add_u64 v[20:21], s[2:3], 0, v[16:17]
	global_store_dwordx4 v[18:19], v[12:15], off
	v_cvt_pk_bf16_f32 v22, v12, v13
	v_cvt_pk_bf16_f32 v23, v14, v15
	s_nop 1
	v_mov_b32_e32 v240, v22
	v_mov_b32_e32 v241, v23
	v_lshl_add_u64 v[244:245], v[20:21], 0, v[246:247]
	v_mul_f32_e32 v20, v12, v12
	v_fmac_f32_e32 v20, v13, v13
	v_pk_add_f32 v[10:11], v[10:11], v[42:43]
	v_pk_add_f32 v[8:9], v[8:9], v[40:41]
	v_fmac_f32_e32 v20, v14, v14
	global_store_dwordx4 v[18:19], v[8:11], off offset:64
	v_or_b32_e32 v12, 32, v16
	v_mov_b32_e32 v13, v17
	v_cvt_pk_bf16_f32 v14, v8, v9
	v_mul_f32_e32 v8, v8, v8
	v_lshl_add_u64 v[12:13], s[2:3], 0, v[12:13]
	v_fmac_f32_e32 v8, v9, v9
	v_pk_add_f32 v[6:7], v[6:7], v[38:39]
	v_pk_add_f32 v[4:5], v[4:5], v[36:37]
	v_fmac_f32_e32 v20, v15, v15
	v_cvt_pk_bf16_f32 v15, v10, v11
	v_mov_b32_e32 v242, v14
	v_mov_b32_e32 v243, v15
	s_nop 1
	v_permlane16_swap_b32 v240, v242
	v_permlane16_swap_b32 v241, v243
	global_store_dwordx4 v[244:245], v[240:243], off
	v_fmac_f32_e32 v8, v10, v10
	global_store_dwordx4 v[18:19], v[4:7], off offset:512
	v_cvt_pk_bf16_f32 v10, v4, v5
	v_fmac_f32_e32 v8, v11, v11
	v_add_f32_e32 v11, v20, v8
	v_mul_f32_e32 v4, v4, v4
	v_fmac_f32_e32 v4, v5, v5
	v_fmac_f32_e32 v4, v6, v6
	v_fmac_f32_e32 v4, v7, v7
	v_add_f32_e32 v11, v11, v4
	v_pk_add_f32 v[4:5], v[2:3], v[34:35]
	v_pk_add_f32 v[2:3], v[0:1], v[32:33]
	v_or_b32_e32 v8, 0x100, v16
	v_mul_f32_e32 v0, v2, v2
	v_fmac_f32_e32 v0, v3, v3
	v_fmac_f32_e32 v0, v4, v4
	v_fmac_f32_e32 v0, v5, v5
	v_add_f32_e32 v0, v11, v0
	ds_bpermute_b32 v1, v189, v0
	v_mov_b32_e32 v9, v17
	v_or_b32_e32 v16, 0x120, v16
	v_lshl_add_u64 v[8:9], s[2:3], 0, v[8:9]
	v_cvt_pk_bf16_f32 v11, v6, v7
	s_waitcnt lgkmcnt(0)
	v_add_f32_e32 v0, v0, v1
	ds_bpermute_b32 v1, v116, v0
	v_lshl_add_u64 v[6:7], s[2:3], 0, v[16:17]
	s_nop 1
	v_mov_b32_e32 v240, v10
	v_mov_b32_e32 v241, v11
	v_lshl_add_u64 v[244:245], v[8:9], 0, v[246:247]
	global_store_dwordx4 v[18:19], v[2:5], off offset:576
	s_nop 1
	v_cvt_pk_bf16_f32 v2, v2, v3
	v_cvt_pk_bf16_f32 v3, v4, v5
	v_mov_b32_e32 v242, v2
	v_mov_b32_e32 v243, v3
	s_nop 1
	v_permlane16_swap_b32 v240, v242
	v_permlane16_swap_b32 v241, v243
	global_store_dwordx4 v[244:245], v[240:243], off
	s_and_saveexec_b64 s[30:31], s[6:7]
	s_cbranch_execz .LBB0_1472
	v_lshlrev_b64 v[2:3], 6, v[48:49]
	v_lshl_add_u64 v[2:3], s[4:5], 0, v[2:3]
	v_lshl_add_u64 v[2:3], s[28:29], 2, v[2:3]
	s_lshl_b32 s12, s55, 2
	v_lshl_add_u64 v[2:3], v[2:3], 0, s[12:13]
	s_waitcnt lgkmcnt(0)
	v_add_f32_e32 v0, v0, v1
	flat_store_dword v[2:3], v0
	s_branch .LBB0_1472

.LBB0_1642:
	ds_read_b128 v[128:131], v170
	ds_read_b128 v[132:135], v171
	ds_read_b128 v[136:139], v172
	ds_read_b128 v[140:143], v173
	s_add_u32 s28, s26, 0xfff50080
	s_addc_u32 s29, s27, -1
	s_cmp_eq_u32 s65, 40
	s_cselect_b32 s31, s11, s29
	s_cselect_b32 s30, s10, s28
	s_cselect_b32 s29, s13, s64
	s_cselect_b32 s28, s12, s25
	s_mov_b32 m0, s59
	v_lshl_add_u64 v[214:215], s[26:27], 0, v[156:157]
	ds_read_b128 v[162:165], v151
	ds_read_b128 v[166:169], v151 offset:1024
	ds_read_b128 v[190:193], v151 offset:2048
	ds_read_b128 v[194:197], v151 offset:3072
	ds_read_b128 v[198:201], v151 offset:4096
	ds_read_b128 v[202:205], v151 offset:5120
	ds_read_b128 v[206:209], v151 offset:6144
	ds_read_b128 v[210:213], v151 offset:7168
	global_load_lds_dwordx4 v[214:215], off
	v_lshl_add_u64 v[214:215], s[26:27], 0, v[154:155]
	s_mov_b32 m0, s60
	s_nop 0
	global_load_lds_dwordx4 v[214:215], off
	s_waitcnt lgkmcnt(8)
	s_barrier
	s_waitcnt lgkmcnt(0)
	s_setprio 1
	s_waitcnt lgkmcnt(0)
	v_mfma_f32_16x16x32_bf16 v[124:127], v[128:131], v[162:165], v[124:127]
	v_mfma_f32_16x16x32_bf16 v[120:123], v[136:139], v[162:165], v[120:123]
	v_mfma_f32_16x16x32_bf16 v[108:111], v[128:131], v[190:193], v[108:111]
	v_mfma_f32_16x16x32_bf16 v[104:107], v[136:139], v[190:193], v[104:107]
	v_mfma_f32_16x16x32_bf16 v[92:95], v[128:131], v[198:201], v[92:95]
	v_mfma_f32_16x16x32_bf16 v[88:91], v[136:139], v[198:201], v[88:91]
	v_mfma_f32_16x16x32_bf16 v[76:79], v[128:131], v[206:209], v[76:79]
	v_mfma_f32_16x16x32_bf16 v[72:75], v[136:139], v[206:209], v[72:75]
	v_mfma_f32_16x16x32_bf16 v[124:127], v[132:135], v[166:169], v[124:127]
	v_mfma_f32_16x16x32_bf16 v[120:123], v[140:143], v[166:169], v[120:123]
	v_mfma_f32_16x16x32_bf16 v[108:111], v[132:135], v[194:197], v[108:111]
	v_mfma_f32_16x16x32_bf16 v[104:107], v[140:143], v[194:197], v[104:107]
	v_mfma_f32_16x16x32_bf16 v[92:95], v[132:135], v[202:205], v[92:95]
	v_mfma_f32_16x16x32_bf16 v[88:91], v[140:143], v[202:205], v[88:91]
	v_mfma_f32_16x16x32_bf16 v[76:79], v[132:135], v[210:213], v[76:79]
	v_mfma_f32_16x16x32_bf16 v[72:75], v[140:143], v[210:213], v[72:75]
	s_setprio 0
	s_barrier
	s_mov_b32 m0, s42
	v_lshl_add_u64 v[230:231], s[28:29], 0, v[144:145]
	ds_read_b128 v[214:217], v174
	ds_read_b128 v[218:221], v175
	ds_read_b128 v[222:225], v177
	ds_read_b128 v[226:229], v178
	global_load_lds_dwordx4 v[230:231], off
	v_lshl_add_u64 v[232:233], s[28:29], 0, v[146:147]
	s_mov_b32 m0, s43
	s_nop 0
	global_load_lds_dwordx4 v[232:233], off
	s_barrier
	s_waitcnt lgkmcnt(0)
	s_setprio 1
	s_waitcnt lgkmcnt(0)
	v_mfma_f32_16x16x32_bf16 v[116:119], v[214:217], v[162:165], v[116:119]
	v_mfma_f32_16x16x32_bf16 v[112:115], v[222:225], v[162:165], v[112:115]
	v_mfma_f32_16x16x32_bf16 v[100:103], v[214:217], v[190:193], v[100:103]
	v_mfma_f32_16x16x32_bf16 v[96:99], v[222:225], v[190:193], v[96:99]
	v_mfma_f32_16x16x32_bf16 v[84:87], v[214:217], v[198:201], v[84:87]
	v_mfma_f32_16x16x32_bf16 v[80:83], v[222:225], v[198:201], v[80:83]
	v_mfma_f32_16x16x32_bf16 v[68:71], v[214:217], v[206:209], v[68:71]
	v_mfma_f32_16x16x32_bf16 v[64:67], v[222:225], v[206:209], v[64:67]
	v_mfma_f32_16x16x32_bf16 v[116:119], v[218:221], v[166:169], v[116:119]
	v_mfma_f32_16x16x32_bf16 v[112:115], v[226:229], v[166:169], v[112:115]
	v_mfma_f32_16x16x32_bf16 v[100:103], v[218:221], v[194:197], v[100:103]
	v_mfma_f32_16x16x32_bf16 v[96:99], v[226:229], v[194:197], v[96:99]
	v_mfma_f32_16x16x32_bf16 v[84:87], v[218:221], v[202:205], v[84:87]
	v_mfma_f32_16x16x32_bf16 v[80:83], v[226:229], v[202:205], v[80:83]
	v_mfma_f32_16x16x32_bf16 v[68:71], v[218:221], v[210:213], v[68:71]
	v_mfma_f32_16x16x32_bf16 v[64:67], v[226:229], v[210:213], v[64:67]
	s_setprio 0
	s_mov_b32 m0, s41
	v_lshl_add_u64 v[234:235], s[30:31], 0, v[144:145]
	s_barrier
	ds_read_b128 v[162:165], v151 offset:16384
	ds_read_b128 v[166:169], v151 offset:17408
	ds_read_b128 v[190:193], v151 offset:18432
	ds_read_b128 v[194:197], v151 offset:19456
	ds_read_b128 v[198:201], v151 offset:20480
	ds_read_b128 v[202:205], v151 offset:21504
	ds_read_b128 v[206:209], v151 offset:22528
	ds_read_b128 v[210:213], v151 offset:23552
	global_load_lds_dwordx4 v[234:235], off
	v_lshl_add_u64 v[236:237], s[30:31], 0, v[146:147]
	s_mov_b32 m0, s44
	s_nop 0
	global_load_lds_dwordx4 v[236:237], off
	s_barrier
	s_waitcnt lgkmcnt(0)
	s_setprio 1
	s_waitcnt lgkmcnt(0)
	v_mfma_f32_16x16x32_bf16 v[60:63], v[128:131], v[162:165], v[60:63]
	v_mfma_f32_16x16x32_bf16 v[56:59], v[136:139], v[162:165], v[56:59]
	v_mfma_f32_16x16x32_bf16 v[44:47], v[128:131], v[190:193], v[44:47]
	v_mfma_f32_16x16x32_bf16 v[40:43], v[136:139], v[190:193], v[40:43]
	v_mfma_f32_16x16x32_bf16 v[28:31], v[128:131], v[198:201], v[28:31]
	v_mfma_f32_16x16x32_bf16 v[24:27], v[136:139], v[198:201], v[24:27]
	v_mfma_f32_16x16x32_bf16 v[12:15], v[128:131], v[206:209], v[12:15]
	v_mfma_f32_16x16x32_bf16 v[8:11], v[136:139], v[206:209], v[8:11]
	v_mfma_f32_16x16x32_bf16 v[60:63], v[132:135], v[166:169], v[60:63]
	v_mfma_f32_16x16x32_bf16 v[56:59], v[140:143], v[166:169], v[56:59]
	v_mfma_f32_16x16x32_bf16 v[44:47], v[132:135], v[194:197], v[44:47]
	v_mfma_f32_16x16x32_bf16 v[40:43], v[140:143], v[194:197], v[40:43]
	v_mfma_f32_16x16x32_bf16 v[28:31], v[132:135], v[202:205], v[28:31]
	v_mfma_f32_16x16x32_bf16 v[24:27], v[140:143], v[202:205], v[24:27]
	v_mfma_f32_16x16x32_bf16 v[12:15], v[132:135], v[210:213], v[12:15]
	v_mfma_f32_16x16x32_bf16 v[8:11], v[140:143], v[210:213], v[8:11]
	s_setprio 0
	s_barrier
	s_add_u32 s66, s28, 0xb0000
	s_addc_u32 s67, s29, 0
	s_mov_b32 m0, s45
	v_lshl_add_u64 v[128:129], s[66:67], 0, v[144:145]
	global_load_lds_dwordx4 v[128:129], off
	v_lshl_add_u64 v[128:129], s[66:67], 0, v[146:147]
	s_mov_b32 m0, s46
	s_nop 0
	global_load_lds_dwordx4 v[128:129], off
	s_waitcnt vmcnt(6)
	s_barrier
	s_setprio 1
	v_mfma_f32_16x16x32_bf16 v[52:55], v[214:217], v[162:165], v[52:55]
	v_mfma_f32_16x16x32_bf16 v[48:51], v[222:225], v[162:165], v[48:51]
	v_mfma_f32_16x16x32_bf16 v[36:39], v[214:217], v[190:193], v[36:39]
	v_mfma_f32_16x16x32_bf16 v[32:35], v[222:225], v[190:193], v[32:35]
	v_mfma_f32_16x16x32_bf16 v[20:23], v[214:217], v[198:201], v[20:23]
	v_mfma_f32_16x16x32_bf16 v[16:19], v[222:225], v[198:201], v[16:19]
	v_mfma_f32_16x16x32_bf16 v[4:7], v[214:217], v[206:209], v[4:7]
	v_mfma_f32_16x16x32_bf16 v[0:3], v[222:225], v[206:209], v[0:3]
	v_mfma_f32_16x16x32_bf16 v[52:55], v[218:221], v[166:169], v[52:55]
	v_mfma_f32_16x16x32_bf16 v[48:51], v[226:229], v[166:169], v[48:51]
	v_mfma_f32_16x16x32_bf16 v[36:39], v[218:221], v[194:197], v[36:39]
	v_mfma_f32_16x16x32_bf16 v[32:35], v[226:229], v[194:197], v[32:35]
	v_mfma_f32_16x16x32_bf16 v[20:23], v[218:221], v[202:205], v[20:23]
	v_mfma_f32_16x16x32_bf16 v[16:19], v[226:229], v[202:205], v[16:19]
	v_mfma_f32_16x16x32_bf16 v[4:7], v[218:221], v[210:213], v[4:7]
	v_mfma_f32_16x16x32_bf16 v[0:3], v[226:229], v[210:213], v[0:3]
	s_setprio 0
	s_barrier
	ds_read_b128 v[128:131], v180
	ds_read_b128 v[132:135], v181
	ds_read_b128 v[136:139], v182
	ds_read_b128 v[140:143], v183
	s_add_u32 s30, s30, 0xb0000
	s_addc_u32 s31, s31, 0
	s_mov_b32 m0, s47
	v_lshl_add_u64 v[214:215], s[30:31], 0, v[144:145]
	ds_read_b128 v[162:165], v151 offset:32768
	ds_read_b128 v[166:169], v151 offset:33792
	ds_read_b128 v[190:193], v151 offset:34816
	ds_read_b128 v[194:197], v151 offset:35840
	ds_read_b128 v[198:201], v151 offset:36864
	ds_read_b128 v[202:205], v151 offset:37888
	ds_read_b128 v[206:209], v151 offset:38912
	ds_read_b128 v[210:213], v151 offset:39936
	global_load_lds_dwordx4 v[214:215], off
	v_lshl_add_u64 v[214:215], s[30:31], 0, v[146:147]
	s_mov_b32 m0, s48
	s_nop 0
	global_load_lds_dwordx4 v[214:215], off
	s_waitcnt lgkmcnt(8)
	s_barrier
	s_waitcnt lgkmcnt(0)
	s_setprio 1
	s_waitcnt lgkmcnt(0)
	v_mfma_f32_16x16x32_bf16 v[124:127], v[128:131], v[162:165], v[124:127]
	v_mfma_f32_16x16x32_bf16 v[120:123], v[136:139], v[162:165], v[120:123]
	v_mfma_f32_16x16x32_bf16 v[108:111], v[128:131], v[190:193], v[108:111]
	v_mfma_f32_16x16x32_bf16 v[104:107], v[136:139], v[190:193], v[104:107]
	v_mfma_f32_16x16x32_bf16 v[92:95], v[128:131], v[198:201], v[92:95]
	v_mfma_f32_16x16x32_bf16 v[88:91], v[136:139], v[198:201], v[88:91]
	v_mfma_f32_16x16x32_bf16 v[76:79], v[128:131], v[206:209], v[76:79]
	v_mfma_f32_16x16x32_bf16 v[72:75], v[136:139], v[206:209], v[72:75]
	v_mfma_f32_16x16x32_bf16 v[124:127], v[132:135], v[166:169], v[124:127]
	v_mfma_f32_16x16x32_bf16 v[120:123], v[140:143], v[166:169], v[120:123]
	v_mfma_f32_16x16x32_bf16 v[108:111], v[132:135], v[194:197], v[108:111]
	v_mfma_f32_16x16x32_bf16 v[104:107], v[140:143], v[194:197], v[104:107]
	v_mfma_f32_16x16x32_bf16 v[92:95], v[132:135], v[202:205], v[92:95]
	v_mfma_f32_16x16x32_bf16 v[88:91], v[140:143], v[202:205], v[88:91]
	v_mfma_f32_16x16x32_bf16 v[76:79], v[132:135], v[210:213], v[76:79]
	v_mfma_f32_16x16x32_bf16 v[72:75], v[140:143], v[210:213], v[72:75]
	s_setprio 0
	s_barrier
	s_mov_b32 m0, s52
	v_lshl_add_u64 v[230:231], v[230:231], 0, s[14:15]
	ds_read_b128 v[214:217], v184
	ds_read_b128 v[218:221], v185
	ds_read_b128 v[222:225], v186
	ds_read_b128 v[226:229], v187
	global_load_lds_dwordx4 v[230:231], off
	v_lshl_add_u64 v[230:231], v[232:233], 0, s[14:15]
	s_mov_b32 m0, s53
	s_nop 0
	global_load_lds_dwordx4 v[230:231], off
	s_barrier
	s_waitcnt lgkmcnt(0)
	s_setprio 1
	s_waitcnt lgkmcnt(0)
	v_mfma_f32_16x16x32_bf16 v[116:119], v[214:217], v[162:165], v[116:119]
	v_mfma_f32_16x16x32_bf16 v[112:115], v[222:225], v[162:165], v[112:115]
	v_mfma_f32_16x16x32_bf16 v[100:103], v[214:217], v[190:193], v[100:103]
	v_mfma_f32_16x16x32_bf16 v[96:99], v[222:225], v[190:193], v[96:99]
	v_mfma_f32_16x16x32_bf16 v[84:87], v[214:217], v[198:201], v[84:87]
	v_mfma_f32_16x16x32_bf16 v[80:83], v[222:225], v[198:201], v[80:83]
	v_mfma_f32_16x16x32_bf16 v[68:71], v[214:217], v[206:209], v[68:71]
	v_mfma_f32_16x16x32_bf16 v[64:67], v[222:225], v[206:209], v[64:67]
	v_mfma_f32_16x16x32_bf16 v[116:119], v[218:221], v[166:169], v[116:119]
	v_mfma_f32_16x16x32_bf16 v[112:115], v[226:229], v[166:169], v[112:115]
	v_mfma_f32_16x16x32_bf16 v[100:103], v[218:221], v[194:197], v[100:103]
	v_mfma_f32_16x16x32_bf16 v[96:99], v[226:229], v[194:197], v[96:99]
	v_mfma_f32_16x16x32_bf16 v[84:87], v[218:221], v[202:205], v[84:87]
	v_mfma_f32_16x16x32_bf16 v[80:83], v[226:229], v[202:205], v[80:83]
	v_mfma_f32_16x16x32_bf16 v[68:71], v[218:221], v[210:213], v[68:71]
	v_mfma_f32_16x16x32_bf16 v[64:67], v[226:229], v[210:213], v[64:67]
	s_setprio 0
	s_mov_b32 m0, s54
	v_lshl_add_u64 v[230:231], v[234:235], 0, s[14:15]
	s_barrier
	ds_read_b128 v[162:165], v151 offset:49152
	ds_read_b128 v[166:169], v151 offset:50176
	ds_read_b128 v[190:193], v151 offset:51200
	ds_read_b128 v[194:197], v151 offset:52224
	ds_read_b128 v[198:201], v151 offset:53248
	ds_read_b128 v[202:205], v151 offset:54272
	ds_read_b128 v[206:209], v151 offset:55296
	ds_read_b128 v[210:213], v151 offset:56320
	global_load_lds_dwordx4 v[230:231], off
	v_lshl_add_u64 v[230:231], v[236:237], 0, s[14:15]
	s_mov_b32 m0, s55
	s_nop 0
	global_load_lds_dwordx4 v[230:231], off
	s_barrier
	s_waitcnt lgkmcnt(0)
	s_setprio 1
	s_waitcnt lgkmcnt(0)
	v_mfma_f32_16x16x32_bf16 v[60:63], v[128:131], v[162:165], v[60:63]
	v_mfma_f32_16x16x32_bf16 v[56:59], v[136:139], v[162:165], v[56:59]
	v_mfma_f32_16x16x32_bf16 v[44:47], v[128:131], v[190:193], v[44:47]
	v_mfma_f32_16x16x32_bf16 v[40:43], v[136:139], v[190:193], v[40:43]
	v_mfma_f32_16x16x32_bf16 v[28:31], v[128:131], v[198:201], v[28:31]
	v_mfma_f32_16x16x32_bf16 v[24:27], v[136:139], v[198:201], v[24:27]
	v_mfma_f32_16x16x32_bf16 v[12:15], v[128:131], v[206:209], v[12:15]
	v_mfma_f32_16x16x32_bf16 v[8:11], v[136:139], v[206:209], v[8:11]
	v_mfma_f32_16x16x32_bf16 v[60:63], v[132:135], v[166:169], v[60:63]
	v_mfma_f32_16x16x32_bf16 v[56:59], v[140:143], v[166:169], v[56:59]
	v_mfma_f32_16x16x32_bf16 v[44:47], v[132:135], v[194:197], v[44:47]
	v_mfma_f32_16x16x32_bf16 v[40:43], v[140:143], v[194:197], v[40:43]
	v_mfma_f32_16x16x32_bf16 v[28:31], v[132:135], v[202:205], v[28:31]
	v_mfma_f32_16x16x32_bf16 v[24:27], v[140:143], v[202:205], v[24:27]
	v_mfma_f32_16x16x32_bf16 v[12:15], v[132:135], v[210:213], v[12:15]
	v_mfma_f32_16x16x32_bf16 v[8:11], v[140:143], v[210:213], v[8:11]
	s_setprio 0
	s_barrier
	s_add_u32 s28, s28, 0xb0080
	s_addc_u32 s29, s29, 0
	s_mov_b32 m0, s56
	v_lshl_add_u64 v[128:129], s[28:29], 0, v[144:145]
	global_load_lds_dwordx4 v[128:129], off
	v_lshl_add_u64 v[128:129], s[28:29], 0, v[146:147]
	s_mov_b32 m0, s57
	s_nop 0
	global_load_lds_dwordx4 v[128:129], off
	s_waitcnt vmcnt(6)
	s_barrier
	s_setprio 1
	v_mfma_f32_16x16x32_bf16 v[52:55], v[214:217], v[162:165], v[52:55]
	v_mfma_f32_16x16x32_bf16 v[48:51], v[222:225], v[162:165], v[48:51]
	v_mfma_f32_16x16x32_bf16 v[36:39], v[214:217], v[190:193], v[36:39]
	v_mfma_f32_16x16x32_bf16 v[32:35], v[222:225], v[190:193], v[32:35]
	v_mfma_f32_16x16x32_bf16 v[20:23], v[214:217], v[198:201], v[20:23]
	v_mfma_f32_16x16x32_bf16 v[16:19], v[222:225], v[198:201], v[16:19]
	v_mfma_f32_16x16x32_bf16 v[4:7], v[214:217], v[206:209], v[4:7]
	v_mfma_f32_16x16x32_bf16 v[0:3], v[222:225], v[206:209], v[0:3]
	v_mfma_f32_16x16x32_bf16 v[52:55], v[218:221], v[166:169], v[52:55]
	v_mfma_f32_16x16x32_bf16 v[48:51], v[226:229], v[166:169], v[48:51]
	v_mfma_f32_16x16x32_bf16 v[36:39], v[218:221], v[194:197], v[36:39]
	v_mfma_f32_16x16x32_bf16 v[32:35], v[226:229], v[194:197], v[32:35]
	v_mfma_f32_16x16x32_bf16 v[20:23], v[218:221], v[202:205], v[20:23]
	v_mfma_f32_16x16x32_bf16 v[16:19], v[226:229], v[202:205], v[16:19]
	v_mfma_f32_16x16x32_bf16 v[4:7], v[218:221], v[210:213], v[4:7]
	v_mfma_f32_16x16x32_bf16 v[0:3], v[226:229], v[210:213], v[0:3]
	s_setprio 0
	s_add_i32 s65, s65, 2
	s_add_u32 s25, s25, 0x100
	s_addc_u32 s64, s64, 0
	s_add_u32 s26, s26, 0x100
	s_addc_u32 s27, s27, 0
	s_cmp_gt_u32 s65, 41
	s_barrier
	s_cbranch_scc0 .LBB0_1642
	s_ashr_i32 s25, s24, 31
	s_lshl_b64 s[24:25], s[24:25], 8
	s_lshl_b32 s26, s16, 8
	v_lshl_add_u64 v[164:165], s[24:25], 0, v[148:149]
	s_ashr_i32 s27, s26, 31
	v_lshl_add_u64 v[166:167], s[26:27], 2, v[152:153]
	v_lshlrev_b64 v[128:129], 12, v[164:165]
	v_lshl_add_u64 v[128:129], v[166:167], 0, v[128:129]
	global_load_dwordx4 v[190:193], v[128:129], off
	global_load_dwordx4 v[194:197], v[128:129], off offset:64
	global_load_dwordx4 v[198:201], v[128:129], off offset:512
	global_load_dwordx4 v[202:205], v[128:129], off offset:576
	v_or_b32_e32 v168, 16, v164
	v_mov_b32_e32 v169, v165
	v_lshlrev_b64 v[128:129], 12, v[168:169]
	v_lshl_add_u64 v[128:129], v[166:167], 0, v[128:129]
	global_load_dwordx4 v[140:143], v[128:129], off
	global_load_dwordx4 v[136:139], v[128:129], off offset:64
	global_load_dwordx4 v[132:135], v[128:129], off offset:512
	s_nop 0
	global_load_dwordx4 v[128:131], v[128:129], off offset:576
	v_and_b32_e32 v163, 64, v188
	v_xor_b32_e32 v189, 16, v188
	v_add_u32_e32 v207, 64, v163
	v_xor_b32_e32 v206, 32, v188
	v_cmp_lt_i32_e32 vcc, v189, v207
	v_or_b32_e32 v162, s26, v150
	v_mov_b32_e32 v163, s27
	v_cndmask_b32_e32 v189, v188, v189, vcc
	v_cmp_lt_i32_e32 vcc, v206, v207
	s_waitcnt vmcnt(0)
	v_lshlrev_b32_e32 v189, 2, v189
	s_lshl_b32 s24, s16, 2
	v_cndmask_b32_e32 v216, v188, v206, vcc
	v_lshlrev_b64 v[206:207], 10, v[164:165]
	v_lshl_add_u64 v[206:207], v[206:207], 0, v[162:163]
	v_lshl_add_u64 v[208:209], v[206:207], 2, s[78:79]
	v_lshlrev_b64 v[206:207], 1, v[206:207]
	v_lshl_add_u64 v[210:211], s[2:3], 0, v[206:207]
	v_or_b32_e32 v212, 32, v206
	v_mov_b32_e32 v213, v207
	v_or_b32_e32 v214, 0x100, v206
	v_mov_b32_e32 v215, v207
	v_lshl_add_u64 v[212:213], s[2:3], 0, v[212:213]
	v_lshl_add_u64 v[214:215], s[2:3], 0, v[214:215]
	v_or_b32_e32 v206, 0x120, v206
	s_ashr_i32 s25, s24, 31
	s_waitcnt vmcnt(0)
	v_pk_fma_f32 v[126:127], v[126:127], 0.5, v[192:193] op_sel_hi:[1,0,1]
	v_pk_fma_f32 v[124:125], v[124:125], 0.5, v[190:191] op_sel_hi:[1,0,1]
	v_pk_fma_f32 v[120:121], v[120:121], 0.5, v[194:195] op_sel_hi:[1,0,1]
	v_pk_fma_f32 v[122:123], v[122:123], 0.5, v[196:197] op_sel_hi:[1,0,1]
	v_pk_fma_f32 v[116:117], v[116:117], 0.5, v[198:199] op_sel_hi:[1,0,1]
	v_pk_fma_f32 v[190:191], v[112:113], 0.5, v[202:203] op_sel_hi:[1,0,1]
	global_store_dwordx4 v[208:209], v[124:127], off
	v_cvt_pk_bf16_f32 v112, v124, v125
	v_mul_f32_e32 v196, v120, v120
	v_mul_f32_e32 v197, v116, v116
	v_mul_f32_e32 v124, v124, v124
	v_fmac_f32_e32 v124, v125, v125
	v_fmac_f32_e32 v196, v121, v121
	v_pk_fma_f32 v[118:119], v[118:119], 0.5, v[200:201] op_sel_hi:[1,0,1]
	v_mul_f32_e32 v198, v190, v190
	v_fmac_f32_e32 v197, v117, v117
	v_fmac_f32_e32 v124, v126, v126
	v_fmac_f32_e32 v196, v122, v122
	v_pk_fma_f32 v[192:193], v[114:115], 0.5, v[204:205] op_sel_hi:[1,0,1]
	v_fmac_f32_e32 v198, v191, v191
	v_fmac_f32_e32 v197, v118, v118
	v_fmac_f32_e32 v124, v127, v127
	v_fmac_f32_e32 v196, v123, v123
	v_cvt_pk_bf16_f32 v113, v126, v127
	v_bfe_u32 v246, v176, 4, 1
	v_mul_u32_u24_e32 v246, 24, v246
	v_mov_b32_e32 v247, 0
	s_nop 1
	v_mov_b32_e32 v240, v112
	v_mov_b32_e32 v241, v113
	v_lshl_add_u64 v[244:245], v[210:211], 0, v[246:247]
	v_fmac_f32_e32 v198, v192, v192
	v_fmac_f32_e32 v197, v119, v119
	v_add_f32_e32 v112, v124, v196
	v_fmac_f32_e32 v198, v193, v193
	v_add_f32_e32 v112, v112, v197
	v_add_f32_e32 v112, v112, v198
	ds_bpermute_b32 v113, v189, v112
	v_cvt_pk_bf16_f32 v114, v120, v121
	v_cvt_pk_bf16_f32 v115, v122, v123
	v_cvt_pk_bf16_f32 v194, v116, v117
	v_cvt_pk_bf16_f32 v195, v118, v119
	global_store_dwordx4 v[208:209], v[120:123], off offset:64
	v_mov_b32_e32 v242, v114
	v_mov_b32_e32 v243, v115
	s_nop 1
	v_permlane16_swap_b32 v240, v242
	v_permlane16_swap_b32 v241, v243
	global_store_dwordx4 v[244:245], v[240:243], off
	global_store_dwordx4 v[208:209], v[116:119], off offset:512
	s_nop 1
	v_mov_b32_e32 v240, v194
	v_mov_b32_e32 v241, v195
	v_lshl_add_u64 v[244:245], v[214:215], 0, v[246:247]
	global_store_dwordx4 v[208:209], v[190:193], off offset:576
	s_waitcnt lgkmcnt(0)
	v_add_f32_e32 v112, v112, v113
	v_lshlrev_b32_e32 v116, 2, v216
	ds_bpermute_b32 v113, v116, v112
	v_lshl_add_u64 v[114:115], s[2:3], 0, v[206:207]
	v_cvt_pk_bf16_f32 v118, v190, v191
	v_cvt_pk_bf16_f32 v119, v192, v193
	v_mov_b32_e32 v242, v118
	v_mov_b32_e32 v243, v119
	s_nop 1
	v_permlane16_swap_b32 v240, v242
	v_permlane16_swap_b32 v241, v243
	global_store_dwordx4 v[244:245], v[240:243], off
	s_and_saveexec_b64 s[26:27], s[6:7]
	s_cbranch_execz .LBB0_1645
	v_lshlrev_b64 v[114:115], 6, v[164:165]
	v_lshl_add_u64 v[114:115], s[4:5], 0, v[114:115]
	v_lshl_add_u64 v[114:115], s[24:25], 2, v[114:115]
	s_lshl_b32 s16, s49, 2
	v_lshl_add_u64 v[114:115], v[114:115], 0, s[16:17]
	s_waitcnt lgkmcnt(0)
	v_add_f32_e32 v112, v112, v113
	flat_store_dword v[114:115], v112
.LBB0_1645:
	s_or_b64 exec, exec, s[26:27]
	s_waitcnt lgkmcnt(0)
	v_lshlrev_b64 v[112:113], 10, v[168:169]
	v_lshl_add_u64 v[112:113], v[112:113], 0, v[162:163]
	v_pk_fma_f32 v[108:109], v[108:109], 0.5, v[140:141] op_sel_hi:[1,0,1]
	v_lshl_add_u64 v[114:115], v[112:113], 2, s[78:79]
	v_lshlrev_b64 v[112:113], 1, v[112:113]
	v_mul_f32_e32 v117, v108, v108
	v_pk_fma_f32 v[110:111], v[110:111], 0.5, v[142:143] op_sel_hi:[1,0,1]
	v_lshl_add_u64 v[118:119], s[2:3], 0, v[112:113]
	v_fmac_f32_e32 v117, v109, v109
	v_pk_fma_f32 v[106:107], v[106:107], 0.5, v[138:139] op_sel_hi:[1,0,1]
	v_pk_fma_f32 v[104:105], v[104:105], 0.5, v[136:137] op_sel_hi:[1,0,1]
	global_store_dwordx4 v[114:115], v[108:111], off
	v_cvt_pk_bf16_f32 v120, v108, v109
	v_cvt_pk_bf16_f32 v121, v110, v111
	s_nop 1
	v_mov_b32_e32 v240, v120
	v_mov_b32_e32 v241, v121
	v_lshl_add_u64 v[244:245], v[118:119], 0, v[246:247]
	v_fmac_f32_e32 v117, v110, v110
	global_store_dwordx4 v[114:115], v[104:107], off offset:64
	v_or_b32_e32 v108, 32, v112
	v_mov_b32_e32 v109, v113
	v_cvt_pk_bf16_f32 v110, v104, v105
	v_mul_f32_e32 v104, v104, v104
	v_lshl_add_u64 v[108:109], s[2:3], 0, v[108:109]
	v_fmac_f32_e32 v104, v105, v105
	v_pk_fma_f32 v[102:103], v[102:103], 0.5, v[134:135] op_sel_hi:[1,0,1]
	v_pk_fma_f32 v[100:101], v[100:101], 0.5, v[132:133] op_sel_hi:[1,0,1]
	v_fmac_f32_e32 v117, v111, v111
	v_cvt_pk_bf16_f32 v111, v106, v107
	v_mov_b32_e32 v242, v110
	v_mov_b32_e32 v243, v111
	s_nop 1
	v_permlane16_swap_b32 v240, v242
	v_permlane16_swap_b32 v241, v243
	global_store_dwordx4 v[244:245], v[240:243], off
	v_fmac_f32_e32 v104, v106, v106
	global_store_dwordx4 v[114:115], v[100:103], off offset:512
	v_cvt_pk_bf16_f32 v106, v100, v101
	v_fmac_f32_e32 v104, v107, v107
	v_add_f32_e32 v107, v117, v104
	v_mul_f32_e32 v100, v100, v100
	v_fmac_f32_e32 v100, v101, v101
	v_fmac_f32_e32 v100, v102, v102
	v_fmac_f32_e32 v100, v103, v103
	v_add_f32_e32 v107, v107, v100
	v_pk_fma_f32 v[100:101], v[98:99], 0.5, v[130:131] op_sel_hi:[1,0,1]
	v_pk_fma_f32 v[98:99], v[96:97], 0.5, v[128:129] op_sel_hi:[1,0,1]
	v_or_b32_e32 v104, 0x100, v112
	v_mul_f32_e32 v96, v98, v98
	v_fmac_f32_e32 v96, v99, v99
	v_fmac_f32_e32 v96, v100, v100
	v_fmac_f32_e32 v96, v101, v101
	v_add_f32_e32 v96, v107, v96
	ds_bpermute_b32 v97, v189, v96
	v_mov_b32_e32 v105, v113
	v_or_b32_e32 v112, 0x120, v112
	v_lshl_add_u64 v[104:105], s[2:3], 0, v[104:105]
	v_cvt_pk_bf16_f32 v107, v102, v103
	s_waitcnt lgkmcnt(0)
	v_add_f32_e32 v96, v96, v97
	ds_bpermute_b32 v97, v116, v96
	v_lshl_add_u64 v[102:103], s[2:3], 0, v[112:113]
	s_nop 1
	v_mov_b32_e32 v240, v106
	v_mov_b32_e32 v241, v107
	v_lshl_add_u64 v[244:245], v[104:105], 0, v[246:247]
	global_store_dwordx4 v[114:115], v[98:101], off offset:576
	s_nop 1
	v_cvt_pk_bf16_f32 v98, v98, v99
	v_cvt_pk_bf16_f32 v99, v100, v101
	v_mov_b32_e32 v242, v98
	v_mov_b32_e32 v243, v99
	s_nop 1
	v_permlane16_swap_b32 v240, v242
	v_permlane16_swap_b32 v241, v243
	global_store_dwordx4 v[244:245], v[240:243], off
	s_and_saveexec_b64 s[26:27], s[6:7]
	s_cbranch_execz .LBB0_1647
	v_lshlrev_b64 v[98:99], 6, v[168:169]
	v_lshl_add_u64 v[98:99], s[4:5], 0, v[98:99]
	v_lshl_add_u64 v[98:99], s[24:25], 2, v[98:99]
	s_lshl_b32 s16, s49, 2
	v_lshl_add_u64 v[98:99], v[98:99], 0, s[16:17]
	s_waitcnt lgkmcnt(0)
	v_add_f32_e32 v96, v96, v97
	flat_store_dword v[98:99], v96
.LBB0_1647:
	s_or_b64 exec, exec, s[26:27]
	v_or_b32_e32 v114, 32, v164
	v_mov_b32_e32 v115, v165
	s_waitcnt lgkmcnt(0)
	v_lshlrev_b64 v[96:97], 12, v[114:115]
	v_lshl_add_u64 v[96:97], v[166:167], 0, v[96:97]
	global_load_dwordx4 v[118:121], v[96:97], off
	global_load_dwordx4 v[122:125], v[96:97], off offset:64
	global_load_dwordx4 v[126:129], v[96:97], off offset:512
	global_load_dwordx4 v[130:133], v[96:97], off offset:576
	v_or_b32_e32 v112, 48, v164
	v_mov_b32_e32 v113, v165
	v_lshlrev_b64 v[96:97], 12, v[112:113]
	v_lshl_add_u64 v[96:97], v[166:167], 0, v[96:97]
	global_load_dwordx4 v[108:111], v[96:97], off
	global_load_dwordx4 v[104:107], v[96:97], off offset:64
	global_load_dwordx4 v[100:103], v[96:97], off offset:512
	s_nop 0
	global_load_dwordx4 v[96:99], v[96:97], off offset:576
	v_lshlrev_b64 v[134:135], 10, v[114:115]
	v_lshl_add_u64 v[134:135], v[134:135], 0, v[162:163]
	v_lshl_add_u64 v[136:137], v[134:135], 2, s[78:79]
	v_lshlrev_b64 v[134:135], 1, v[134:135]
	v_lshl_add_u64 v[138:139], s[2:3], 0, v[134:135]
	s_waitcnt vmcnt(0)
	v_or_b32_e32 v140, 32, v134
	v_mov_b32_e32 v141, v135
	v_or_b32_e32 v142, 0x100, v134
	v_mov_b32_e32 v143, v135
	v_or_b32_e32 v134, 0x120, v134
	v_lshl_add_u64 v[140:141], s[2:3], 0, v[140:141]
	v_lshl_add_u64 v[142:143], s[2:3], 0, v[142:143]
	s_waitcnt vmcnt(0)
	v_pk_fma_f32 v[92:93], v[92:93], 0.5, v[118:119] op_sel_hi:[1,0,1]
	v_pk_fma_f32 v[88:89], v[88:89], 0.5, v[122:123] op_sel_hi:[1,0,1]
	v_pk_fma_f32 v[84:85], v[84:85], 0.5, v[126:127] op_sel_hi:[1,0,1]
	v_mul_f32_e32 v117, v92, v92
	v_mul_f32_e32 v122, v88, v88
	v_pk_fma_f32 v[94:95], v[94:95], 0.5, v[120:121] op_sel_hi:[1,0,1]
	v_pk_fma_f32 v[90:91], v[90:91], 0.5, v[124:125] op_sel_hi:[1,0,1]
	v_pk_fma_f32 v[118:119], v[80:81], 0.5, v[130:131] op_sel_hi:[1,0,1]
	v_mul_f32_e32 v123, v84, v84
	v_fmac_f32_e32 v117, v93, v93
	v_fmac_f32_e32 v122, v89, v89
	v_pk_fma_f32 v[86:87], v[86:87], 0.5, v[128:129] op_sel_hi:[1,0,1]
	v_mul_f32_e32 v124, v118, v118
	v_fmac_f32_e32 v123, v85, v85
	v_fmac_f32_e32 v117, v94, v94
	v_fmac_f32_e32 v122, v90, v90
	v_pk_fma_f32 v[120:121], v[82:83], 0.5, v[132:133] op_sel_hi:[1,0,1]
	v_cvt_pk_bf16_f32 v80, v92, v93
	v_fmac_f32_e32 v124, v119, v119
	v_fmac_f32_e32 v123, v86, v86
	v_fmac_f32_e32 v117, v95, v95
	v_fmac_f32_e32 v122, v91, v91
	global_store_dwordx4 v[136:137], v[92:95], off
	v_cvt_pk_bf16_f32 v81, v94, v95
	s_nop 1
	v_mov_b32_e32 v240, v80
	v_mov_b32_e32 v241, v81
	v_lshl_add_u64 v[244:245], v[138:139], 0, v[246:247]
	v_fmac_f32_e32 v124, v120, v120
	v_fmac_f32_e32 v123, v87, v87
	v_add_f32_e32 v80, v117, v122
	v_add_f32_e32 v80, v80, v123
	v_fmac_f32_e32 v124, v121, v121
	v_add_f32_e32 v80, v80, v124
	ds_bpermute_b32 v81, v189, v80
	v_cvt_pk_bf16_f32 v82, v88, v89
	v_cvt_pk_bf16_f32 v83, v90, v91
	v_cvt_pk_bf16_f32 v92, v84, v85
	global_store_dwordx4 v[136:137], v[88:91], off offset:64
	v_mov_b32_e32 v242, v82
	v_mov_b32_e32 v243, v83
	s_nop 1
	v_permlane16_swap_b32 v240, v242
	v_permlane16_swap_b32 v241, v243
	global_store_dwordx4 v[244:245], v[240:243], off
	s_waitcnt lgkmcnt(0)
	v_add_f32_e32 v80, v80, v81
	ds_bpermute_b32 v81, v116, v80
	v_cvt_pk_bf16_f32 v93, v86, v87
	v_lshl_add_u64 v[82:83], s[2:3], 0, v[134:135]
	global_store_dwordx4 v[136:137], v[84:87], off offset:512
	s_nop 1
	v_mov_b32_e32 v240, v92
	v_mov_b32_e32 v241, v93
	v_lshl_add_u64 v[244:245], v[142:143], 0, v[246:247]
	global_store_dwordx4 v[136:137], v[118:121], off offset:576
	v_cvt_pk_bf16_f32 v84, v118, v119
	v_cvt_pk_bf16_f32 v85, v120, v121
	v_mov_b32_e32 v242, v84
	v_mov_b32_e32 v243, v85
	s_nop 1
	v_permlane16_swap_b32 v240, v242
	v_permlane16_swap_b32 v241, v243
	global_store_dwordx4 v[244:245], v[240:243], off
	s_and_saveexec_b64 s[26:27], s[6:7]
	s_cbranch_execz .LBB0_1649
	v_lshlrev_b64 v[82:83], 6, v[114:115]
	v_lshl_add_u64 v[82:83], s[4:5], 0, v[82:83]
	v_lshl_add_u64 v[82:83], s[24:25], 2, v[82:83]
	s_lshl_b32 s16, s49, 2
	v_lshl_add_u64 v[82:83], v[82:83], 0, s[16:17]
	s_waitcnt lgkmcnt(0)
	v_add_f32_e32 v80, v80, v81
	flat_store_dword v[82:83], v80
.LBB0_1649:
	s_or_b64 exec, exec, s[26:27]
	s_waitcnt lgkmcnt(0)
	v_lshlrev_b64 v[80:81], 10, v[112:113]
	v_lshl_add_u64 v[80:81], v[80:81], 0, v[162:163]
	v_lshl_add_u64 v[82:83], v[80:81], 2, s[78:79]
	v_lshlrev_b64 v[80:81], 1, v[80:81]
	v_pk_fma_f32 v[78:79], v[78:79], 0.5, v[110:111] op_sel_hi:[1,0,1]
	v_pk_fma_f32 v[76:77], v[76:77], 0.5, v[108:109] op_sel_hi:[1,0,1]
	v_lshl_add_u64 v[84:85], s[2:3], 0, v[80:81]
	global_store_dwordx4 v[82:83], v[76:79], off
	v_cvt_pk_bf16_f32 v86, v76, v77
	v_cvt_pk_bf16_f32 v87, v78, v79
	s_nop 1
	v_mov_b32_e32 v240, v86
	v_mov_b32_e32 v241, v87
	v_lshl_add_u64 v[244:245], v[84:85], 0, v[246:247]
	v_mul_f32_e32 v84, v76, v76
	v_fmac_f32_e32 v84, v77, v77
	v_pk_fma_f32 v[74:75], v[74:75], 0.5, v[106:107] op_sel_hi:[1,0,1]
	v_pk_fma_f32 v[72:73], v[72:73], 0.5, v[104:105] op_sel_hi:[1,0,1]
	v_fmac_f32_e32 v84, v78, v78
	global_store_dwordx4 v[82:83], v[72:75], off offset:64
	v_or_b32_e32 v76, 32, v80
	v_mov_b32_e32 v77, v81
	v_cvt_pk_bf16_f32 v78, v72, v73
	v_mul_f32_e32 v72, v72, v72
	v_lshl_add_u64 v[76:77], s[2:3], 0, v[76:77]
	v_fmac_f32_e32 v72, v73, v73
	v_pk_fma_f32 v[70:71], v[70:71], 0.5, v[102:103] op_sel_hi:[1,0,1]
	v_pk_fma_f32 v[68:69], v[68:69], 0.5, v[100:101] op_sel_hi:[1,0,1]
	v_fmac_f32_e32 v84, v79, v79
	v_cvt_pk_bf16_f32 v79, v74, v75
	v_mov_b32_e32 v242, v78
	v_mov_b32_e32 v243, v79
	s_nop 1
	v_permlane16_swap_b32 v240, v242
	v_permlane16_swap_b32 v241, v243
	global_store_dwordx4 v[244:245], v[240:243], off
	v_fmac_f32_e32 v72, v74, v74
	global_store_dwordx4 v[82:83], v[68:71], off offset:512
	v_cvt_pk_bf16_f32 v74, v68, v69
	v_fmac_f32_e32 v72, v75, v75
	v_add_f32_e32 v75, v84, v72
	v_mul_f32_e32 v68, v68, v68
	v_fmac_f32_e32 v68, v69, v69
	v_fmac_f32_e32 v68, v70, v70
	v_fmac_f32_e32 v68, v71, v71
	v_add_f32_e32 v75, v75, v68
	v_pk_fma_f32 v[68:69], v[66:67], 0.5, v[98:99] op_sel_hi:[1,0,1]
	v_pk_fma_f32 v[66:67], v[64:65], 0.5, v[96:97] op_sel_hi:[1,0,1]
	v_or_b32_e32 v72, 0x100, v80
	v_mul_f32_e32 v64, v66, v66
	v_fmac_f32_e32 v64, v67, v67
	v_fmac_f32_e32 v64, v68, v68
	v_fmac_f32_e32 v64, v69, v69
	v_add_f32_e32 v64, v75, v64
	ds_bpermute_b32 v65, v189, v64
	v_mov_b32_e32 v73, v81
	v_or_b32_e32 v80, 0x120, v80
	v_lshl_add_u64 v[72:73], s[2:3], 0, v[72:73]
	v_cvt_pk_bf16_f32 v75, v70, v71
	s_waitcnt lgkmcnt(0)
	v_add_f32_e32 v64, v64, v65
	ds_bpermute_b32 v65, v116, v64
	v_lshl_add_u64 v[70:71], s[2:3], 0, v[80:81]
	s_nop 1
	v_mov_b32_e32 v240, v74
	v_mov_b32_e32 v241, v75
	v_lshl_add_u64 v[244:245], v[72:73], 0, v[246:247]
	global_store_dwordx4 v[82:83], v[66:69], off offset:576
	s_nop 1
	v_cvt_pk_bf16_f32 v66, v66, v67
	v_cvt_pk_bf16_f32 v67, v68, v69
	v_mov_b32_e32 v242, v66
	v_mov_b32_e32 v243, v67
	s_nop 1
	v_permlane16_swap_b32 v240, v242
	v_permlane16_swap_b32 v241, v243
	global_store_dwordx4 v[244:245], v[240:243], off
	s_and_saveexec_b64 s[26:27], s[6:7]
	s_cbranch_execz .LBB0_1651
	v_lshlrev_b64 v[66:67], 6, v[112:113]
	v_lshl_add_u64 v[66:67], s[4:5], 0, v[66:67]
	v_lshl_add_u64 v[66:67], s[24:25], 2, v[66:67]
	s_lshl_b32 s16, s49, 2
	v_lshl_add_u64 v[66:67], v[66:67], 0, s[16:17]
	s_waitcnt lgkmcnt(0)
	v_add_f32_e32 v64, v64, v65
	flat_store_dword v[66:67], v64
.LBB0_1651:
	s_or_b64 exec, exec, s[26:27]
	v_lshl_add_u64 v[82:83], v[164:165], 0, s[14:15]
	s_waitcnt lgkmcnt(0)
	v_lshlrev_b64 v[64:65], 12, v[82:83]
	v_lshl_add_u64 v[64:65], v[166:167], 0, v[64:65]
	global_load_dwordx4 v[84:87], v[64:65], off
	global_load_dwordx4 v[88:91], v[64:65], off offset:64
	global_load_dwordx4 v[92:95], v[64:65], off offset:512
	global_load_dwordx4 v[96:99], v[64:65], off offset:576
	v_lshl_add_u64 v[80:81], v[164:165], 0, s[18:19]
	v_lshlrev_b64 v[64:65], 12, v[80:81]
	v_lshl_add_u64 v[64:65], v[166:167], 0, v[64:65]
	global_load_dwordx4 v[76:79], v[64:65], off
	global_load_dwordx4 v[72:75], v[64:65], off offset:64
	global_load_dwordx4 v[68:71], v[64:65], off offset:512
	s_nop 0
	global_load_dwordx4 v[64:67], v[64:65], off offset:576
	v_lshlrev_b64 v[100:101], 10, v[82:83]
	v_lshl_add_u64 v[100:101], v[100:101], 0, v[162:163]
	v_lshl_add_u64 v[102:103], v[100:101], 2, s[78:79]
	v_lshlrev_b64 v[100:101], 1, v[100:101]
	v_lshl_add_u64 v[104:105], s[2:3], 0, v[100:101]
	s_waitcnt vmcnt(0)
	v_or_b32_e32 v106, 32, v100
	v_mov_b32_e32 v107, v101
	v_or_b32_e32 v108, 0x100, v100
	v_mov_b32_e32 v109, v101
	v_or_b32_e32 v100, 0x120, v100
	v_lshl_add_u64 v[106:107], s[2:3], 0, v[106:107]
	v_lshl_add_u64 v[108:109], s[2:3], 0, v[108:109]
	s_waitcnt vmcnt(0)
	v_pk_fma_f32 v[60:61], v[60:61], 0.5, v[84:85] op_sel_hi:[1,0,1]
	v_pk_fma_f32 v[56:57], v[56:57], 0.5, v[88:89] op_sel_hi:[1,0,1]
	v_pk_fma_f32 v[52:53], v[52:53], 0.5, v[92:93] op_sel_hi:[1,0,1]
	v_mul_f32_e32 v88, v60, v60
	v_mul_f32_e32 v89, v56, v56
	v_pk_fma_f32 v[62:63], v[62:63], 0.5, v[86:87] op_sel_hi:[1,0,1]
	v_pk_fma_f32 v[58:59], v[58:59], 0.5, v[90:91] op_sel_hi:[1,0,1]
	v_pk_fma_f32 v[84:85], v[48:49], 0.5, v[96:97] op_sel_hi:[1,0,1]
	v_mul_f32_e32 v90, v52, v52
	v_fmac_f32_e32 v88, v61, v61
	v_fmac_f32_e32 v89, v57, v57
	v_pk_fma_f32 v[54:55], v[54:55], 0.5, v[94:95] op_sel_hi:[1,0,1]
	v_mul_f32_e32 v91, v84, v84
	v_fmac_f32_e32 v90, v53, v53
	v_fmac_f32_e32 v88, v62, v62
	v_fmac_f32_e32 v89, v58, v58
	v_pk_fma_f32 v[86:87], v[50:51], 0.5, v[98:99] op_sel_hi:[1,0,1]
	v_cvt_pk_bf16_f32 v48, v60, v61
	v_fmac_f32_e32 v91, v85, v85
	v_fmac_f32_e32 v90, v54, v54
	v_fmac_f32_e32 v88, v63, v63
	v_fmac_f32_e32 v89, v59, v59
	global_store_dwordx4 v[102:103], v[60:63], off
	v_cvt_pk_bf16_f32 v49, v62, v63
	s_nop 1
	v_mov_b32_e32 v240, v48
	v_mov_b32_e32 v241, v49
	v_lshl_add_u64 v[244:245], v[104:105], 0, v[246:247]
	v_fmac_f32_e32 v91, v86, v86
	v_fmac_f32_e32 v90, v55, v55
	v_add_f32_e32 v48, v88, v89
	v_add_f32_e32 v48, v48, v90
	v_fmac_f32_e32 v91, v87, v87
	v_add_f32_e32 v48, v48, v91
	ds_bpermute_b32 v49, v189, v48
	v_cvt_pk_bf16_f32 v50, v56, v57
	v_cvt_pk_bf16_f32 v51, v58, v59
	v_cvt_pk_bf16_f32 v60, v52, v53
	global_store_dwordx4 v[102:103], v[56:59], off offset:64
	v_mov_b32_e32 v242, v50
	v_mov_b32_e32 v243, v51
	s_nop 1
	v_permlane16_swap_b32 v240, v242
	v_permlane16_swap_b32 v241, v243
	global_store_dwordx4 v[244:245], v[240:243], off
	s_waitcnt lgkmcnt(0)
	v_add_f32_e32 v48, v48, v49
	ds_bpermute_b32 v49, v116, v48
	v_cvt_pk_bf16_f32 v61, v54, v55
	v_lshl_add_u64 v[50:51], s[2:3], 0, v[100:101]
	global_store_dwordx4 v[102:103], v[52:55], off offset:512
	s_nop 1
	v_mov_b32_e32 v240, v60
	v_mov_b32_e32 v241, v61
	v_lshl_add_u64 v[244:245], v[108:109], 0, v[246:247]
	global_store_dwordx4 v[102:103], v[84:87], off offset:576
	v_cvt_pk_bf16_f32 v52, v84, v85
	v_cvt_pk_bf16_f32 v53, v86, v87
	v_mov_b32_e32 v242, v52
	v_mov_b32_e32 v243, v53
	s_nop 1
	v_permlane16_swap_b32 v240, v242
	v_permlane16_swap_b32 v241, v243
	global_store_dwordx4 v[244:245], v[240:243], off
	s_and_saveexec_b64 s[26:27], s[6:7]
	s_cbranch_execz .LBB0_1653
	v_lshlrev_b64 v[50:51], 6, v[82:83]
	v_lshl_add_u64 v[50:51], s[4:5], 0, v[50:51]
	v_lshl_add_u64 v[50:51], s[24:25], 2, v[50:51]
	s_lshl_b32 s16, s49, 2
	v_lshl_add_u64 v[50:51], v[50:51], 0, s[16:17]
	s_waitcnt lgkmcnt(0)
	v_add_f32_e32 v48, v48, v49
	flat_store_dword v[50:51], v48
.LBB0_1653:
	s_or_b64 exec, exec, s[26:27]
	s_waitcnt lgkmcnt(0)
	v_lshlrev_b64 v[48:49], 10, v[80:81]
	v_lshl_add_u64 v[48:49], v[48:49], 0, v[162:163]
	v_lshl_add_u64 v[50:51], v[48:49], 2, s[78:79]
	v_lshlrev_b64 v[48:49], 1, v[48:49]
	v_pk_fma_f32 v[46:47], v[46:47], 0.5, v[78:79] op_sel_hi:[1,0,1]
	v_pk_fma_f32 v[44:45], v[44:45], 0.5, v[76:77] op_sel_hi:[1,0,1]
	v_lshl_add_u64 v[52:53], s[2:3], 0, v[48:49]
	global_store_dwordx4 v[50:51], v[44:47], off
	v_cvt_pk_bf16_f32 v54, v44, v45
	v_cvt_pk_bf16_f32 v55, v46, v47
	s_nop 1
	v_mov_b32_e32 v240, v54
	v_mov_b32_e32 v241, v55
	v_lshl_add_u64 v[244:245], v[52:53], 0, v[246:247]
	v_mul_f32_e32 v52, v44, v44
	v_fmac_f32_e32 v52, v45, v45
	v_pk_fma_f32 v[42:43], v[42:43], 0.5, v[74:75] op_sel_hi:[1,0,1]
	v_pk_fma_f32 v[40:41], v[40:41], 0.5, v[72:73] op_sel_hi:[1,0,1]
	v_fmac_f32_e32 v52, v46, v46
	global_store_dwordx4 v[50:51], v[40:43], off offset:64
	v_or_b32_e32 v44, 32, v48
	v_mov_b32_e32 v45, v49
	v_cvt_pk_bf16_f32 v46, v40, v41
	v_mul_f32_e32 v40, v40, v40
	v_lshl_add_u64 v[44:45], s[2:3], 0, v[44:45]
	v_fmac_f32_e32 v40, v41, v41
	v_pk_fma_f32 v[38:39], v[38:39], 0.5, v[70:71] op_sel_hi:[1,0,1]
	v_pk_fma_f32 v[36:37], v[36:37], 0.5, v[68:69] op_sel_hi:[1,0,1]
	v_fmac_f32_e32 v52, v47, v47
	v_cvt_pk_bf16_f32 v47, v42, v43
	v_mov_b32_e32 v242, v46
	v_mov_b32_e32 v243, v47
	s_nop 1
	v_permlane16_swap_b32 v240, v242
	v_permlane16_swap_b32 v241, v243
	global_store_dwordx4 v[244:245], v[240:243], off
	v_fmac_f32_e32 v40, v42, v42
	global_store_dwordx4 v[50:51], v[36:39], off offset:512
	v_cvt_pk_bf16_f32 v42, v36, v37
	v_fmac_f32_e32 v40, v43, v43
	v_add_f32_e32 v43, v52, v40
	v_mul_f32_e32 v36, v36, v36
	v_fmac_f32_e32 v36, v37, v37
	v_fmac_f32_e32 v36, v38, v38
	v_fmac_f32_e32 v36, v39, v39
	v_add_f32_e32 v43, v43, v36
	v_pk_fma_f32 v[36:37], v[34:35], 0.5, v[66:67] op_sel_hi:[1,0,1]
	v_pk_fma_f32 v[34:35], v[32:33], 0.5, v[64:65] op_sel_hi:[1,0,1]
	v_or_b32_e32 v40, 0x100, v48
	v_mul_f32_e32 v32, v34, v34
	v_fmac_f32_e32 v32, v35, v35
	v_fmac_f32_e32 v32, v36, v36
	v_fmac_f32_e32 v32, v37, v37
	v_add_f32_e32 v32, v43, v32
	ds_bpermute_b32 v33, v189, v32
	v_mov_b32_e32 v41, v49
	v_or_b32_e32 v48, 0x120, v48
	v_lshl_add_u64 v[40:41], s[2:3], 0, v[40:41]
	v_cvt_pk_bf16_f32 v43, v38, v39
	s_waitcnt lgkmcnt(0)
	v_add_f32_e32 v32, v32, v33
	ds_bpermute_b32 v33, v116, v32
	v_lshl_add_u64 v[38:39], s[2:3], 0, v[48:49]
	s_nop 1
	v_mov_b32_e32 v240, v42
	v_mov_b32_e32 v241, v43
	v_lshl_add_u64 v[244:245], v[40:41], 0, v[246:247]
	global_store_dwordx4 v[50:51], v[34:37], off offset:576
	s_nop 1
	v_cvt_pk_bf16_f32 v34, v34, v35
	v_cvt_pk_bf16_f32 v35, v36, v37
	v_mov_b32_e32 v242, v34
	v_mov_b32_e32 v243, v35
	s_nop 1
	v_permlane16_swap_b32 v240, v242
	v_permlane16_swap_b32 v241, v243
	global_store_dwordx4 v[244:245], v[240:243], off
	s_and_saveexec_b64 s[26:27], s[6:7]
	s_cbranch_execz .LBB0_1655
	v_lshlrev_b64 v[34:35], 6, v[80:81]
	v_lshl_add_u64 v[34:35], s[4:5], 0, v[34:35]
	v_lshl_add_u64 v[34:35], s[24:25], 2, v[34:35]
	s_lshl_b32 s16, s49, 2
	v_lshl_add_u64 v[34:35], v[34:35], 0, s[16:17]
	s_waitcnt lgkmcnt(0)
	v_add_f32_e32 v32, v32, v33
	flat_store_dword v[34:35], v32
.LBB0_1655:
	s_or_b64 exec, exec, s[26:27]
	v_lshl_add_u64 v[50:51], v[164:165], 0, s[20:21]
	s_waitcnt lgkmcnt(0)
	v_lshlrev_b64 v[32:33], 12, v[50:51]
	v_lshl_add_u64 v[32:33], v[166:167], 0, v[32:33]
	global_load_dwordx4 v[52:55], v[32:33], off
	global_load_dwordx4 v[56:59], v[32:33], off offset:64
	global_load_dwordx4 v[60:63], v[32:33], off offset:512
	global_load_dwordx4 v[64:67], v[32:33], off offset:576
	v_lshl_add_u64 v[48:49], v[164:165], 0, s[22:23]
	v_lshlrev_b64 v[32:33], 12, v[48:49]
	v_lshl_add_u64 v[32:33], v[166:167], 0, v[32:33]
	global_load_dwordx4 v[44:47], v[32:33], off
	global_load_dwordx4 v[40:43], v[32:33], off offset:64
	global_load_dwordx4 v[36:39], v[32:33], off offset:512
	s_nop 0
	global_load_dwordx4 v[32:35], v[32:33], off offset:576
	v_lshlrev_b64 v[68:69], 10, v[50:51]
	v_lshl_add_u64 v[68:69], v[68:69], 0, v[162:163]
	v_lshl_add_u64 v[70:71], v[68:69], 2, s[78:79]
	v_lshlrev_b64 v[68:69], 1, v[68:69]
	v_lshl_add_u64 v[72:73], s[2:3], 0, v[68:69]
	s_waitcnt vmcnt(0)
	v_or_b32_e32 v74, 32, v68
	v_mov_b32_e32 v75, v69
	v_or_b32_e32 v76, 0x100, v68
	v_mov_b32_e32 v77, v69
	v_or_b32_e32 v68, 0x120, v68
	v_lshl_add_u64 v[74:75], s[2:3], 0, v[74:75]
	v_lshl_add_u64 v[76:77], s[2:3], 0, v[76:77]
	s_waitcnt vmcnt(0)
	v_pk_fma_f32 v[28:29], v[28:29], 0.5, v[52:53] op_sel_hi:[1,0,1]
	v_pk_fma_f32 v[24:25], v[24:25], 0.5, v[56:57] op_sel_hi:[1,0,1]
	v_pk_fma_f32 v[20:21], v[20:21], 0.5, v[60:61] op_sel_hi:[1,0,1]
	v_mul_f32_e32 v56, v28, v28
	v_mul_f32_e32 v57, v24, v24
	v_pk_fma_f32 v[30:31], v[30:31], 0.5, v[54:55] op_sel_hi:[1,0,1]
	v_pk_fma_f32 v[26:27], v[26:27], 0.5, v[58:59] op_sel_hi:[1,0,1]
	v_pk_fma_f32 v[52:53], v[16:17], 0.5, v[64:65] op_sel_hi:[1,0,1]
	v_mul_f32_e32 v58, v20, v20
	v_fmac_f32_e32 v56, v29, v29
	v_fmac_f32_e32 v57, v25, v25
	v_pk_fma_f32 v[22:23], v[22:23], 0.5, v[62:63] op_sel_hi:[1,0,1]
	v_mul_f32_e32 v59, v52, v52
	v_fmac_f32_e32 v58, v21, v21
	v_fmac_f32_e32 v56, v30, v30
	v_fmac_f32_e32 v57, v26, v26
	v_pk_fma_f32 v[54:55], v[18:19], 0.5, v[66:67] op_sel_hi:[1,0,1]
	v_cvt_pk_bf16_f32 v16, v28, v29
	v_fmac_f32_e32 v59, v53, v53
	v_fmac_f32_e32 v58, v22, v22
	v_fmac_f32_e32 v56, v31, v31
	v_fmac_f32_e32 v57, v27, v27
	global_store_dwordx4 v[70:71], v[28:31], off
	v_cvt_pk_bf16_f32 v17, v30, v31
	s_nop 1
	v_mov_b32_e32 v240, v16
	v_mov_b32_e32 v241, v17
	v_lshl_add_u64 v[244:245], v[72:73], 0, v[246:247]
	v_fmac_f32_e32 v59, v54, v54
	v_fmac_f32_e32 v58, v23, v23
	v_add_f32_e32 v16, v56, v57
	v_add_f32_e32 v16, v16, v58
	v_fmac_f32_e32 v59, v55, v55
	v_add_f32_e32 v16, v16, v59
	ds_bpermute_b32 v17, v189, v16
	v_cvt_pk_bf16_f32 v18, v24, v25
	v_cvt_pk_bf16_f32 v19, v26, v27
	v_cvt_pk_bf16_f32 v28, v20, v21
	global_store_dwordx4 v[70:71], v[24:27], off offset:64
	v_mov_b32_e32 v242, v18
	v_mov_b32_e32 v243, v19
	s_nop 1
	v_permlane16_swap_b32 v240, v242
	v_permlane16_swap_b32 v241, v243
	global_store_dwordx4 v[244:245], v[240:243], off
	s_waitcnt lgkmcnt(0)
	v_add_f32_e32 v16, v16, v17
	ds_bpermute_b32 v17, v116, v16
	v_cvt_pk_bf16_f32 v29, v22, v23
	v_lshl_add_u64 v[18:19], s[2:3], 0, v[68:69]
	global_store_dwordx4 v[70:71], v[20:23], off offset:512
	s_nop 1
	v_mov_b32_e32 v240, v28
	v_mov_b32_e32 v241, v29
	v_lshl_add_u64 v[244:245], v[76:77], 0, v[246:247]
	global_store_dwordx4 v[70:71], v[52:55], off offset:576
	v_cvt_pk_bf16_f32 v20, v52, v53
	v_cvt_pk_bf16_f32 v21, v54, v55
	v_mov_b32_e32 v242, v20
	v_mov_b32_e32 v243, v21
	s_nop 1
	v_permlane16_swap_b32 v240, v242
	v_permlane16_swap_b32 v241, v243
	global_store_dwordx4 v[244:245], v[240:243], off
	s_and_saveexec_b64 s[26:27], s[6:7]
	s_cbranch_execz .LBB0_1657
	v_lshlrev_b64 v[18:19], 6, v[50:51]
	v_lshl_add_u64 v[18:19], s[4:5], 0, v[18:19]
	v_lshl_add_u64 v[18:19], s[24:25], 2, v[18:19]
	s_lshl_b32 s16, s49, 2
	v_lshl_add_u64 v[18:19], v[18:19], 0, s[16:17]
	s_waitcnt lgkmcnt(0)
	v_add_f32_e32 v16, v16, v17
	flat_store_dword v[18:19], v16
.LBB0_1657:
	s_or_b64 exec, exec, s[26:27]
	s_waitcnt lgkmcnt(0)
	v_lshlrev_b64 v[16:17], 10, v[48:49]
	v_lshl_add_u64 v[16:17], v[16:17], 0, v[162:163]
	v_lshl_add_u64 v[18:19], v[16:17], 2, s[78:79]
	v_lshlrev_b64 v[16:17], 1, v[16:17]
	v_pk_fma_f32 v[14:15], v[14:15], 0.5, v[46:47] op_sel_hi:[1,0,1]
	v_pk_fma_f32 v[12:13], v[12:13], 0.5, v[44:45] op_sel_hi:[1,0,1]
	v_lshl_add_u64 v[20:21], s[2:3], 0, v[16:17]
	global_store_dwordx4 v[18:19], v[12:15], off
	v_cvt_pk_bf16_f32 v22, v12, v13
	v_cvt_pk_bf16_f32 v23, v14, v15
	s_nop 1
	v_mov_b32_e32 v240, v22
	v_mov_b32_e32 v241, v23
	v_lshl_add_u64 v[244:245], v[20:21], 0, v[246:247]
	v_mul_f32_e32 v20, v12, v12
	v_fmac_f32_e32 v20, v13, v13
	v_pk_fma_f32 v[10:11], v[10:11], 0.5, v[42:43] op_sel_hi:[1,0,1]
	v_pk_fma_f32 v[8:9], v[8:9], 0.5, v[40:41] op_sel_hi:[1,0,1]
	v_fmac_f32_e32 v20, v14, v14
	global_store_dwordx4 v[18:19], v[8:11], off offset:64
	v_or_b32_e32 v12, 32, v16
	v_mov_b32_e32 v13, v17
	v_cvt_pk_bf16_f32 v14, v8, v9
	v_mul_f32_e32 v8, v8, v8
	v_lshl_add_u64 v[12:13], s[2:3], 0, v[12:13]
	v_fmac_f32_e32 v8, v9, v9
	v_pk_fma_f32 v[6:7], v[6:7], 0.5, v[38:39] op_sel_hi:[1,0,1]
	v_pk_fma_f32 v[4:5], v[4:5], 0.5, v[36:37] op_sel_hi:[1,0,1]
	v_fmac_f32_e32 v20, v15, v15
	v_cvt_pk_bf16_f32 v15, v10, v11
	v_mov_b32_e32 v242, v14
	v_mov_b32_e32 v243, v15
	s_nop 1
	v_permlane16_swap_b32 v240, v242
	v_permlane16_swap_b32 v241, v243
	global_store_dwordx4 v[244:245], v[240:243], off
	v_fmac_f32_e32 v8, v10, v10
	global_store_dwordx4 v[18:19], v[4:7], off offset:512
	v_cvt_pk_bf16_f32 v10, v4, v5
	v_fmac_f32_e32 v8, v11, v11
	v_add_f32_e32 v11, v20, v8
	v_mul_f32_e32 v4, v4, v4
	v_fmac_f32_e32 v4, v5, v5
	v_fmac_f32_e32 v4, v6, v6
	v_fmac_f32_e32 v4, v7, v7
	v_add_f32_e32 v11, v11, v4
	v_pk_fma_f32 v[4:5], v[2:3], 0.5, v[34:35] op_sel_hi:[1,0,1]
	v_pk_fma_f32 v[2:3], v[0:1], 0.5, v[32:33] op_sel_hi:[1,0,1]
	v_or_b32_e32 v8, 0x100, v16
	v_mul_f32_e32 v0, v2, v2
	v_fmac_f32_e32 v0, v3, v3
	v_fmac_f32_e32 v0, v4, v4
	v_fmac_f32_e32 v0, v5, v5
	v_add_f32_e32 v0, v11, v0
	ds_bpermute_b32 v1, v189, v0
	v_mov_b32_e32 v9, v17
	v_or_b32_e32 v16, 0x120, v16
	v_lshl_add_u64 v[8:9], s[2:3], 0, v[8:9]
	v_cvt_pk_bf16_f32 v11, v6, v7
	s_waitcnt lgkmcnt(0)
	v_add_f32_e32 v0, v0, v1
	ds_bpermute_b32 v1, v116, v0
	v_lshl_add_u64 v[6:7], s[2:3], 0, v[16:17]
	s_nop 1
	v_mov_b32_e32 v240, v10
	v_mov_b32_e32 v241, v11
	v_lshl_add_u64 v[244:245], v[8:9], 0, v[246:247]
	global_store_dwordx4 v[18:19], v[2:5], off offset:576
	s_nop 1
	v_cvt_pk_bf16_f32 v2, v2, v3
	v_cvt_pk_bf16_f32 v3, v4, v5
	v_mov_b32_e32 v242, v2
	v_mov_b32_e32 v243, v3
	s_nop 1
	v_permlane16_swap_b32 v240, v242
	v_permlane16_swap_b32 v241, v243
	global_store_dwordx4 v[244:245], v[240:243], off
	s_and_saveexec_b64 s[26:27], s[6:7]
	s_cbranch_execz .LBB0_1630
	v_lshlrev_b64 v[2:3], 6, v[48:49]
	v_lshl_add_u64 v[2:3], s[4:5], 0, v[2:3]
	v_lshl_add_u64 v[2:3], s[24:25], 2, v[2:3]
	s_lshl_b32 s16, s49, 2
	v_lshl_add_u64 v[2:3], v[2:3], 0, s[16:17]
	s_waitcnt lgkmcnt(0)
	v_add_f32_e32 v0, v0, v1
	flat_store_dword v[2:3], v0
	s_branch .LBB0_1630

.LBB0_1812:
	ds_read_b128 v[128:131], v173
	ds_read_b128 v[132:135], v174
	ds_read_b128 v[136:139], v175
	ds_read_b128 v[140:143], v177
	s_add_u32 s30, s28, 0xfff50080
	s_addc_u32 s31, s29, -1
	s_cmp_eq_u32 s67, 40
	s_cselect_b32 s35, s11, s31
	s_cselect_b32 s34, s10, s30
	s_cselect_b32 s31, s13, s66
	s_cselect_b32 s30, s12, s27
	s_mov_b32 m0, s61
	v_lshl_add_u64 v[216:217], s[28:29], 0, v[156:157]
	ds_read_b128 v[162:165], v172
	ds_read_b128 v[166:169], v172 offset:1024
	ds_read_b128 v[192:195], v172 offset:2048
	ds_read_b128 v[196:199], v172 offset:3072
	ds_read_b128 v[200:203], v172 offset:4096
	ds_read_b128 v[204:207], v172 offset:5120
	ds_read_b128 v[208:211], v172 offset:6144
	ds_read_b128 v[212:215], v172 offset:7168
	global_load_lds_dwordx4 v[216:217], off
	v_lshl_add_u64 v[216:217], s[28:29], 0, v[154:155]
	s_mov_b32 m0, s62
	s_nop 0
	global_load_lds_dwordx4 v[216:217], off
	s_waitcnt lgkmcnt(8)
	s_barrier
	s_waitcnt lgkmcnt(0)
	s_setprio 1
	s_waitcnt lgkmcnt(0)
	v_mfma_f32_16x16x32_bf16 v[124:127], v[128:131], v[162:165], v[124:127]
	v_mfma_f32_16x16x32_bf16 v[120:123], v[136:139], v[162:165], v[120:123]
	v_mfma_f32_16x16x32_bf16 v[108:111], v[128:131], v[192:195], v[108:111]
	v_mfma_f32_16x16x32_bf16 v[104:107], v[136:139], v[192:195], v[104:107]
	v_mfma_f32_16x16x32_bf16 v[92:95], v[128:131], v[200:203], v[92:95]
	v_mfma_f32_16x16x32_bf16 v[88:91], v[136:139], v[200:203], v[88:91]
	v_mfma_f32_16x16x32_bf16 v[76:79], v[128:131], v[208:211], v[76:79]
	v_mfma_f32_16x16x32_bf16 v[72:75], v[136:139], v[208:211], v[72:75]
	v_mfma_f32_16x16x32_bf16 v[124:127], v[132:135], v[166:169], v[124:127]
	v_mfma_f32_16x16x32_bf16 v[120:123], v[140:143], v[166:169], v[120:123]
	v_mfma_f32_16x16x32_bf16 v[108:111], v[132:135], v[196:199], v[108:111]
	v_mfma_f32_16x16x32_bf16 v[104:107], v[140:143], v[196:199], v[104:107]
	v_mfma_f32_16x16x32_bf16 v[92:95], v[132:135], v[204:207], v[92:95]
	v_mfma_f32_16x16x32_bf16 v[88:91], v[140:143], v[204:207], v[88:91]
	v_mfma_f32_16x16x32_bf16 v[76:79], v[132:135], v[212:215], v[76:79]
	v_mfma_f32_16x16x32_bf16 v[72:75], v[140:143], v[212:215], v[72:75]
	s_setprio 0
	s_barrier
	s_mov_b32 m0, s44
	v_lshl_add_u64 v[232:233], s[30:31], 0, v[144:145]
	ds_read_b128 v[216:219], v178
	ds_read_b128 v[220:223], v180
	ds_read_b128 v[224:227], v181
	ds_read_b128 v[228:231], v182
	global_load_lds_dwordx4 v[232:233], off
	v_lshl_add_u64 v[234:235], s[30:31], 0, v[146:147]
	s_mov_b32 m0, s45
	s_nop 0
	global_load_lds_dwordx4 v[234:235], off
	s_barrier
	s_waitcnt lgkmcnt(0)
	s_setprio 1
	s_waitcnt lgkmcnt(0)
	v_mfma_f32_16x16x32_bf16 v[116:119], v[216:219], v[162:165], v[116:119]
	v_mfma_f32_16x16x32_bf16 v[112:115], v[224:227], v[162:165], v[112:115]
	v_mfma_f32_16x16x32_bf16 v[100:103], v[216:219], v[192:195], v[100:103]
	v_mfma_f32_16x16x32_bf16 v[96:99], v[224:227], v[192:195], v[96:99]
	v_mfma_f32_16x16x32_bf16 v[84:87], v[216:219], v[200:203], v[84:87]
	v_mfma_f32_16x16x32_bf16 v[80:83], v[224:227], v[200:203], v[80:83]
	v_mfma_f32_16x16x32_bf16 v[68:71], v[216:219], v[208:211], v[68:71]
	v_mfma_f32_16x16x32_bf16 v[64:67], v[224:227], v[208:211], v[64:67]
	v_mfma_f32_16x16x32_bf16 v[116:119], v[220:223], v[166:169], v[116:119]
	v_mfma_f32_16x16x32_bf16 v[112:115], v[228:231], v[166:169], v[112:115]
	v_mfma_f32_16x16x32_bf16 v[100:103], v[220:223], v[196:199], v[100:103]
	v_mfma_f32_16x16x32_bf16 v[96:99], v[228:231], v[196:199], v[96:99]
	v_mfma_f32_16x16x32_bf16 v[84:87], v[220:223], v[204:207], v[84:87]
	v_mfma_f32_16x16x32_bf16 v[80:83], v[228:231], v[204:207], v[80:83]
	v_mfma_f32_16x16x32_bf16 v[68:71], v[220:223], v[212:215], v[68:71]
	v_mfma_f32_16x16x32_bf16 v[64:67], v[228:231], v[212:215], v[64:67]
	s_setprio 0
	s_mov_b32 m0, s43
	v_lshl_add_u64 v[236:237], s[34:35], 0, v[144:145]
	s_barrier
	ds_read_b128 v[162:165], v172 offset:16384
	ds_read_b128 v[166:169], v172 offset:17408
	ds_read_b128 v[192:195], v172 offset:18432
	ds_read_b128 v[196:199], v172 offset:19456
	ds_read_b128 v[200:203], v172 offset:20480
	ds_read_b128 v[204:207], v172 offset:21504
	ds_read_b128 v[208:211], v172 offset:22528
	ds_read_b128 v[212:215], v172 offset:23552
	global_load_lds_dwordx4 v[236:237], off
	v_lshl_add_u64 v[238:239], s[34:35], 0, v[146:147]
	s_mov_b32 m0, s46
	s_nop 0
	global_load_lds_dwordx4 v[238:239], off
	s_barrier
	s_waitcnt lgkmcnt(0)
	s_setprio 1
	s_waitcnt lgkmcnt(0)
	v_mfma_f32_16x16x32_bf16 v[60:63], v[128:131], v[162:165], v[60:63]
	v_mfma_f32_16x16x32_bf16 v[56:59], v[136:139], v[162:165], v[56:59]
	v_mfma_f32_16x16x32_bf16 v[44:47], v[128:131], v[192:195], v[44:47]
	v_mfma_f32_16x16x32_bf16 v[40:43], v[136:139], v[192:195], v[40:43]
	v_mfma_f32_16x16x32_bf16 v[28:31], v[128:131], v[200:203], v[28:31]
	v_mfma_f32_16x16x32_bf16 v[24:27], v[136:139], v[200:203], v[24:27]
	v_mfma_f32_16x16x32_bf16 v[12:15], v[128:131], v[208:211], v[12:15]
	v_mfma_f32_16x16x32_bf16 v[8:11], v[136:139], v[208:211], v[8:11]
	v_mfma_f32_16x16x32_bf16 v[60:63], v[132:135], v[166:169], v[60:63]
	v_mfma_f32_16x16x32_bf16 v[56:59], v[140:143], v[166:169], v[56:59]
	v_mfma_f32_16x16x32_bf16 v[44:47], v[132:135], v[196:199], v[44:47]
	v_mfma_f32_16x16x32_bf16 v[40:43], v[140:143], v[196:199], v[40:43]
	v_mfma_f32_16x16x32_bf16 v[28:31], v[132:135], v[204:207], v[28:31]
	v_mfma_f32_16x16x32_bf16 v[24:27], v[140:143], v[204:207], v[24:27]
	v_mfma_f32_16x16x32_bf16 v[12:15], v[132:135], v[212:215], v[12:15]
	v_mfma_f32_16x16x32_bf16 v[8:11], v[140:143], v[212:215], v[8:11]
	s_setprio 0
	s_barrier
	s_add_u32 s68, s30, 0xb0000
	s_addc_u32 s69, s31, 0
	s_mov_b32 m0, s47
	v_lshl_add_u64 v[128:129], s[68:69], 0, v[144:145]
	global_load_lds_dwordx4 v[128:129], off
	v_lshl_add_u64 v[128:129], s[68:69], 0, v[146:147]
	s_mov_b32 m0, s48
	s_nop 0
	global_load_lds_dwordx4 v[128:129], off
	s_waitcnt vmcnt(6)
	s_barrier
	s_setprio 1
	v_mfma_f32_16x16x32_bf16 v[52:55], v[216:219], v[162:165], v[52:55]
	v_mfma_f32_16x16x32_bf16 v[48:51], v[224:227], v[162:165], v[48:51]
	v_mfma_f32_16x16x32_bf16 v[36:39], v[216:219], v[192:195], v[36:39]
	v_mfma_f32_16x16x32_bf16 v[32:35], v[224:227], v[192:195], v[32:35]
	v_mfma_f32_16x16x32_bf16 v[20:23], v[216:219], v[200:203], v[20:23]
	v_mfma_f32_16x16x32_bf16 v[16:19], v[224:227], v[200:203], v[16:19]
	v_mfma_f32_16x16x32_bf16 v[4:7], v[216:219], v[208:211], v[4:7]
	v_mfma_f32_16x16x32_bf16 v[0:3], v[224:227], v[208:211], v[0:3]
	v_mfma_f32_16x16x32_bf16 v[52:55], v[220:223], v[166:169], v[52:55]
	v_mfma_f32_16x16x32_bf16 v[48:51], v[228:231], v[166:169], v[48:51]
	v_mfma_f32_16x16x32_bf16 v[36:39], v[220:223], v[196:199], v[36:39]
	v_mfma_f32_16x16x32_bf16 v[32:35], v[228:231], v[196:199], v[32:35]
	v_mfma_f32_16x16x32_bf16 v[20:23], v[220:223], v[204:207], v[20:23]
	v_mfma_f32_16x16x32_bf16 v[16:19], v[228:231], v[204:207], v[16:19]
	v_mfma_f32_16x16x32_bf16 v[4:7], v[220:223], v[212:215], v[4:7]
	v_mfma_f32_16x16x32_bf16 v[0:3], v[228:231], v[212:215], v[0:3]
	s_setprio 0
	s_barrier
	ds_read_b128 v[128:131], v183
	ds_read_b128 v[132:135], v184
	ds_read_b128 v[136:139], v185
	ds_read_b128 v[140:143], v186
	s_add_u32 s34, s34, 0xb0000
	s_addc_u32 s35, s35, 0
	s_mov_b32 m0, s49
	v_lshl_add_u64 v[216:217], s[34:35], 0, v[144:145]
	ds_read_b128 v[162:165], v172 offset:32768
	ds_read_b128 v[166:169], v172 offset:33792
	ds_read_b128 v[192:195], v172 offset:34816
	ds_read_b128 v[196:199], v172 offset:35840
	ds_read_b128 v[200:203], v172 offset:36864
	ds_read_b128 v[204:207], v172 offset:37888
	ds_read_b128 v[208:211], v172 offset:38912
	ds_read_b128 v[212:215], v172 offset:39936
	global_load_lds_dwordx4 v[216:217], off
	v_lshl_add_u64 v[216:217], s[34:35], 0, v[146:147]
	s_mov_b32 m0, s52
	s_nop 0
	global_load_lds_dwordx4 v[216:217], off
	s_waitcnt lgkmcnt(8)
	s_barrier
	s_waitcnt lgkmcnt(0)
	s_setprio 1
	s_waitcnt lgkmcnt(0)
	v_mfma_f32_16x16x32_bf16 v[124:127], v[128:131], v[162:165], v[124:127]
	v_mfma_f32_16x16x32_bf16 v[120:123], v[136:139], v[162:165], v[120:123]
	v_mfma_f32_16x16x32_bf16 v[108:111], v[128:131], v[192:195], v[108:111]
	v_mfma_f32_16x16x32_bf16 v[104:107], v[136:139], v[192:195], v[104:107]
	v_mfma_f32_16x16x32_bf16 v[92:95], v[128:131], v[200:203], v[92:95]
	v_mfma_f32_16x16x32_bf16 v[88:91], v[136:139], v[200:203], v[88:91]
	v_mfma_f32_16x16x32_bf16 v[76:79], v[128:131], v[208:211], v[76:79]
	v_mfma_f32_16x16x32_bf16 v[72:75], v[136:139], v[208:211], v[72:75]
	v_mfma_f32_16x16x32_bf16 v[124:127], v[132:135], v[166:169], v[124:127]
	v_mfma_f32_16x16x32_bf16 v[120:123], v[140:143], v[166:169], v[120:123]
	v_mfma_f32_16x16x32_bf16 v[108:111], v[132:135], v[196:199], v[108:111]
	v_mfma_f32_16x16x32_bf16 v[104:107], v[140:143], v[196:199], v[104:107]
	v_mfma_f32_16x16x32_bf16 v[92:95], v[132:135], v[204:207], v[92:95]
	v_mfma_f32_16x16x32_bf16 v[88:91], v[140:143], v[204:207], v[88:91]
	v_mfma_f32_16x16x32_bf16 v[76:79], v[132:135], v[212:215], v[76:79]
	v_mfma_f32_16x16x32_bf16 v[72:75], v[140:143], v[212:215], v[72:75]
	s_setprio 0
	s_barrier
	s_mov_b32 m0, s54
	v_lshl_add_u64 v[232:233], v[232:233], 0, s[16:17]
	ds_read_b128 v[216:219], v187
	ds_read_b128 v[220:223], v188
	ds_read_b128 v[224:227], v189
	ds_read_b128 v[228:231], v190
	global_load_lds_dwordx4 v[232:233], off
	v_lshl_add_u64 v[232:233], v[234:235], 0, s[16:17]
	s_mov_b32 m0, s55
	s_nop 0
	global_load_lds_dwordx4 v[232:233], off
	s_barrier
	s_waitcnt lgkmcnt(0)
	s_setprio 1
	s_waitcnt lgkmcnt(0)
	v_mfma_f32_16x16x32_bf16 v[116:119], v[216:219], v[162:165], v[116:119]
	v_mfma_f32_16x16x32_bf16 v[112:115], v[224:227], v[162:165], v[112:115]
	v_mfma_f32_16x16x32_bf16 v[100:103], v[216:219], v[192:195], v[100:103]
	v_mfma_f32_16x16x32_bf16 v[96:99], v[224:227], v[192:195], v[96:99]
	v_mfma_f32_16x16x32_bf16 v[84:87], v[216:219], v[200:203], v[84:87]
	v_mfma_f32_16x16x32_bf16 v[80:83], v[224:227], v[200:203], v[80:83]
	v_mfma_f32_16x16x32_bf16 v[68:71], v[216:219], v[208:211], v[68:71]
	v_mfma_f32_16x16x32_bf16 v[64:67], v[224:227], v[208:211], v[64:67]
	v_mfma_f32_16x16x32_bf16 v[116:119], v[220:223], v[166:169], v[116:119]
	v_mfma_f32_16x16x32_bf16 v[112:115], v[228:231], v[166:169], v[112:115]
	v_mfma_f32_16x16x32_bf16 v[100:103], v[220:223], v[196:199], v[100:103]
	v_mfma_f32_16x16x32_bf16 v[96:99], v[228:231], v[196:199], v[96:99]
	v_mfma_f32_16x16x32_bf16 v[84:87], v[220:223], v[204:207], v[84:87]
	v_mfma_f32_16x16x32_bf16 v[80:83], v[228:231], v[204:207], v[80:83]
	v_mfma_f32_16x16x32_bf16 v[68:71], v[220:223], v[212:215], v[68:71]
	v_mfma_f32_16x16x32_bf16 v[64:67], v[228:231], v[212:215], v[64:67]
	s_setprio 0
	s_mov_b32 m0, s56
	v_lshl_add_u64 v[232:233], v[236:237], 0, s[16:17]
	s_barrier
	ds_read_b128 v[162:165], v172 offset:49152
	ds_read_b128 v[166:169], v172 offset:50176
	ds_read_b128 v[192:195], v172 offset:51200
	ds_read_b128 v[196:199], v172 offset:52224
	ds_read_b128 v[200:203], v172 offset:53248
	ds_read_b128 v[204:207], v172 offset:54272
	ds_read_b128 v[208:211], v172 offset:55296
	ds_read_b128 v[212:215], v172 offset:56320
	global_load_lds_dwordx4 v[232:233], off
	v_lshl_add_u64 v[232:233], v[238:239], 0, s[16:17]
	s_mov_b32 m0, s57
	s_nop 0
	global_load_lds_dwordx4 v[232:233], off
	s_barrier
	s_waitcnt lgkmcnt(0)
	s_setprio 1
	s_waitcnt lgkmcnt(0)
	v_mfma_f32_16x16x32_bf16 v[60:63], v[128:131], v[162:165], v[60:63]
	v_mfma_f32_16x16x32_bf16 v[56:59], v[136:139], v[162:165], v[56:59]
	v_mfma_f32_16x16x32_bf16 v[44:47], v[128:131], v[192:195], v[44:47]
	v_mfma_f32_16x16x32_bf16 v[40:43], v[136:139], v[192:195], v[40:43]
	v_mfma_f32_16x16x32_bf16 v[28:31], v[128:131], v[200:203], v[28:31]
	v_mfma_f32_16x16x32_bf16 v[24:27], v[136:139], v[200:203], v[24:27]
	v_mfma_f32_16x16x32_bf16 v[12:15], v[128:131], v[208:211], v[12:15]
	v_mfma_f32_16x16x32_bf16 v[8:11], v[136:139], v[208:211], v[8:11]
	v_mfma_f32_16x16x32_bf16 v[60:63], v[132:135], v[166:169], v[60:63]
	v_mfma_f32_16x16x32_bf16 v[56:59], v[140:143], v[166:169], v[56:59]
	v_mfma_f32_16x16x32_bf16 v[44:47], v[132:135], v[196:199], v[44:47]
	v_mfma_f32_16x16x32_bf16 v[40:43], v[140:143], v[196:199], v[40:43]
	v_mfma_f32_16x16x32_bf16 v[28:31], v[132:135], v[204:207], v[28:31]
	v_mfma_f32_16x16x32_bf16 v[24:27], v[140:143], v[204:207], v[24:27]
	v_mfma_f32_16x16x32_bf16 v[12:15], v[132:135], v[212:215], v[12:15]
	v_mfma_f32_16x16x32_bf16 v[8:11], v[140:143], v[212:215], v[8:11]
	s_setprio 0
	s_barrier
	s_add_u32 s30, s30, 0xb0080
	s_addc_u32 s31, s31, 0
	s_mov_b32 m0, s58
	v_lshl_add_u64 v[128:129], s[30:31], 0, v[144:145]
	global_load_lds_dwordx4 v[128:129], off
	v_lshl_add_u64 v[128:129], s[30:31], 0, v[146:147]
	s_mov_b32 m0, s59
	s_nop 0
	global_load_lds_dwordx4 v[128:129], off
	s_waitcnt vmcnt(6)
	s_barrier
	s_setprio 1
	v_mfma_f32_16x16x32_bf16 v[52:55], v[216:219], v[162:165], v[52:55]
	v_mfma_f32_16x16x32_bf16 v[48:51], v[224:227], v[162:165], v[48:51]
	v_mfma_f32_16x16x32_bf16 v[36:39], v[216:219], v[192:195], v[36:39]
	v_mfma_f32_16x16x32_bf16 v[32:35], v[224:227], v[192:195], v[32:35]
	v_mfma_f32_16x16x32_bf16 v[20:23], v[216:219], v[200:203], v[20:23]
	v_mfma_f32_16x16x32_bf16 v[16:19], v[224:227], v[200:203], v[16:19]
	v_mfma_f32_16x16x32_bf16 v[4:7], v[216:219], v[208:211], v[4:7]
	v_mfma_f32_16x16x32_bf16 v[0:3], v[224:227], v[208:211], v[0:3]
	v_mfma_f32_16x16x32_bf16 v[52:55], v[220:223], v[166:169], v[52:55]
	v_mfma_f32_16x16x32_bf16 v[48:51], v[228:231], v[166:169], v[48:51]
	v_mfma_f32_16x16x32_bf16 v[36:39], v[220:223], v[196:199], v[36:39]
	v_mfma_f32_16x16x32_bf16 v[32:35], v[228:231], v[196:199], v[32:35]
	v_mfma_f32_16x16x32_bf16 v[20:23], v[220:223], v[204:207], v[20:23]
	v_mfma_f32_16x16x32_bf16 v[16:19], v[228:231], v[204:207], v[16:19]
	v_mfma_f32_16x16x32_bf16 v[4:7], v[220:223], v[212:215], v[4:7]
	v_mfma_f32_16x16x32_bf16 v[0:3], v[228:231], v[212:215], v[0:3]
	s_setprio 0
	s_add_i32 s67, s67, 2
	s_add_u32 s27, s27, 0x100
	s_addc_u32 s66, s66, 0
	s_add_u32 s28, s28, 0x100
	s_addc_u32 s29, s29, 0
	s_cmp_gt_u32 s67, 41
	s_barrier
	s_cbranch_scc0 .LBB0_1812
	s_ashr_i32 s27, s26, 31
	s_lshl_b64 s[26:27], s[26:27], 8
	s_lshl_b32 s28, s18, 8
	v_lshl_add_u64 v[164:165], s[26:27], 0, v[148:149]
	s_ashr_i32 s29, s28, 31
	v_lshl_add_u64 v[166:167], s[28:29], 2, v[152:153]
	v_lshlrev_b64 v[128:129], 12, v[164:165]
	v_lshl_add_u64 v[128:129], v[166:167], 0, v[128:129]
	global_load_dwordx4 v[194:197], v[128:129], off
	global_load_dwordx4 v[198:201], v[128:129], off offset:64
	global_load_dwordx4 v[202:205], v[128:129], off offset:512
	global_load_dwordx4 v[206:209], v[128:129], off offset:576
	v_or_b32_e32 v168, 16, v164
	v_mov_b32_e32 v169, v165
	v_lshlrev_b64 v[128:129], 12, v[168:169]
	v_lshl_add_u64 v[128:129], v[166:167], 0, v[128:129]
	global_load_dwordx4 v[140:143], v[128:129], off
	global_load_dwordx4 v[136:139], v[128:129], off offset:64
	global_load_dwordx4 v[132:135], v[128:129], off offset:512
	s_nop 0
	global_load_dwordx4 v[128:131], v[128:129], off offset:576
	v_and_b32_e32 v163, 64, v191
	v_xor_b32_e32 v192, 16, v191
	v_add_u32_e32 v210, 64, v163
	v_xor_b32_e32 v193, 32, v191
	v_cmp_lt_i32_e32 vcc, v192, v210
	v_or_b32_e32 v162, s28, v150
	v_mov_b32_e32 v163, s29
	v_cndmask_b32_e32 v192, v191, v192, vcc
	v_cmp_lt_i32_e32 vcc, v193, v210
	v_lshlrev_b64 v[210:211], 10, v[164:165]
	v_lshl_add_u64 v[210:211], v[210:211], 0, v[162:163]
	v_lshl_add_u64 v[212:213], v[210:211], 2, s[78:79]
	s_waitcnt vmcnt(0)
	v_lshlrev_b64 v[210:211], 1, v[210:211]
	v_lshl_add_u64 v[214:215], s[4:5], 0, v[210:211]
	v_lshlrev_b32_e32 v192, 2, v192
	v_or_b32_e32 v216, 32, v210
	v_mov_b32_e32 v217, v211
	v_cndmask_b32_e32 v193, v191, v193, vcc
	v_or_b32_e32 v218, 0x100, v210
	v_mov_b32_e32 v219, v211
	v_lshl_add_u64 v[216:217], s[4:5], 0, v[216:217]
	v_lshl_add_u64 v[218:219], s[4:5], 0, v[218:219]
	s_lshl_b32 s26, s18, 2
	v_or_b32_e32 v210, 0x120, v210
	s_ashr_i32 s27, s26, 31
	s_waitcnt vmcnt(0)
	v_pk_fma_f32 v[126:127], v[126:127], 0.5, v[196:197] op_sel_hi:[1,0,1]
	v_pk_fma_f32 v[124:125], v[124:125], 0.5, v[194:195] op_sel_hi:[1,0,1]
	v_pk_fma_f32 v[120:121], v[120:121], 0.5, v[198:199] op_sel_hi:[1,0,1]
	v_pk_fma_f32 v[122:123], v[122:123], 0.5, v[200:201] op_sel_hi:[1,0,1]
	v_pk_fma_f32 v[116:117], v[116:117], 0.5, v[202:203] op_sel_hi:[1,0,1]
	v_pk_fma_f32 v[194:195], v[112:113], 0.5, v[206:207] op_sel_hi:[1,0,1]
	global_store_dwordx4 v[212:213], v[124:127], off
	v_cvt_pk_bf16_f32 v112, v124, v125
	v_mul_f32_e32 v200, v120, v120
	v_mul_f32_e32 v201, v116, v116
	v_mul_f32_e32 v124, v124, v124
	v_fmac_f32_e32 v124, v125, v125
	v_fmac_f32_e32 v200, v121, v121
	v_pk_fma_f32 v[118:119], v[118:119], 0.5, v[204:205] op_sel_hi:[1,0,1]
	v_mul_f32_e32 v202, v194, v194
	v_fmac_f32_e32 v201, v117, v117
	v_fmac_f32_e32 v124, v126, v126
	v_fmac_f32_e32 v200, v122, v122
	v_pk_fma_f32 v[196:197], v[114:115], 0.5, v[208:209] op_sel_hi:[1,0,1]
	v_fmac_f32_e32 v202, v195, v195
	v_fmac_f32_e32 v201, v118, v118
	v_fmac_f32_e32 v124, v127, v127
	v_fmac_f32_e32 v200, v123, v123
	v_cvt_pk_bf16_f32 v113, v126, v127
	v_bfe_u32 v246, v176, 4, 1
	v_mul_u32_u24_e32 v246, 24, v246
	v_mov_b32_e32 v247, 0
	s_nop 1
	v_mov_b32_e32 v240, v112
	v_mov_b32_e32 v241, v113
	v_lshl_add_u64 v[244:245], v[214:215], 0, v[246:247]
	v_fmac_f32_e32 v202, v196, v196
	v_fmac_f32_e32 v201, v119, v119
	v_add_f32_e32 v112, v124, v200
	v_fmac_f32_e32 v202, v197, v197
	v_add_f32_e32 v112, v112, v201
	v_add_f32_e32 v112, v112, v202
	ds_bpermute_b32 v113, v192, v112
	v_cvt_pk_bf16_f32 v114, v120, v121
	v_cvt_pk_bf16_f32 v115, v122, v123
	v_cvt_pk_bf16_f32 v198, v116, v117
	v_cvt_pk_bf16_f32 v199, v118, v119
	global_store_dwordx4 v[212:213], v[120:123], off offset:64
	v_mov_b32_e32 v242, v114
	v_mov_b32_e32 v243, v115
	s_nop 1
	v_permlane16_swap_b32 v240, v242
	v_permlane16_swap_b32 v241, v243
	global_store_dwordx4 v[244:245], v[240:243], off
	global_store_dwordx4 v[212:213], v[116:119], off offset:512
	s_nop 1
	v_mov_b32_e32 v240, v198
	v_mov_b32_e32 v241, v199
	v_lshl_add_u64 v[244:245], v[218:219], 0, v[246:247]
	global_store_dwordx4 v[212:213], v[194:197], off offset:576
	s_waitcnt lgkmcnt(0)
	v_add_f32_e32 v112, v112, v113
	v_lshlrev_b32_e32 v116, 2, v193
	ds_bpermute_b32 v113, v116, v112
	v_lshl_add_u64 v[114:115], s[4:5], 0, v[210:211]
	v_cvt_pk_bf16_f32 v118, v194, v195
	v_cvt_pk_bf16_f32 v119, v196, v197
	v_mov_b32_e32 v242, v118
	v_mov_b32_e32 v243, v119
	s_nop 1
	v_permlane16_swap_b32 v240, v242
	v_permlane16_swap_b32 v241, v243
	global_store_dwordx4 v[244:245], v[240:243], off
	s_and_saveexec_b64 s[28:29], s[6:7]
	s_cbranch_execz .LBB0_1815
	v_lshlrev_b64 v[114:115], 6, v[164:165]
	v_lshl_add_u64 v[114:115], s[14:15], 0, v[114:115]
	v_lshl_add_u64 v[114:115], s[26:27], 2, v[114:115]
	s_lshl_b32 s18, s53, 2
	v_lshl_add_u64 v[114:115], v[114:115], 0, s[18:19]
	s_waitcnt lgkmcnt(0)
	v_add_f32_e32 v112, v112, v113
	flat_store_dword v[114:115], v112
.LBB0_1815:
	s_or_b64 exec, exec, s[28:29]
	s_waitcnt lgkmcnt(0)
	v_lshlrev_b64 v[112:113], 10, v[168:169]
	v_lshl_add_u64 v[112:113], v[112:113], 0, v[162:163]
	v_pk_fma_f32 v[108:109], v[108:109], 0.5, v[140:141] op_sel_hi:[1,0,1]
	v_lshl_add_u64 v[114:115], v[112:113], 2, s[78:79]
	v_lshlrev_b64 v[112:113], 1, v[112:113]
	v_mul_f32_e32 v117, v108, v108
	v_pk_fma_f32 v[110:111], v[110:111], 0.5, v[142:143] op_sel_hi:[1,0,1]
	v_lshl_add_u64 v[118:119], s[4:5], 0, v[112:113]
	v_fmac_f32_e32 v117, v109, v109
	v_pk_fma_f32 v[106:107], v[106:107], 0.5, v[138:139] op_sel_hi:[1,0,1]
	v_pk_fma_f32 v[104:105], v[104:105], 0.5, v[136:137] op_sel_hi:[1,0,1]
	global_store_dwordx4 v[114:115], v[108:111], off
	v_cvt_pk_bf16_f32 v120, v108, v109
	v_cvt_pk_bf16_f32 v121, v110, v111
	s_nop 1
	v_mov_b32_e32 v240, v120
	v_mov_b32_e32 v241, v121
	v_lshl_add_u64 v[244:245], v[118:119], 0, v[246:247]
	v_fmac_f32_e32 v117, v110, v110
	global_store_dwordx4 v[114:115], v[104:107], off offset:64
	v_or_b32_e32 v108, 32, v112
	v_mov_b32_e32 v109, v113
	v_cvt_pk_bf16_f32 v110, v104, v105
	v_mul_f32_e32 v104, v104, v104
	v_lshl_add_u64 v[108:109], s[4:5], 0, v[108:109]
	v_fmac_f32_e32 v104, v105, v105
	v_pk_fma_f32 v[102:103], v[102:103], 0.5, v[134:135] op_sel_hi:[1,0,1]
	v_pk_fma_f32 v[100:101], v[100:101], 0.5, v[132:133] op_sel_hi:[1,0,1]
	v_fmac_f32_e32 v117, v111, v111
	v_cvt_pk_bf16_f32 v111, v106, v107
	v_mov_b32_e32 v242, v110
	v_mov_b32_e32 v243, v111
	s_nop 1
	v_permlane16_swap_b32 v240, v242
	v_permlane16_swap_b32 v241, v243
	global_store_dwordx4 v[244:245], v[240:243], off
	v_fmac_f32_e32 v104, v106, v106
	global_store_dwordx4 v[114:115], v[100:103], off offset:512
	v_cvt_pk_bf16_f32 v106, v100, v101
	v_fmac_f32_e32 v104, v107, v107
	v_add_f32_e32 v107, v117, v104
	v_mul_f32_e32 v100, v100, v100
	v_fmac_f32_e32 v100, v101, v101
	v_fmac_f32_e32 v100, v102, v102
	v_fmac_f32_e32 v100, v103, v103
	v_add_f32_e32 v107, v107, v100
	v_pk_fma_f32 v[100:101], v[98:99], 0.5, v[130:131] op_sel_hi:[1,0,1]
	v_pk_fma_f32 v[98:99], v[96:97], 0.5, v[128:129] op_sel_hi:[1,0,1]
	v_or_b32_e32 v104, 0x100, v112
	v_mul_f32_e32 v96, v98, v98
	v_fmac_f32_e32 v96, v99, v99
	v_fmac_f32_e32 v96, v100, v100
	v_fmac_f32_e32 v96, v101, v101
	v_add_f32_e32 v96, v107, v96
	ds_bpermute_b32 v97, v192, v96
	v_mov_b32_e32 v105, v113
	v_or_b32_e32 v112, 0x120, v112
	v_lshl_add_u64 v[104:105], s[4:5], 0, v[104:105]
	v_cvt_pk_bf16_f32 v107, v102, v103
	s_waitcnt lgkmcnt(0)
	v_add_f32_e32 v96, v96, v97
	ds_bpermute_b32 v97, v116, v96
	v_lshl_add_u64 v[102:103], s[4:5], 0, v[112:113]
	s_nop 1
	v_mov_b32_e32 v240, v106
	v_mov_b32_e32 v241, v107
	v_lshl_add_u64 v[244:245], v[104:105], 0, v[246:247]
	global_store_dwordx4 v[114:115], v[98:101], off offset:576
	s_nop 1
	v_cvt_pk_bf16_f32 v98, v98, v99
	v_cvt_pk_bf16_f32 v99, v100, v101
	v_mov_b32_e32 v242, v98
	v_mov_b32_e32 v243, v99
	s_nop 1
	v_permlane16_swap_b32 v240, v242
	v_permlane16_swap_b32 v241, v243
	global_store_dwordx4 v[244:245], v[240:243], off
	s_and_saveexec_b64 s[28:29], s[6:7]
	s_cbranch_execz .LBB0_1817
	v_lshlrev_b64 v[98:99], 6, v[168:169]
	v_lshl_add_u64 v[98:99], s[14:15], 0, v[98:99]
	v_lshl_add_u64 v[98:99], s[26:27], 2, v[98:99]
	s_lshl_b32 s18, s53, 2
	v_lshl_add_u64 v[98:99], v[98:99], 0, s[18:19]
	s_waitcnt lgkmcnt(0)
	v_add_f32_e32 v96, v96, v97
	flat_store_dword v[98:99], v96
.LBB0_1817:
	s_or_b64 exec, exec, s[28:29]
	v_or_b32_e32 v114, 32, v164
	v_mov_b32_e32 v115, v165
	s_waitcnt lgkmcnt(0)
	v_lshlrev_b64 v[96:97], 12, v[114:115]
	v_lshl_add_u64 v[96:97], v[166:167], 0, v[96:97]
	global_load_dwordx4 v[118:121], v[96:97], off
	global_load_dwordx4 v[122:125], v[96:97], off offset:64
	global_load_dwordx4 v[126:129], v[96:97], off offset:512
	global_load_dwordx4 v[130:133], v[96:97], off offset:576
	v_or_b32_e32 v112, 48, v164
	v_mov_b32_e32 v113, v165
	v_lshlrev_b64 v[96:97], 12, v[112:113]
	v_lshl_add_u64 v[96:97], v[166:167], 0, v[96:97]
	global_load_dwordx4 v[108:111], v[96:97], off
	global_load_dwordx4 v[104:107], v[96:97], off offset:64
	global_load_dwordx4 v[100:103], v[96:97], off offset:512
	s_nop 0
	global_load_dwordx4 v[96:99], v[96:97], off offset:576
	v_lshlrev_b64 v[134:135], 10, v[114:115]
	v_lshl_add_u64 v[134:135], v[134:135], 0, v[162:163]
	v_lshl_add_u64 v[136:137], v[134:135], 2, s[78:79]
	v_lshlrev_b64 v[134:135], 1, v[134:135]
	v_lshl_add_u64 v[138:139], s[4:5], 0, v[134:135]
	s_waitcnt vmcnt(0)
	v_or_b32_e32 v140, 32, v134
	v_mov_b32_e32 v141, v135
	v_or_b32_e32 v142, 0x100, v134
	v_mov_b32_e32 v143, v135
	v_or_b32_e32 v134, 0x120, v134
	v_lshl_add_u64 v[140:141], s[4:5], 0, v[140:141]
	v_lshl_add_u64 v[142:143], s[4:5], 0, v[142:143]
	s_waitcnt vmcnt(0)
	v_pk_fma_f32 v[92:93], v[92:93], 0.5, v[118:119] op_sel_hi:[1,0,1]
	v_pk_fma_f32 v[88:89], v[88:89], 0.5, v[122:123] op_sel_hi:[1,0,1]
	v_pk_fma_f32 v[84:85], v[84:85], 0.5, v[126:127] op_sel_hi:[1,0,1]
	v_mul_f32_e32 v117, v92, v92
	v_mul_f32_e32 v122, v88, v88
	v_pk_fma_f32 v[94:95], v[94:95], 0.5, v[120:121] op_sel_hi:[1,0,1]
	v_pk_fma_f32 v[90:91], v[90:91], 0.5, v[124:125] op_sel_hi:[1,0,1]
	v_pk_fma_f32 v[118:119], v[80:81], 0.5, v[130:131] op_sel_hi:[1,0,1]
	v_mul_f32_e32 v123, v84, v84
	v_fmac_f32_e32 v117, v93, v93
	v_fmac_f32_e32 v122, v89, v89
	v_pk_fma_f32 v[86:87], v[86:87], 0.5, v[128:129] op_sel_hi:[1,0,1]
	v_mul_f32_e32 v124, v118, v118
	v_fmac_f32_e32 v123, v85, v85
	v_fmac_f32_e32 v117, v94, v94
	v_fmac_f32_e32 v122, v90, v90
	v_pk_fma_f32 v[120:121], v[82:83], 0.5, v[132:133] op_sel_hi:[1,0,1]
	v_cvt_pk_bf16_f32 v80, v92, v93
	v_fmac_f32_e32 v124, v119, v119
	v_fmac_f32_e32 v123, v86, v86
	v_fmac_f32_e32 v117, v95, v95
	v_fmac_f32_e32 v122, v91, v91
	global_store_dwordx4 v[136:137], v[92:95], off
	v_cvt_pk_bf16_f32 v81, v94, v95
	s_nop 1
	v_mov_b32_e32 v240, v80
	v_mov_b32_e32 v241, v81
	v_lshl_add_u64 v[244:245], v[138:139], 0, v[246:247]
	v_fmac_f32_e32 v124, v120, v120
	v_fmac_f32_e32 v123, v87, v87
	v_add_f32_e32 v80, v117, v122
	v_add_f32_e32 v80, v80, v123
	v_fmac_f32_e32 v124, v121, v121
	v_add_f32_e32 v80, v80, v124
	ds_bpermute_b32 v81, v192, v80
	v_cvt_pk_bf16_f32 v82, v88, v89
	v_cvt_pk_bf16_f32 v83, v90, v91
	v_cvt_pk_bf16_f32 v92, v84, v85
	global_store_dwordx4 v[136:137], v[88:91], off offset:64
	v_mov_b32_e32 v242, v82
	v_mov_b32_e32 v243, v83
	s_nop 1
	v_permlane16_swap_b32 v240, v242
	v_permlane16_swap_b32 v241, v243
	global_store_dwordx4 v[244:245], v[240:243], off
	s_waitcnt lgkmcnt(0)
	v_add_f32_e32 v80, v80, v81
	ds_bpermute_b32 v81, v116, v80
	v_cvt_pk_bf16_f32 v93, v86, v87
	v_lshl_add_u64 v[82:83], s[4:5], 0, v[134:135]
	global_store_dwordx4 v[136:137], v[84:87], off offset:512
	s_nop 1
	v_mov_b32_e32 v240, v92
	v_mov_b32_e32 v241, v93
	v_lshl_add_u64 v[244:245], v[142:143], 0, v[246:247]
	global_store_dwordx4 v[136:137], v[118:121], off offset:576
	v_cvt_pk_bf16_f32 v84, v118, v119
	v_cvt_pk_bf16_f32 v85, v120, v121
	v_mov_b32_e32 v242, v84
	v_mov_b32_e32 v243, v85
	s_nop 1
	v_permlane16_swap_b32 v240, v242
	v_permlane16_swap_b32 v241, v243
	global_store_dwordx4 v[244:245], v[240:243], off
	s_and_saveexec_b64 s[28:29], s[6:7]
	s_cbranch_execz .LBB0_1819
	v_lshlrev_b64 v[82:83], 6, v[114:115]
	v_lshl_add_u64 v[82:83], s[14:15], 0, v[82:83]
	v_lshl_add_u64 v[82:83], s[26:27], 2, v[82:83]
	s_lshl_b32 s18, s53, 2
	v_lshl_add_u64 v[82:83], v[82:83], 0, s[18:19]
	s_waitcnt lgkmcnt(0)
	v_add_f32_e32 v80, v80, v81
	flat_store_dword v[82:83], v80
.LBB0_1819:
	s_or_b64 exec, exec, s[28:29]
	s_waitcnt lgkmcnt(0)
	v_lshlrev_b64 v[80:81], 10, v[112:113]
	v_lshl_add_u64 v[80:81], v[80:81], 0, v[162:163]
	v_lshl_add_u64 v[82:83], v[80:81], 2, s[78:79]
	v_lshlrev_b64 v[80:81], 1, v[80:81]
	v_pk_fma_f32 v[78:79], v[78:79], 0.5, v[110:111] op_sel_hi:[1,0,1]
	v_pk_fma_f32 v[76:77], v[76:77], 0.5, v[108:109] op_sel_hi:[1,0,1]
	v_lshl_add_u64 v[84:85], s[4:5], 0, v[80:81]
	global_store_dwordx4 v[82:83], v[76:79], off
	v_cvt_pk_bf16_f32 v86, v76, v77
	v_cvt_pk_bf16_f32 v87, v78, v79
	s_nop 1
	v_mov_b32_e32 v240, v86
	v_mov_b32_e32 v241, v87
	v_lshl_add_u64 v[244:245], v[84:85], 0, v[246:247]
	v_mul_f32_e32 v84, v76, v76
	v_fmac_f32_e32 v84, v77, v77
	v_pk_fma_f32 v[74:75], v[74:75], 0.5, v[106:107] op_sel_hi:[1,0,1]
	v_pk_fma_f32 v[72:73], v[72:73], 0.5, v[104:105] op_sel_hi:[1,0,1]
	v_fmac_f32_e32 v84, v78, v78
	global_store_dwordx4 v[82:83], v[72:75], off offset:64
	v_or_b32_e32 v76, 32, v80
	v_mov_b32_e32 v77, v81
	v_cvt_pk_bf16_f32 v78, v72, v73
	v_mul_f32_e32 v72, v72, v72
	v_lshl_add_u64 v[76:77], s[4:5], 0, v[76:77]
	v_fmac_f32_e32 v72, v73, v73
	v_pk_fma_f32 v[70:71], v[70:71], 0.5, v[102:103] op_sel_hi:[1,0,1]
	v_pk_fma_f32 v[68:69], v[68:69], 0.5, v[100:101] op_sel_hi:[1,0,1]
	v_fmac_f32_e32 v84, v79, v79
	v_cvt_pk_bf16_f32 v79, v74, v75
	v_mov_b32_e32 v242, v78
	v_mov_b32_e32 v243, v79
	s_nop 1
	v_permlane16_swap_b32 v240, v242
	v_permlane16_swap_b32 v241, v243
	global_store_dwordx4 v[244:245], v[240:243], off
	v_fmac_f32_e32 v72, v74, v74
	global_store_dwordx4 v[82:83], v[68:71], off offset:512
	v_cvt_pk_bf16_f32 v74, v68, v69
	v_fmac_f32_e32 v72, v75, v75
	v_add_f32_e32 v75, v84, v72
	v_mul_f32_e32 v68, v68, v68
	v_fmac_f32_e32 v68, v69, v69
	v_fmac_f32_e32 v68, v70, v70
	v_fmac_f32_e32 v68, v71, v71
	v_add_f32_e32 v75, v75, v68
	v_pk_fma_f32 v[68:69], v[66:67], 0.5, v[98:99] op_sel_hi:[1,0,1]
	v_pk_fma_f32 v[66:67], v[64:65], 0.5, v[96:97] op_sel_hi:[1,0,1]
	v_or_b32_e32 v72, 0x100, v80
	v_mul_f32_e32 v64, v66, v66
	v_fmac_f32_e32 v64, v67, v67
	v_fmac_f32_e32 v64, v68, v68
	v_fmac_f32_e32 v64, v69, v69
	v_add_f32_e32 v64, v75, v64
	ds_bpermute_b32 v65, v192, v64
	v_mov_b32_e32 v73, v81
	v_or_b32_e32 v80, 0x120, v80
	v_lshl_add_u64 v[72:73], s[4:5], 0, v[72:73]
	v_cvt_pk_bf16_f32 v75, v70, v71
	s_waitcnt lgkmcnt(0)
	v_add_f32_e32 v64, v64, v65
	ds_bpermute_b32 v65, v116, v64
	v_lshl_add_u64 v[70:71], s[4:5], 0, v[80:81]
	s_nop 1
	v_mov_b32_e32 v240, v74
	v_mov_b32_e32 v241, v75
	v_lshl_add_u64 v[244:245], v[72:73], 0, v[246:247]
	global_store_dwordx4 v[82:83], v[66:69], off offset:576
	s_nop 1
	v_cvt_pk_bf16_f32 v66, v66, v67
	v_cvt_pk_bf16_f32 v67, v68, v69
	v_mov_b32_e32 v242, v66
	v_mov_b32_e32 v243, v67
	s_nop 1
	v_permlane16_swap_b32 v240, v242
	v_permlane16_swap_b32 v241, v243
	global_store_dwordx4 v[244:245], v[240:243], off
	s_and_saveexec_b64 s[28:29], s[6:7]
	s_cbranch_execz .LBB0_1821
	v_lshlrev_b64 v[66:67], 6, v[112:113]
	v_lshl_add_u64 v[66:67], s[14:15], 0, v[66:67]
	v_lshl_add_u64 v[66:67], s[26:27], 2, v[66:67]
	s_lshl_b32 s18, s53, 2
	v_lshl_add_u64 v[66:67], v[66:67], 0, s[18:19]
	s_waitcnt lgkmcnt(0)
	v_add_f32_e32 v64, v64, v65
	flat_store_dword v[66:67], v64
.LBB0_1821:
	s_or_b64 exec, exec, s[28:29]
	v_lshl_add_u64 v[82:83], v[164:165], 0, s[16:17]
	s_waitcnt lgkmcnt(0)
	v_lshlrev_b64 v[64:65], 12, v[82:83]
	v_lshl_add_u64 v[64:65], v[166:167], 0, v[64:65]
	global_load_dwordx4 v[84:87], v[64:65], off
	global_load_dwordx4 v[88:91], v[64:65], off offset:64
	global_load_dwordx4 v[92:95], v[64:65], off offset:512
	global_load_dwordx4 v[96:99], v[64:65], off offset:576
	v_lshl_add_u64 v[80:81], v[164:165], 0, s[20:21]
	v_lshlrev_b64 v[64:65], 12, v[80:81]
	v_lshl_add_u64 v[64:65], v[166:167], 0, v[64:65]
	global_load_dwordx4 v[76:79], v[64:65], off
	global_load_dwordx4 v[72:75], v[64:65], off offset:64
	global_load_dwordx4 v[68:71], v[64:65], off offset:512
	s_nop 0
	global_load_dwordx4 v[64:67], v[64:65], off offset:576
	v_lshlrev_b64 v[100:101], 10, v[82:83]
	v_lshl_add_u64 v[100:101], v[100:101], 0, v[162:163]
	v_lshl_add_u64 v[102:103], v[100:101], 2, s[78:79]
	v_lshlrev_b64 v[100:101], 1, v[100:101]
	v_lshl_add_u64 v[104:105], s[4:5], 0, v[100:101]
	s_waitcnt vmcnt(0)
	v_or_b32_e32 v106, 32, v100
	v_mov_b32_e32 v107, v101
	v_or_b32_e32 v108, 0x100, v100
	v_mov_b32_e32 v109, v101
	v_or_b32_e32 v100, 0x120, v100
	v_lshl_add_u64 v[106:107], s[4:5], 0, v[106:107]
	v_lshl_add_u64 v[108:109], s[4:5], 0, v[108:109]
	s_waitcnt vmcnt(0)
	v_pk_fma_f32 v[60:61], v[60:61], 0.5, v[84:85] op_sel_hi:[1,0,1]
	v_pk_fma_f32 v[56:57], v[56:57], 0.5, v[88:89] op_sel_hi:[1,0,1]
	v_pk_fma_f32 v[52:53], v[52:53], 0.5, v[92:93] op_sel_hi:[1,0,1]
	v_mul_f32_e32 v88, v60, v60
	v_mul_f32_e32 v89, v56, v56
	v_pk_fma_f32 v[62:63], v[62:63], 0.5, v[86:87] op_sel_hi:[1,0,1]
	v_pk_fma_f32 v[58:59], v[58:59], 0.5, v[90:91] op_sel_hi:[1,0,1]
	v_pk_fma_f32 v[84:85], v[48:49], 0.5, v[96:97] op_sel_hi:[1,0,1]
	v_mul_f32_e32 v90, v52, v52
	v_fmac_f32_e32 v88, v61, v61
	v_fmac_f32_e32 v89, v57, v57
	v_pk_fma_f32 v[54:55], v[54:55], 0.5, v[94:95] op_sel_hi:[1,0,1]
	v_mul_f32_e32 v91, v84, v84
	v_fmac_f32_e32 v90, v53, v53
	v_fmac_f32_e32 v88, v62, v62
	v_fmac_f32_e32 v89, v58, v58
	v_pk_fma_f32 v[86:87], v[50:51], 0.5, v[98:99] op_sel_hi:[1,0,1]
	v_cvt_pk_bf16_f32 v48, v60, v61
	v_fmac_f32_e32 v91, v85, v85
	v_fmac_f32_e32 v90, v54, v54
	v_fmac_f32_e32 v88, v63, v63
	v_fmac_f32_e32 v89, v59, v59
	global_store_dwordx4 v[102:103], v[60:63], off
	v_cvt_pk_bf16_f32 v49, v62, v63
	s_nop 1
	v_mov_b32_e32 v240, v48
	v_mov_b32_e32 v241, v49
	v_lshl_add_u64 v[244:245], v[104:105], 0, v[246:247]
	v_fmac_f32_e32 v91, v86, v86
	v_fmac_f32_e32 v90, v55, v55
	v_add_f32_e32 v48, v88, v89
	v_add_f32_e32 v48, v48, v90
	v_fmac_f32_e32 v91, v87, v87
	v_add_f32_e32 v48, v48, v91
	ds_bpermute_b32 v49, v192, v48
	v_cvt_pk_bf16_f32 v50, v56, v57
	v_cvt_pk_bf16_f32 v51, v58, v59
	v_cvt_pk_bf16_f32 v60, v52, v53
	global_store_dwordx4 v[102:103], v[56:59], off offset:64
	v_mov_b32_e32 v242, v50
	v_mov_b32_e32 v243, v51
	s_nop 1
	v_permlane16_swap_b32 v240, v242
	v_permlane16_swap_b32 v241, v243
	global_store_dwordx4 v[244:245], v[240:243], off
	s_waitcnt lgkmcnt(0)
	v_add_f32_e32 v48, v48, v49
	ds_bpermute_b32 v49, v116, v48
	v_cvt_pk_bf16_f32 v61, v54, v55
	v_lshl_add_u64 v[50:51], s[4:5], 0, v[100:101]
	global_store_dwordx4 v[102:103], v[52:55], off offset:512
	s_nop 1
	v_mov_b32_e32 v240, v60
	v_mov_b32_e32 v241, v61
	v_lshl_add_u64 v[244:245], v[108:109], 0, v[246:247]
	global_store_dwordx4 v[102:103], v[84:87], off offset:576
	v_cvt_pk_bf16_f32 v52, v84, v85
	v_cvt_pk_bf16_f32 v53, v86, v87
	v_mov_b32_e32 v242, v52
	v_mov_b32_e32 v243, v53
	s_nop 1
	v_permlane16_swap_b32 v240, v242
	v_permlane16_swap_b32 v241, v243
	global_store_dwordx4 v[244:245], v[240:243], off
	s_and_saveexec_b64 s[28:29], s[6:7]
	s_cbranch_execz .LBB0_1823
	v_lshlrev_b64 v[50:51], 6, v[82:83]
	v_lshl_add_u64 v[50:51], s[14:15], 0, v[50:51]
	v_lshl_add_u64 v[50:51], s[26:27], 2, v[50:51]
	s_lshl_b32 s18, s53, 2
	v_lshl_add_u64 v[50:51], v[50:51], 0, s[18:19]
	s_waitcnt lgkmcnt(0)
	v_add_f32_e32 v48, v48, v49
	flat_store_dword v[50:51], v48
.LBB0_1823:
	s_or_b64 exec, exec, s[28:29]
	s_waitcnt lgkmcnt(0)
	v_lshlrev_b64 v[48:49], 10, v[80:81]
	v_lshl_add_u64 v[48:49], v[48:49], 0, v[162:163]
	v_lshl_add_u64 v[50:51], v[48:49], 2, s[78:79]
	v_lshlrev_b64 v[48:49], 1, v[48:49]
	v_pk_fma_f32 v[46:47], v[46:47], 0.5, v[78:79] op_sel_hi:[1,0,1]
	v_pk_fma_f32 v[44:45], v[44:45], 0.5, v[76:77] op_sel_hi:[1,0,1]
	v_lshl_add_u64 v[52:53], s[4:5], 0, v[48:49]
	global_store_dwordx4 v[50:51], v[44:47], off
	v_cvt_pk_bf16_f32 v54, v44, v45
	v_cvt_pk_bf16_f32 v55, v46, v47
	s_nop 1
	v_mov_b32_e32 v240, v54
	v_mov_b32_e32 v241, v55
	v_lshl_add_u64 v[244:245], v[52:53], 0, v[246:247]
	v_mul_f32_e32 v52, v44, v44
	v_fmac_f32_e32 v52, v45, v45
	v_pk_fma_f32 v[42:43], v[42:43], 0.5, v[74:75] op_sel_hi:[1,0,1]
	v_pk_fma_f32 v[40:41], v[40:41], 0.5, v[72:73] op_sel_hi:[1,0,1]
	v_fmac_f32_e32 v52, v46, v46
	global_store_dwordx4 v[50:51], v[40:43], off offset:64
	v_or_b32_e32 v44, 32, v48
	v_mov_b32_e32 v45, v49
	v_cvt_pk_bf16_f32 v46, v40, v41
	v_mul_f32_e32 v40, v40, v40
	v_lshl_add_u64 v[44:45], s[4:5], 0, v[44:45]
	v_fmac_f32_e32 v40, v41, v41
	v_pk_fma_f32 v[38:39], v[38:39], 0.5, v[70:71] op_sel_hi:[1,0,1]
	v_pk_fma_f32 v[36:37], v[36:37], 0.5, v[68:69] op_sel_hi:[1,0,1]
	v_fmac_f32_e32 v52, v47, v47
	v_cvt_pk_bf16_f32 v47, v42, v43
	v_mov_b32_e32 v242, v46
	v_mov_b32_e32 v243, v47
	s_nop 1
	v_permlane16_swap_b32 v240, v242
	v_permlane16_swap_b32 v241, v243
	global_store_dwordx4 v[244:245], v[240:243], off
	v_fmac_f32_e32 v40, v42, v42
	global_store_dwordx4 v[50:51], v[36:39], off offset:512
	v_cvt_pk_bf16_f32 v42, v36, v37
	v_fmac_f32_e32 v40, v43, v43
	v_add_f32_e32 v43, v52, v40
	v_mul_f32_e32 v36, v36, v36
	v_fmac_f32_e32 v36, v37, v37
	v_fmac_f32_e32 v36, v38, v38
	v_fmac_f32_e32 v36, v39, v39
	v_add_f32_e32 v43, v43, v36
	v_pk_fma_f32 v[36:37], v[34:35], 0.5, v[66:67] op_sel_hi:[1,0,1]
	v_pk_fma_f32 v[34:35], v[32:33], 0.5, v[64:65] op_sel_hi:[1,0,1]
	v_or_b32_e32 v40, 0x100, v48
	v_mul_f32_e32 v32, v34, v34
	v_fmac_f32_e32 v32, v35, v35
	v_fmac_f32_e32 v32, v36, v36
	v_fmac_f32_e32 v32, v37, v37
	v_add_f32_e32 v32, v43, v32
	ds_bpermute_b32 v33, v192, v32
	v_mov_b32_e32 v41, v49
	v_or_b32_e32 v48, 0x120, v48
	v_lshl_add_u64 v[40:41], s[4:5], 0, v[40:41]
	v_cvt_pk_bf16_f32 v43, v38, v39
	s_waitcnt lgkmcnt(0)
	v_add_f32_e32 v32, v32, v33
	ds_bpermute_b32 v33, v116, v32
	v_lshl_add_u64 v[38:39], s[4:5], 0, v[48:49]
	s_nop 1
	v_mov_b32_e32 v240, v42
	v_mov_b32_e32 v241, v43
	v_lshl_add_u64 v[244:245], v[40:41], 0, v[246:247]
	global_store_dwordx4 v[50:51], v[34:37], off offset:576
	s_nop 1
	v_cvt_pk_bf16_f32 v34, v34, v35
	v_cvt_pk_bf16_f32 v35, v36, v37
	v_mov_b32_e32 v242, v34
	v_mov_b32_e32 v243, v35
	s_nop 1
	v_permlane16_swap_b32 v240, v242
	v_permlane16_swap_b32 v241, v243
	global_store_dwordx4 v[244:245], v[240:243], off
	s_and_saveexec_b64 s[28:29], s[6:7]
	s_cbranch_execz .LBB0_1825
	v_lshlrev_b64 v[34:35], 6, v[80:81]
	v_lshl_add_u64 v[34:35], s[14:15], 0, v[34:35]
	v_lshl_add_u64 v[34:35], s[26:27], 2, v[34:35]
	s_lshl_b32 s18, s53, 2
	v_lshl_add_u64 v[34:35], v[34:35], 0, s[18:19]
	s_waitcnt lgkmcnt(0)
	v_add_f32_e32 v32, v32, v33
	flat_store_dword v[34:35], v32
.LBB0_1825:
	s_or_b64 exec, exec, s[28:29]
	v_lshl_add_u64 v[50:51], v[164:165], 0, s[22:23]
	s_waitcnt lgkmcnt(0)
	v_lshlrev_b64 v[32:33], 12, v[50:51]
	v_lshl_add_u64 v[32:33], v[166:167], 0, v[32:33]
	global_load_dwordx4 v[52:55], v[32:33], off
	global_load_dwordx4 v[56:59], v[32:33], off offset:64
	global_load_dwordx4 v[60:63], v[32:33], off offset:512
	global_load_dwordx4 v[64:67], v[32:33], off offset:576
	v_lshl_add_u64 v[48:49], v[164:165], 0, s[24:25]
	v_lshlrev_b64 v[32:33], 12, v[48:49]
	v_lshl_add_u64 v[32:33], v[166:167], 0, v[32:33]
	global_load_dwordx4 v[44:47], v[32:33], off
	global_load_dwordx4 v[40:43], v[32:33], off offset:64
	global_load_dwordx4 v[36:39], v[32:33], off offset:512
	s_nop 0
	global_load_dwordx4 v[32:35], v[32:33], off offset:576
	v_lshlrev_b64 v[68:69], 10, v[50:51]
	v_lshl_add_u64 v[68:69], v[68:69], 0, v[162:163]
	v_lshl_add_u64 v[70:71], v[68:69], 2, s[78:79]
	v_lshlrev_b64 v[68:69], 1, v[68:69]
	v_lshl_add_u64 v[72:73], s[4:5], 0, v[68:69]
	s_waitcnt vmcnt(0)
	v_or_b32_e32 v74, 32, v68
	v_mov_b32_e32 v75, v69
	v_or_b32_e32 v76, 0x100, v68
	v_mov_b32_e32 v77, v69
	v_or_b32_e32 v68, 0x120, v68
	v_lshl_add_u64 v[74:75], s[4:5], 0, v[74:75]
	v_lshl_add_u64 v[76:77], s[4:5], 0, v[76:77]
	s_waitcnt vmcnt(0)
	v_pk_fma_f32 v[28:29], v[28:29], 0.5, v[52:53] op_sel_hi:[1,0,1]
	v_pk_fma_f32 v[24:25], v[24:25], 0.5, v[56:57] op_sel_hi:[1,0,1]
	v_pk_fma_f32 v[20:21], v[20:21], 0.5, v[60:61] op_sel_hi:[1,0,1]
	v_mul_f32_e32 v56, v28, v28
	v_mul_f32_e32 v57, v24, v24
	v_pk_fma_f32 v[30:31], v[30:31], 0.5, v[54:55] op_sel_hi:[1,0,1]
	v_pk_fma_f32 v[26:27], v[26:27], 0.5, v[58:59] op_sel_hi:[1,0,1]
	v_pk_fma_f32 v[52:53], v[16:17], 0.5, v[64:65] op_sel_hi:[1,0,1]
	v_mul_f32_e32 v58, v20, v20
	v_fmac_f32_e32 v56, v29, v29
	v_fmac_f32_e32 v57, v25, v25
	v_pk_fma_f32 v[22:23], v[22:23], 0.5, v[62:63] op_sel_hi:[1,0,1]
	v_mul_f32_e32 v59, v52, v52
	v_fmac_f32_e32 v58, v21, v21
	v_fmac_f32_e32 v56, v30, v30
	v_fmac_f32_e32 v57, v26, v26
	v_pk_fma_f32 v[54:55], v[18:19], 0.5, v[66:67] op_sel_hi:[1,0,1]
	v_cvt_pk_bf16_f32 v16, v28, v29
	v_fmac_f32_e32 v59, v53, v53
	v_fmac_f32_e32 v58, v22, v22
	v_fmac_f32_e32 v56, v31, v31
	v_fmac_f32_e32 v57, v27, v27
	global_store_dwordx4 v[70:71], v[28:31], off
	v_cvt_pk_bf16_f32 v17, v30, v31
	s_nop 1
	v_mov_b32_e32 v240, v16
	v_mov_b32_e32 v241, v17
	v_lshl_add_u64 v[244:245], v[72:73], 0, v[246:247]
	v_fmac_f32_e32 v59, v54, v54
	v_fmac_f32_e32 v58, v23, v23
	v_add_f32_e32 v16, v56, v57
	v_add_f32_e32 v16, v16, v58
	v_fmac_f32_e32 v59, v55, v55
	v_add_f32_e32 v16, v16, v59
	ds_bpermute_b32 v17, v192, v16
	v_cvt_pk_bf16_f32 v18, v24, v25
	v_cvt_pk_bf16_f32 v19, v26, v27
	v_cvt_pk_bf16_f32 v28, v20, v21
	global_store_dwordx4 v[70:71], v[24:27], off offset:64
	v_mov_b32_e32 v242, v18
	v_mov_b32_e32 v243, v19
	s_nop 1
	v_permlane16_swap_b32 v240, v242
	v_permlane16_swap_b32 v241, v243
	global_store_dwordx4 v[244:245], v[240:243], off
	s_waitcnt lgkmcnt(0)
	v_add_f32_e32 v16, v16, v17
	ds_bpermute_b32 v17, v116, v16
	v_cvt_pk_bf16_f32 v29, v22, v23
	v_lshl_add_u64 v[18:19], s[4:5], 0, v[68:69]
	global_store_dwordx4 v[70:71], v[20:23], off offset:512
	s_nop 1
	v_mov_b32_e32 v240, v28
	v_mov_b32_e32 v241, v29
	v_lshl_add_u64 v[244:245], v[76:77], 0, v[246:247]
	global_store_dwordx4 v[70:71], v[52:55], off offset:576
	v_cvt_pk_bf16_f32 v20, v52, v53
	v_cvt_pk_bf16_f32 v21, v54, v55
	v_mov_b32_e32 v242, v20
	v_mov_b32_e32 v243, v21
	s_nop 1
	v_permlane16_swap_b32 v240, v242
	v_permlane16_swap_b32 v241, v243
	global_store_dwordx4 v[244:245], v[240:243], off
	s_and_saveexec_b64 s[28:29], s[6:7]
	s_cbranch_execz .LBB0_1827
	v_lshlrev_b64 v[18:19], 6, v[50:51]
	v_lshl_add_u64 v[18:19], s[14:15], 0, v[18:19]
	v_lshl_add_u64 v[18:19], s[26:27], 2, v[18:19]
	s_lshl_b32 s18, s53, 2
	v_lshl_add_u64 v[18:19], v[18:19], 0, s[18:19]
	s_waitcnt lgkmcnt(0)
	v_add_f32_e32 v16, v16, v17
	flat_store_dword v[18:19], v16
.LBB0_1827:
	s_or_b64 exec, exec, s[28:29]
	s_waitcnt lgkmcnt(0)
	v_lshlrev_b64 v[16:17], 10, v[48:49]
	v_lshl_add_u64 v[16:17], v[16:17], 0, v[162:163]
	v_lshl_add_u64 v[18:19], v[16:17], 2, s[78:79]
	v_lshlrev_b64 v[16:17], 1, v[16:17]
	v_pk_fma_f32 v[14:15], v[14:15], 0.5, v[46:47] op_sel_hi:[1,0,1]
	v_pk_fma_f32 v[12:13], v[12:13], 0.5, v[44:45] op_sel_hi:[1,0,1]
	v_lshl_add_u64 v[20:21], s[4:5], 0, v[16:17]
	global_store_dwordx4 v[18:19], v[12:15], off
	v_cvt_pk_bf16_f32 v22, v12, v13
	v_cvt_pk_bf16_f32 v23, v14, v15
	s_nop 1
	v_mov_b32_e32 v240, v22
	v_mov_b32_e32 v241, v23
	v_lshl_add_u64 v[244:245], v[20:21], 0, v[246:247]
	v_mul_f32_e32 v20, v12, v12
	v_fmac_f32_e32 v20, v13, v13
	v_pk_fma_f32 v[10:11], v[10:11], 0.5, v[42:43] op_sel_hi:[1,0,1]
	v_pk_fma_f32 v[8:9], v[8:9], 0.5, v[40:41] op_sel_hi:[1,0,1]
	v_fmac_f32_e32 v20, v14, v14
	global_store_dwordx4 v[18:19], v[8:11], off offset:64
	v_or_b32_e32 v12, 32, v16
	v_mov_b32_e32 v13, v17
	v_cvt_pk_bf16_f32 v14, v8, v9
	v_mul_f32_e32 v8, v8, v8
	v_lshl_add_u64 v[12:13], s[4:5], 0, v[12:13]
	v_fmac_f32_e32 v8, v9, v9
	v_pk_fma_f32 v[6:7], v[6:7], 0.5, v[38:39] op_sel_hi:[1,0,1]
	v_pk_fma_f32 v[4:5], v[4:5], 0.5, v[36:37] op_sel_hi:[1,0,1]
	v_fmac_f32_e32 v20, v15, v15
	v_cvt_pk_bf16_f32 v15, v10, v11
	v_mov_b32_e32 v242, v14
	v_mov_b32_e32 v243, v15
	s_nop 1
	v_permlane16_swap_b32 v240, v242
	v_permlane16_swap_b32 v241, v243
	global_store_dwordx4 v[244:245], v[240:243], off
	v_fmac_f32_e32 v8, v10, v10
	global_store_dwordx4 v[18:19], v[4:7], off offset:512
	v_cvt_pk_bf16_f32 v10, v4, v5
	v_fmac_f32_e32 v8, v11, v11
	v_add_f32_e32 v11, v20, v8
	v_mul_f32_e32 v4, v4, v4
	v_fmac_f32_e32 v4, v5, v5
	v_fmac_f32_e32 v4, v6, v6
	v_fmac_f32_e32 v4, v7, v7
	v_add_f32_e32 v11, v11, v4
	v_pk_fma_f32 v[4:5], v[2:3], 0.5, v[34:35] op_sel_hi:[1,0,1]
	v_pk_fma_f32 v[2:3], v[0:1], 0.5, v[32:33] op_sel_hi:[1,0,1]
	v_or_b32_e32 v8, 0x100, v16
	v_mul_f32_e32 v0, v2, v2
	v_fmac_f32_e32 v0, v3, v3
	v_fmac_f32_e32 v0, v4, v4
	v_fmac_f32_e32 v0, v5, v5
	v_add_f32_e32 v0, v11, v0
	ds_bpermute_b32 v1, v192, v0
	v_mov_b32_e32 v9, v17
	v_or_b32_e32 v16, 0x120, v16
	v_lshl_add_u64 v[8:9], s[4:5], 0, v[8:9]
	v_cvt_pk_bf16_f32 v11, v6, v7
	s_waitcnt lgkmcnt(0)
	v_add_f32_e32 v0, v0, v1
	ds_bpermute_b32 v1, v116, v0
	v_lshl_add_u64 v[6:7], s[4:5], 0, v[16:17]
	s_nop 1
	v_mov_b32_e32 v240, v10
	v_mov_b32_e32 v241, v11
	v_lshl_add_u64 v[244:245], v[8:9], 0, v[246:247]
	global_store_dwordx4 v[18:19], v[2:5], off offset:576
	s_nop 1
	v_cvt_pk_bf16_f32 v2, v2, v3
	v_cvt_pk_bf16_f32 v3, v4, v5
	v_mov_b32_e32 v242, v2
	v_mov_b32_e32 v243, v3
	s_nop 1
	v_permlane16_swap_b32 v240, v242
	v_permlane16_swap_b32 v241, v243
	global_store_dwordx4 v[244:245], v[240:243], off
	s_and_saveexec_b64 s[28:29], s[6:7]
	s_cbranch_execz .LBB0_1800
	v_lshlrev_b64 v[2:3], 6, v[48:49]
	v_lshl_add_u64 v[2:3], s[14:15], 0, v[2:3]
	v_lshl_add_u64 v[2:3], s[26:27], 2, v[2:3]
	s_lshl_b32 s18, s53, 2
	v_lshl_add_u64 v[2:3], v[2:3], 0, s[18:19]
	s_waitcnt lgkmcnt(0)
	v_add_f32_e32 v0, v0, v1
	flat_store_dword v[2:3], v0
	s_branch .LBB0_1800

.LBB0_2164:
	ds_read_b128 v[128:131], v170
	ds_read_b128 v[132:135], v171
	ds_read_b128 v[136:139], v172
	ds_read_b128 v[140:143], v173
	s_add_u32 s34, s30, 0xfffc0080
	s_addc_u32 s35, s31, -1
	s_cmp_eq_u32 s67, 12
	s_cselect_b32 s37, s23, s35
	s_cselect_b32 s36, s29, s34
	s_cselect_b32 s35, s21, s66
	s_cselect_b32 s34, s64, s65
	s_mov_b32 m0, s61
	v_lshl_add_u64 v[212:213], s[30:31], 0, v[156:157]
	ds_read_b128 v[162:165], v151
	ds_read_b128 v[166:169], v151 offset:1024
	ds_read_b128 v[188:191], v151 offset:2048
	ds_read_b128 v[192:195], v151 offset:3072
	ds_read_b128 v[196:199], v151 offset:4096
	ds_read_b128 v[200:203], v151 offset:5120
	ds_read_b128 v[204:207], v151 offset:6144
	ds_read_b128 v[208:211], v151 offset:7168
	global_load_lds_dwordx4 v[212:213], off
	v_lshl_add_u64 v[212:213], s[30:31], 0, v[154:155]
	s_mov_b32 m0, s62
	s_nop 0
	global_load_lds_dwordx4 v[212:213], off
	s_waitcnt lgkmcnt(8)
	s_barrier
	s_waitcnt lgkmcnt(0)
	s_setprio 1
	s_waitcnt lgkmcnt(0)
	v_mfma_f32_16x16x32_bf16 v[124:127], v[128:131], v[162:165], v[124:127]
	v_mfma_f32_16x16x32_bf16 v[120:123], v[136:139], v[162:165], v[120:123]
	v_mfma_f32_16x16x32_bf16 v[108:111], v[128:131], v[188:191], v[108:111]
	v_mfma_f32_16x16x32_bf16 v[104:107], v[136:139], v[188:191], v[104:107]
	v_mfma_f32_16x16x32_bf16 v[92:95], v[128:131], v[196:199], v[92:95]
	v_mfma_f32_16x16x32_bf16 v[88:91], v[136:139], v[196:199], v[88:91]
	v_mfma_f32_16x16x32_bf16 v[76:79], v[128:131], v[204:207], v[76:79]
	v_mfma_f32_16x16x32_bf16 v[72:75], v[136:139], v[204:207], v[72:75]
	v_mfma_f32_16x16x32_bf16 v[124:127], v[132:135], v[166:169], v[124:127]
	v_mfma_f32_16x16x32_bf16 v[120:123], v[140:143], v[166:169], v[120:123]
	v_mfma_f32_16x16x32_bf16 v[108:111], v[132:135], v[192:195], v[108:111]
	v_mfma_f32_16x16x32_bf16 v[104:107], v[140:143], v[192:195], v[104:107]
	v_mfma_f32_16x16x32_bf16 v[92:95], v[132:135], v[200:203], v[92:95]
	v_mfma_f32_16x16x32_bf16 v[88:91], v[140:143], v[200:203], v[88:91]
	v_mfma_f32_16x16x32_bf16 v[76:79], v[132:135], v[208:211], v[76:79]
	v_mfma_f32_16x16x32_bf16 v[72:75], v[140:143], v[208:211], v[72:75]
	s_setprio 0
	s_barrier
	s_mov_b32 m0, s46
	v_lshl_add_u64 v[228:229], s[34:35], 0, v[144:145]
	ds_read_b128 v[212:215], v174
	ds_read_b128 v[216:219], v175
	ds_read_b128 v[220:223], v177
	ds_read_b128 v[224:227], v178
	global_load_lds_dwordx4 v[228:229], off
	v_lshl_add_u64 v[230:231], s[34:35], 0, v[146:147]
	s_mov_b32 m0, s47
	s_nop 0
	global_load_lds_dwordx4 v[230:231], off
	s_barrier
	s_waitcnt lgkmcnt(0)
	s_setprio 1
	s_waitcnt lgkmcnt(0)
	v_mfma_f32_16x16x32_bf16 v[116:119], v[212:215], v[162:165], v[116:119]
	v_mfma_f32_16x16x32_bf16 v[112:115], v[220:223], v[162:165], v[112:115]
	v_mfma_f32_16x16x32_bf16 v[100:103], v[212:215], v[188:191], v[100:103]
	v_mfma_f32_16x16x32_bf16 v[96:99], v[220:223], v[188:191], v[96:99]
	v_mfma_f32_16x16x32_bf16 v[84:87], v[212:215], v[196:199], v[84:87]
	v_mfma_f32_16x16x32_bf16 v[80:83], v[220:223], v[196:199], v[80:83]
	v_mfma_f32_16x16x32_bf16 v[68:71], v[212:215], v[204:207], v[68:71]
	v_mfma_f32_16x16x32_bf16 v[64:67], v[220:223], v[204:207], v[64:67]
	v_mfma_f32_16x16x32_bf16 v[116:119], v[216:219], v[166:169], v[116:119]
	v_mfma_f32_16x16x32_bf16 v[112:115], v[224:227], v[166:169], v[112:115]
	v_mfma_f32_16x16x32_bf16 v[100:103], v[216:219], v[192:195], v[100:103]
	v_mfma_f32_16x16x32_bf16 v[96:99], v[224:227], v[192:195], v[96:99]
	v_mfma_f32_16x16x32_bf16 v[84:87], v[216:219], v[200:203], v[84:87]
	v_mfma_f32_16x16x32_bf16 v[80:83], v[224:227], v[200:203], v[80:83]
	v_mfma_f32_16x16x32_bf16 v[68:71], v[216:219], v[208:211], v[68:71]
	v_mfma_f32_16x16x32_bf16 v[64:67], v[224:227], v[208:211], v[64:67]
	s_setprio 0
	s_mov_b32 m0, s45
	v_lshl_add_u64 v[232:233], s[36:37], 0, v[144:145]
	s_barrier
	ds_read_b128 v[162:165], v151 offset:16384
	ds_read_b128 v[166:169], v151 offset:17408
	ds_read_b128 v[188:191], v151 offset:18432
	ds_read_b128 v[192:195], v151 offset:19456
	ds_read_b128 v[196:199], v151 offset:20480
	ds_read_b128 v[200:203], v151 offset:21504
	ds_read_b128 v[204:207], v151 offset:22528
	ds_read_b128 v[208:211], v151 offset:23552
	global_load_lds_dwordx4 v[232:233], off
	v_lshl_add_u64 v[234:235], s[36:37], 0, v[146:147]
	s_mov_b32 m0, s48
	s_nop 0
	global_load_lds_dwordx4 v[234:235], off
	s_barrier
	s_waitcnt lgkmcnt(0)
	s_setprio 1
	s_waitcnt lgkmcnt(0)
	v_mfma_f32_16x16x32_bf16 v[60:63], v[128:131], v[162:165], v[60:63]
	v_mfma_f32_16x16x32_bf16 v[56:59], v[136:139], v[162:165], v[56:59]
	v_mfma_f32_16x16x32_bf16 v[44:47], v[128:131], v[188:191], v[44:47]
	v_mfma_f32_16x16x32_bf16 v[40:43], v[136:139], v[188:191], v[40:43]
	v_mfma_f32_16x16x32_bf16 v[28:31], v[128:131], v[196:199], v[28:31]
	v_mfma_f32_16x16x32_bf16 v[24:27], v[136:139], v[196:199], v[24:27]
	v_mfma_f32_16x16x32_bf16 v[12:15], v[128:131], v[204:207], v[12:15]
	v_mfma_f32_16x16x32_bf16 v[8:11], v[136:139], v[204:207], v[8:11]
	v_mfma_f32_16x16x32_bf16 v[60:63], v[132:135], v[166:169], v[60:63]
	v_mfma_f32_16x16x32_bf16 v[56:59], v[140:143], v[166:169], v[56:59]
	v_mfma_f32_16x16x32_bf16 v[44:47], v[132:135], v[192:195], v[44:47]
	v_mfma_f32_16x16x32_bf16 v[40:43], v[140:143], v[192:195], v[40:43]
	v_mfma_f32_16x16x32_bf16 v[28:31], v[132:135], v[200:203], v[28:31]
	v_mfma_f32_16x16x32_bf16 v[24:27], v[140:143], v[200:203], v[24:27]
	v_mfma_f32_16x16x32_bf16 v[12:15], v[132:135], v[208:211], v[12:15]
	v_mfma_f32_16x16x32_bf16 v[8:11], v[140:143], v[208:211], v[8:11]
	s_setprio 0
	s_barrier
	s_add_u32 s68, s34, 0x40000
	s_addc_u32 s69, s35, 0
	s_mov_b32 m0, s49
	v_lshl_add_u64 v[128:129], s[68:69], 0, v[144:145]
	global_load_lds_dwordx4 v[128:129], off
	v_lshl_add_u64 v[128:129], s[68:69], 0, v[146:147]
	s_mov_b32 m0, s50
	s_nop 0
	global_load_lds_dwordx4 v[128:129], off
	s_waitcnt vmcnt(6)
	s_barrier
	s_setprio 1
	v_mfma_f32_16x16x32_bf16 v[52:55], v[212:215], v[162:165], v[52:55]
	v_mfma_f32_16x16x32_bf16 v[48:51], v[220:223], v[162:165], v[48:51]
	v_mfma_f32_16x16x32_bf16 v[36:39], v[212:215], v[188:191], v[36:39]
	v_mfma_f32_16x16x32_bf16 v[32:35], v[220:223], v[188:191], v[32:35]
	v_mfma_f32_16x16x32_bf16 v[20:23], v[212:215], v[196:199], v[20:23]
	v_mfma_f32_16x16x32_bf16 v[16:19], v[220:223], v[196:199], v[16:19]
	v_mfma_f32_16x16x32_bf16 v[4:7], v[212:215], v[204:207], v[4:7]
	v_mfma_f32_16x16x32_bf16 v[0:3], v[220:223], v[204:207], v[0:3]
	v_mfma_f32_16x16x32_bf16 v[52:55], v[216:219], v[166:169], v[52:55]
	v_mfma_f32_16x16x32_bf16 v[48:51], v[224:227], v[166:169], v[48:51]
	v_mfma_f32_16x16x32_bf16 v[36:39], v[216:219], v[192:195], v[36:39]
	v_mfma_f32_16x16x32_bf16 v[32:35], v[224:227], v[192:195], v[32:35]
	v_mfma_f32_16x16x32_bf16 v[20:23], v[216:219], v[200:203], v[20:23]
	v_mfma_f32_16x16x32_bf16 v[16:19], v[224:227], v[200:203], v[16:19]
	v_mfma_f32_16x16x32_bf16 v[4:7], v[216:219], v[208:211], v[4:7]
	v_mfma_f32_16x16x32_bf16 v[0:3], v[224:227], v[208:211], v[0:3]
	s_setprio 0
	s_barrier
	ds_read_b128 v[128:131], v179
	ds_read_b128 v[132:135], v180
	ds_read_b128 v[136:139], v181
	ds_read_b128 v[140:143], v182
	s_add_u32 s36, s36, 0x40000
	s_addc_u32 s37, s37, 0
	s_mov_b32 m0, s51
	v_lshl_add_u64 v[212:213], s[36:37], 0, v[144:145]
	ds_read_b128 v[162:165], v151 offset:32768
	ds_read_b128 v[166:169], v151 offset:33792
	ds_read_b128 v[188:191], v151 offset:34816
	ds_read_b128 v[192:195], v151 offset:35840
	ds_read_b128 v[196:199], v151 offset:36864
	ds_read_b128 v[200:203], v151 offset:37888
	ds_read_b128 v[204:207], v151 offset:38912
	ds_read_b128 v[208:211], v151 offset:39936
	global_load_lds_dwordx4 v[212:213], off
	v_lshl_add_u64 v[212:213], s[36:37], 0, v[146:147]
	s_mov_b32 m0, s52
	s_nop 0
	global_load_lds_dwordx4 v[212:213], off
	s_waitcnt lgkmcnt(8)
	s_barrier
	s_waitcnt lgkmcnt(0)
	s_setprio 1
	s_waitcnt lgkmcnt(0)
	v_mfma_f32_16x16x32_bf16 v[124:127], v[128:131], v[162:165], v[124:127]
	v_mfma_f32_16x16x32_bf16 v[120:123], v[136:139], v[162:165], v[120:123]
	v_mfma_f32_16x16x32_bf16 v[108:111], v[128:131], v[188:191], v[108:111]
	v_mfma_f32_16x16x32_bf16 v[104:107], v[136:139], v[188:191], v[104:107]
	v_mfma_f32_16x16x32_bf16 v[92:95], v[128:131], v[196:199], v[92:95]
	v_mfma_f32_16x16x32_bf16 v[88:91], v[136:139], v[196:199], v[88:91]
	v_mfma_f32_16x16x32_bf16 v[76:79], v[128:131], v[204:207], v[76:79]
	v_mfma_f32_16x16x32_bf16 v[72:75], v[136:139], v[204:207], v[72:75]
	v_mfma_f32_16x16x32_bf16 v[124:127], v[132:135], v[166:169], v[124:127]
	v_mfma_f32_16x16x32_bf16 v[120:123], v[140:143], v[166:169], v[120:123]
	v_mfma_f32_16x16x32_bf16 v[108:111], v[132:135], v[192:195], v[108:111]
	v_mfma_f32_16x16x32_bf16 v[104:107], v[140:143], v[192:195], v[104:107]
	v_mfma_f32_16x16x32_bf16 v[92:95], v[132:135], v[200:203], v[92:95]
	v_mfma_f32_16x16x32_bf16 v[88:91], v[140:143], v[200:203], v[88:91]
	v_mfma_f32_16x16x32_bf16 v[76:79], v[132:135], v[208:211], v[76:79]
	v_mfma_f32_16x16x32_bf16 v[72:75], v[140:143], v[208:211], v[72:75]
	s_setprio 0
	s_barrier
	s_mov_b32 m0, s54
	v_lshl_add_u64 v[228:229], v[228:229], 0, s[10:11]
	ds_read_b128 v[212:215], v183
	ds_read_b128 v[216:219], v184
	ds_read_b128 v[220:223], v185
	ds_read_b128 v[224:227], v186
	global_load_lds_dwordx4 v[228:229], off
	v_lshl_add_u64 v[228:229], v[230:231], 0, s[10:11]
	s_mov_b32 m0, s55
	s_nop 0
	global_load_lds_dwordx4 v[228:229], off
	s_barrier
	s_waitcnt lgkmcnt(0)
	s_setprio 1
	s_waitcnt lgkmcnt(0)
	v_mfma_f32_16x16x32_bf16 v[116:119], v[212:215], v[162:165], v[116:119]
	v_mfma_f32_16x16x32_bf16 v[112:115], v[220:223], v[162:165], v[112:115]
	v_mfma_f32_16x16x32_bf16 v[100:103], v[212:215], v[188:191], v[100:103]
	v_mfma_f32_16x16x32_bf16 v[96:99], v[220:223], v[188:191], v[96:99]
	v_mfma_f32_16x16x32_bf16 v[84:87], v[212:215], v[196:199], v[84:87]
	v_mfma_f32_16x16x32_bf16 v[80:83], v[220:223], v[196:199], v[80:83]
	v_mfma_f32_16x16x32_bf16 v[68:71], v[212:215], v[204:207], v[68:71]
	v_mfma_f32_16x16x32_bf16 v[64:67], v[220:223], v[204:207], v[64:67]
	v_mfma_f32_16x16x32_bf16 v[116:119], v[216:219], v[166:169], v[116:119]
	v_mfma_f32_16x16x32_bf16 v[112:115], v[224:227], v[166:169], v[112:115]
	v_mfma_f32_16x16x32_bf16 v[100:103], v[216:219], v[192:195], v[100:103]
	v_mfma_f32_16x16x32_bf16 v[96:99], v[224:227], v[192:195], v[96:99]
	v_mfma_f32_16x16x32_bf16 v[84:87], v[216:219], v[200:203], v[84:87]
	v_mfma_f32_16x16x32_bf16 v[80:83], v[224:227], v[200:203], v[80:83]
	v_mfma_f32_16x16x32_bf16 v[68:71], v[216:219], v[208:211], v[68:71]
	v_mfma_f32_16x16x32_bf16 v[64:67], v[224:227], v[208:211], v[64:67]
	s_setprio 0
	s_mov_b32 m0, s56
	v_lshl_add_u64 v[228:229], v[232:233], 0, s[10:11]
	s_barrier
	ds_read_b128 v[162:165], v151 offset:49152
	ds_read_b128 v[166:169], v151 offset:50176
	ds_read_b128 v[188:191], v151 offset:51200
	ds_read_b128 v[192:195], v151 offset:52224
	ds_read_b128 v[196:199], v151 offset:53248
	ds_read_b128 v[200:203], v151 offset:54272
	ds_read_b128 v[204:207], v151 offset:55296
	ds_read_b128 v[208:211], v151 offset:56320
	global_load_lds_dwordx4 v[228:229], off
	v_lshl_add_u64 v[228:229], v[234:235], 0, s[10:11]
	s_mov_b32 m0, s57
	s_nop 0
	global_load_lds_dwordx4 v[228:229], off
	s_barrier
	s_waitcnt lgkmcnt(0)
	s_setprio 1
	s_waitcnt lgkmcnt(0)
	v_mfma_f32_16x16x32_bf16 v[60:63], v[128:131], v[162:165], v[60:63]
	v_mfma_f32_16x16x32_bf16 v[56:59], v[136:139], v[162:165], v[56:59]
	v_mfma_f32_16x16x32_bf16 v[44:47], v[128:131], v[188:191], v[44:47]
	v_mfma_f32_16x16x32_bf16 v[40:43], v[136:139], v[188:191], v[40:43]
	v_mfma_f32_16x16x32_bf16 v[28:31], v[128:131], v[196:199], v[28:31]
	v_mfma_f32_16x16x32_bf16 v[24:27], v[136:139], v[196:199], v[24:27]
	v_mfma_f32_16x16x32_bf16 v[12:15], v[128:131], v[204:207], v[12:15]
	v_mfma_f32_16x16x32_bf16 v[8:11], v[136:139], v[204:207], v[8:11]
	v_mfma_f32_16x16x32_bf16 v[60:63], v[132:135], v[166:169], v[60:63]
	v_mfma_f32_16x16x32_bf16 v[56:59], v[140:143], v[166:169], v[56:59]
	v_mfma_f32_16x16x32_bf16 v[44:47], v[132:135], v[192:195], v[44:47]
	v_mfma_f32_16x16x32_bf16 v[40:43], v[140:143], v[192:195], v[40:43]
	v_mfma_f32_16x16x32_bf16 v[28:31], v[132:135], v[200:203], v[28:31]
	v_mfma_f32_16x16x32_bf16 v[24:27], v[140:143], v[200:203], v[24:27]
	v_mfma_f32_16x16x32_bf16 v[12:15], v[132:135], v[208:211], v[12:15]
	v_mfma_f32_16x16x32_bf16 v[8:11], v[140:143], v[208:211], v[8:11]
	s_setprio 0
	s_barrier
	s_add_u32 s34, s34, 0x40080
	s_addc_u32 s35, s35, 0
	s_mov_b32 m0, s58
	v_lshl_add_u64 v[128:129], s[34:35], 0, v[144:145]
	global_load_lds_dwordx4 v[128:129], off
	v_lshl_add_u64 v[128:129], s[34:35], 0, v[146:147]
	s_mov_b32 m0, s59
	s_nop 0
	global_load_lds_dwordx4 v[128:129], off
	s_waitcnt vmcnt(6)
	s_barrier
	s_setprio 1
	v_mfma_f32_16x16x32_bf16 v[52:55], v[212:215], v[162:165], v[52:55]
	v_mfma_f32_16x16x32_bf16 v[48:51], v[220:223], v[162:165], v[48:51]
	v_mfma_f32_16x16x32_bf16 v[36:39], v[212:215], v[188:191], v[36:39]
	v_mfma_f32_16x16x32_bf16 v[32:35], v[220:223], v[188:191], v[32:35]
	v_mfma_f32_16x16x32_bf16 v[20:23], v[212:215], v[196:199], v[20:23]
	v_mfma_f32_16x16x32_bf16 v[16:19], v[220:223], v[196:199], v[16:19]
	v_mfma_f32_16x16x32_bf16 v[4:7], v[212:215], v[204:207], v[4:7]
	v_mfma_f32_16x16x32_bf16 v[0:3], v[220:223], v[204:207], v[0:3]
	v_mfma_f32_16x16x32_bf16 v[52:55], v[216:219], v[166:169], v[52:55]
	v_mfma_f32_16x16x32_bf16 v[48:51], v[224:227], v[166:169], v[48:51]
	v_mfma_f32_16x16x32_bf16 v[36:39], v[216:219], v[192:195], v[36:39]
	v_mfma_f32_16x16x32_bf16 v[32:35], v[224:227], v[192:195], v[32:35]
	v_mfma_f32_16x16x32_bf16 v[20:23], v[216:219], v[200:203], v[20:23]
	v_mfma_f32_16x16x32_bf16 v[16:19], v[224:227], v[200:203], v[16:19]
	v_mfma_f32_16x16x32_bf16 v[4:7], v[216:219], v[208:211], v[4:7]
	v_mfma_f32_16x16x32_bf16 v[0:3], v[224:227], v[208:211], v[0:3]
	s_setprio 0
	s_add_i32 s67, s67, 2
	s_add_u32 s65, s65, 0x100
	s_addc_u32 s66, s66, 0
	s_add_u32 s30, s30, 0x100
	s_addc_u32 s31, s31, 0
	s_cmp_gt_u32 s67, 13
	s_barrier
	s_cbranch_scc0 .LBB0_2164
	s_ashr_i32 s29, s28, 31
	s_lshl_b64 s[28:29], s[28:29], 8
	s_lshl_b32 s30, s12, 8
	v_lshl_add_u64 v[164:165], s[28:29], 0, v[148:149]
	s_ashr_i32 s31, s30, 31
	v_lshl_add_u64 v[166:167], s[30:31], 2, v[152:153]
	v_lshlrev_b64 v[128:129], 12, v[164:165]
	v_lshl_add_u64 v[128:129], v[166:167], 0, v[128:129]
	global_load_dwordx4 v[190:193], v[128:129], off
	global_load_dwordx4 v[194:197], v[128:129], off offset:64
	global_load_dwordx4 v[198:201], v[128:129], off offset:512
	global_load_dwordx4 v[202:205], v[128:129], off offset:576
	v_or_b32_e32 v168, 16, v164
	v_mov_b32_e32 v169, v165
	v_lshlrev_b64 v[128:129], 12, v[168:169]
	v_lshl_add_u64 v[128:129], v[166:167], 0, v[128:129]
	global_load_dwordx4 v[140:143], v[128:129], off
	global_load_dwordx4 v[136:139], v[128:129], off offset:64
	global_load_dwordx4 v[132:135], v[128:129], off offset:512
	s_nop 0
	global_load_dwordx4 v[128:131], v[128:129], off offset:576
	v_and_b32_e32 v163, 64, v187
	v_xor_b32_e32 v188, 16, v187
	v_add_u32_e32 v206, 64, v163
	v_xor_b32_e32 v189, 32, v187
	v_cmp_lt_i32_e32 vcc, v188, v206
	v_or_b32_e32 v162, s30, v150
	v_mov_b32_e32 v163, s31
	v_cndmask_b32_e32 v188, v187, v188, vcc
	v_cmp_lt_i32_e32 vcc, v189, v206
	v_lshlrev_b64 v[206:207], 10, v[164:165]
	v_lshl_add_u64 v[206:207], v[206:207], 0, v[162:163]
	v_lshl_add_u64 v[208:209], v[206:207], 2, s[78:79]
	s_waitcnt vmcnt(0)
	v_lshlrev_b64 v[206:207], 1, v[206:207]
	v_lshl_add_u64 v[210:211], s[2:3], 0, v[206:207]
	v_lshlrev_b32_e32 v188, 2, v188
	v_or_b32_e32 v212, 32, v206
	v_mov_b32_e32 v213, v207
	v_cndmask_b32_e32 v189, v187, v189, vcc
	v_or_b32_e32 v214, 0x100, v206
	v_mov_b32_e32 v215, v207
	v_lshl_add_u64 v[212:213], s[2:3], 0, v[212:213]
	v_lshl_add_u64 v[214:215], s[2:3], 0, v[214:215]
	s_lshl_b32 s28, s12, 2
	v_or_b32_e32 v206, 0x120, v206
	s_ashr_i32 s29, s28, 31
	s_waitcnt vmcnt(0)
	v_pk_add_f32 v[126:127], v[126:127], v[192:193]
	v_pk_add_f32 v[124:125], v[124:125], v[190:191]
	v_pk_add_f32 v[120:121], v[120:121], v[194:195]
	v_pk_add_f32 v[122:123], v[122:123], v[196:197]
	v_pk_add_f32 v[116:117], v[116:117], v[198:199]
	v_pk_add_f32 v[190:191], v[112:113], v[202:203]
	global_store_dwordx4 v[208:209], v[124:127], off
	v_cvt_pk_bf16_f32 v112, v124, v125
	v_mul_f32_e32 v196, v120, v120
	v_mul_f32_e32 v197, v116, v116
	v_mul_f32_e32 v124, v124, v124
	v_fmac_f32_e32 v124, v125, v125
	v_fmac_f32_e32 v196, v121, v121
	v_pk_add_f32 v[118:119], v[118:119], v[200:201]
	v_mul_f32_e32 v198, v190, v190
	v_fmac_f32_e32 v197, v117, v117
	v_fmac_f32_e32 v124, v126, v126
	v_fmac_f32_e32 v196, v122, v122
	v_pk_add_f32 v[192:193], v[114:115], v[204:205]
	v_fmac_f32_e32 v198, v191, v191
	v_fmac_f32_e32 v197, v118, v118
	v_fmac_f32_e32 v124, v127, v127
	v_fmac_f32_e32 v196, v123, v123
	v_cvt_pk_bf16_f32 v113, v126, v127
	v_bfe_u32 v246, v176, 4, 1
	v_mul_u32_u24_e32 v246, 24, v246
	v_mov_b32_e32 v247, 0
	s_nop 1
	v_mov_b32_e32 v240, v112
	v_mov_b32_e32 v241, v113
	v_lshl_add_u64 v[244:245], v[210:211], 0, v[246:247]
	v_fmac_f32_e32 v198, v192, v192
	v_fmac_f32_e32 v197, v119, v119
	v_add_f32_e32 v112, v124, v196
	v_fmac_f32_e32 v198, v193, v193
	v_add_f32_e32 v112, v112, v197
	v_add_f32_e32 v112, v112, v198
	ds_bpermute_b32 v113, v188, v112
	v_cvt_pk_bf16_f32 v114, v120, v121
	v_cvt_pk_bf16_f32 v115, v122, v123
	v_cvt_pk_bf16_f32 v194, v116, v117
	v_cvt_pk_bf16_f32 v195, v118, v119
	global_store_dwordx4 v[208:209], v[120:123], off offset:64
	v_mov_b32_e32 v242, v114
	v_mov_b32_e32 v243, v115
	s_nop 1
	v_permlane16_swap_b32 v240, v242
	v_permlane16_swap_b32 v241, v243
	global_store_dwordx4 v[244:245], v[240:243], off
	global_store_dwordx4 v[208:209], v[116:119], off offset:512
	s_nop 1
	v_mov_b32_e32 v240, v194
	v_mov_b32_e32 v241, v195
	v_lshl_add_u64 v[244:245], v[214:215], 0, v[246:247]
	global_store_dwordx4 v[208:209], v[190:193], off offset:576
	s_waitcnt lgkmcnt(0)
	v_add_f32_e32 v112, v112, v113
	v_lshlrev_b32_e32 v116, 2, v189
	ds_bpermute_b32 v113, v116, v112
	v_lshl_add_u64 v[114:115], s[2:3], 0, v[206:207]
	v_cvt_pk_bf16_f32 v118, v190, v191
	v_cvt_pk_bf16_f32 v119, v192, v193
	v_mov_b32_e32 v242, v118
	v_mov_b32_e32 v243, v119
	s_nop 1
	v_permlane16_swap_b32 v240, v242
	v_permlane16_swap_b32 v241, v243
	global_store_dwordx4 v[244:245], v[240:243], off
	s_and_saveexec_b64 s[30:31], s[6:7]
	s_cbranch_execz .LBB0_2167
	v_lshlrev_b64 v[114:115], 6, v[164:165]
	v_lshl_add_u64 v[114:115], s[4:5], 0, v[114:115]
	v_lshl_add_u64 v[114:115], s[28:29], 2, v[114:115]
	s_lshl_b32 s12, s53, 2
	v_lshl_add_u64 v[114:115], v[114:115], 0, s[12:13]
	s_waitcnt lgkmcnt(0)
	v_add_f32_e32 v112, v112, v113
	flat_store_dword v[114:115], v112
.LBB0_2167:
	s_or_b64 exec, exec, s[30:31]
	s_waitcnt lgkmcnt(0)
	v_lshlrev_b64 v[112:113], 10, v[168:169]
	v_lshl_add_u64 v[112:113], v[112:113], 0, v[162:163]
	v_pk_add_f32 v[108:109], v[108:109], v[140:141]
	v_lshl_add_u64 v[114:115], v[112:113], 2, s[78:79]
	v_lshlrev_b64 v[112:113], 1, v[112:113]
	v_mul_f32_e32 v117, v108, v108
	v_pk_add_f32 v[110:111], v[110:111], v[142:143]
	v_lshl_add_u64 v[118:119], s[2:3], 0, v[112:113]
	v_fmac_f32_e32 v117, v109, v109
	v_pk_add_f32 v[106:107], v[106:107], v[138:139]
	v_pk_add_f32 v[104:105], v[104:105], v[136:137]
	global_store_dwordx4 v[114:115], v[108:111], off
	v_cvt_pk_bf16_f32 v120, v108, v109
	v_cvt_pk_bf16_f32 v121, v110, v111
	s_nop 1
	v_mov_b32_e32 v240, v120
	v_mov_b32_e32 v241, v121
	v_lshl_add_u64 v[244:245], v[118:119], 0, v[246:247]
	v_fmac_f32_e32 v117, v110, v110
	global_store_dwordx4 v[114:115], v[104:107], off offset:64
	v_or_b32_e32 v108, 32, v112
	v_mov_b32_e32 v109, v113
	v_cvt_pk_bf16_f32 v110, v104, v105
	v_mul_f32_e32 v104, v104, v104
	v_lshl_add_u64 v[108:109], s[2:3], 0, v[108:109]
	v_fmac_f32_e32 v104, v105, v105
	v_pk_add_f32 v[102:103], v[102:103], v[134:135]
	v_pk_add_f32 v[100:101], v[100:101], v[132:133]
	v_fmac_f32_e32 v117, v111, v111
	v_cvt_pk_bf16_f32 v111, v106, v107
	v_mov_b32_e32 v242, v110
	v_mov_b32_e32 v243, v111
	s_nop 1
	v_permlane16_swap_b32 v240, v242
	v_permlane16_swap_b32 v241, v243
	global_store_dwordx4 v[244:245], v[240:243], off
	v_fmac_f32_e32 v104, v106, v106
	global_store_dwordx4 v[114:115], v[100:103], off offset:512
	v_cvt_pk_bf16_f32 v106, v100, v101
	v_fmac_f32_e32 v104, v107, v107
	v_add_f32_e32 v107, v117, v104
	v_mul_f32_e32 v100, v100, v100
	v_fmac_f32_e32 v100, v101, v101
	v_fmac_f32_e32 v100, v102, v102
	v_fmac_f32_e32 v100, v103, v103
	v_add_f32_e32 v107, v107, v100
	v_pk_add_f32 v[100:101], v[98:99], v[130:131]
	v_pk_add_f32 v[98:99], v[96:97], v[128:129]
	v_or_b32_e32 v104, 0x100, v112
	v_mul_f32_e32 v96, v98, v98
	v_fmac_f32_e32 v96, v99, v99
	v_fmac_f32_e32 v96, v100, v100
	v_fmac_f32_e32 v96, v101, v101
	v_add_f32_e32 v96, v107, v96
	ds_bpermute_b32 v97, v188, v96
	v_mov_b32_e32 v105, v113
	v_or_b32_e32 v112, 0x120, v112
	v_lshl_add_u64 v[104:105], s[2:3], 0, v[104:105]
	v_cvt_pk_bf16_f32 v107, v102, v103
	s_waitcnt lgkmcnt(0)
	v_add_f32_e32 v96, v96, v97
	ds_bpermute_b32 v97, v116, v96
	v_lshl_add_u64 v[102:103], s[2:3], 0, v[112:113]
	s_nop 1
	v_mov_b32_e32 v240, v106
	v_mov_b32_e32 v241, v107
	v_lshl_add_u64 v[244:245], v[104:105], 0, v[246:247]
	global_store_dwordx4 v[114:115], v[98:101], off offset:576
	s_nop 1
	v_cvt_pk_bf16_f32 v98, v98, v99
	v_cvt_pk_bf16_f32 v99, v100, v101
	v_mov_b32_e32 v242, v98
	v_mov_b32_e32 v243, v99
	s_nop 1
	v_permlane16_swap_b32 v240, v242
	v_permlane16_swap_b32 v241, v243
	global_store_dwordx4 v[244:245], v[240:243], off
	s_and_saveexec_b64 s[30:31], s[6:7]
	s_cbranch_execz .LBB0_2169
	v_lshlrev_b64 v[98:99], 6, v[168:169]
	v_lshl_add_u64 v[98:99], s[4:5], 0, v[98:99]
	v_lshl_add_u64 v[98:99], s[28:29], 2, v[98:99]
	s_lshl_b32 s12, s53, 2
	v_lshl_add_u64 v[98:99], v[98:99], 0, s[12:13]
	s_waitcnt lgkmcnt(0)
	v_add_f32_e32 v96, v96, v97
	flat_store_dword v[98:99], v96
.LBB0_2169:
	s_or_b64 exec, exec, s[30:31]
	v_or_b32_e32 v114, 32, v164
	v_mov_b32_e32 v115, v165
	s_waitcnt lgkmcnt(0)
	v_lshlrev_b64 v[96:97], 12, v[114:115]
	v_lshl_add_u64 v[96:97], v[166:167], 0, v[96:97]
	global_load_dwordx4 v[118:121], v[96:97], off
	global_load_dwordx4 v[122:125], v[96:97], off offset:64
	global_load_dwordx4 v[126:129], v[96:97], off offset:512
	global_load_dwordx4 v[130:133], v[96:97], off offset:576
	v_or_b32_e32 v112, 48, v164
	v_mov_b32_e32 v113, v165
	v_lshlrev_b64 v[96:97], 12, v[112:113]
	v_lshl_add_u64 v[96:97], v[166:167], 0, v[96:97]
	global_load_dwordx4 v[108:111], v[96:97], off
	global_load_dwordx4 v[104:107], v[96:97], off offset:64
	global_load_dwordx4 v[100:103], v[96:97], off offset:512
	s_nop 0
	global_load_dwordx4 v[96:99], v[96:97], off offset:576
	v_lshlrev_b64 v[134:135], 10, v[114:115]
	v_lshl_add_u64 v[134:135], v[134:135], 0, v[162:163]
	v_lshl_add_u64 v[136:137], v[134:135], 2, s[78:79]
	v_lshlrev_b64 v[134:135], 1, v[134:135]
	v_lshl_add_u64 v[138:139], s[2:3], 0, v[134:135]
	s_waitcnt vmcnt(0)
	v_or_b32_e32 v140, 32, v134
	v_mov_b32_e32 v141, v135
	v_or_b32_e32 v142, 0x100, v134
	v_mov_b32_e32 v143, v135
	v_or_b32_e32 v134, 0x120, v134
	v_lshl_add_u64 v[140:141], s[2:3], 0, v[140:141]
	v_lshl_add_u64 v[142:143], s[2:3], 0, v[142:143]
	s_waitcnt vmcnt(0)
	v_pk_add_f32 v[92:93], v[92:93], v[118:119]
	v_pk_add_f32 v[88:89], v[88:89], v[122:123]
	v_pk_add_f32 v[84:85], v[84:85], v[126:127]
	v_mul_f32_e32 v117, v92, v92
	v_mul_f32_e32 v122, v88, v88
	v_pk_add_f32 v[94:95], v[94:95], v[120:121]
	v_pk_add_f32 v[90:91], v[90:91], v[124:125]
	v_pk_add_f32 v[118:119], v[80:81], v[130:131]
	v_mul_f32_e32 v123, v84, v84
	v_fmac_f32_e32 v117, v93, v93
	v_fmac_f32_e32 v122, v89, v89
	v_pk_add_f32 v[86:87], v[86:87], v[128:129]
	v_mul_f32_e32 v124, v118, v118
	v_fmac_f32_e32 v123, v85, v85
	v_fmac_f32_e32 v117, v94, v94
	v_fmac_f32_e32 v122, v90, v90
	v_pk_add_f32 v[120:121], v[82:83], v[132:133]
	v_cvt_pk_bf16_f32 v80, v92, v93
	v_fmac_f32_e32 v124, v119, v119
	v_fmac_f32_e32 v123, v86, v86
	v_fmac_f32_e32 v117, v95, v95
	v_fmac_f32_e32 v122, v91, v91
	global_store_dwordx4 v[136:137], v[92:95], off
	v_cvt_pk_bf16_f32 v81, v94, v95
	s_nop 1
	v_mov_b32_e32 v240, v80
	v_mov_b32_e32 v241, v81
	v_lshl_add_u64 v[244:245], v[138:139], 0, v[246:247]
	v_fmac_f32_e32 v124, v120, v120
	v_fmac_f32_e32 v123, v87, v87
	v_add_f32_e32 v80, v117, v122
	v_add_f32_e32 v80, v80, v123
	v_fmac_f32_e32 v124, v121, v121
	v_add_f32_e32 v80, v80, v124
	ds_bpermute_b32 v81, v188, v80
	v_cvt_pk_bf16_f32 v82, v88, v89
	v_cvt_pk_bf16_f32 v83, v90, v91
	v_cvt_pk_bf16_f32 v92, v84, v85
	global_store_dwordx4 v[136:137], v[88:91], off offset:64
	v_mov_b32_e32 v242, v82
	v_mov_b32_e32 v243, v83
	s_nop 1
	v_permlane16_swap_b32 v240, v242
	v_permlane16_swap_b32 v241, v243
	global_store_dwordx4 v[244:245], v[240:243], off
	s_waitcnt lgkmcnt(0)
	v_add_f32_e32 v80, v80, v81
	ds_bpermute_b32 v81, v116, v80
	v_cvt_pk_bf16_f32 v93, v86, v87
	v_lshl_add_u64 v[82:83], s[2:3], 0, v[134:135]
	global_store_dwordx4 v[136:137], v[84:87], off offset:512
	s_nop 1
	v_mov_b32_e32 v240, v92
	v_mov_b32_e32 v241, v93
	v_lshl_add_u64 v[244:245], v[142:143], 0, v[246:247]
	global_store_dwordx4 v[136:137], v[118:121], off offset:576
	v_cvt_pk_bf16_f32 v84, v118, v119
	v_cvt_pk_bf16_f32 v85, v120, v121
	v_mov_b32_e32 v242, v84
	v_mov_b32_e32 v243, v85
	s_nop 1
	v_permlane16_swap_b32 v240, v242
	v_permlane16_swap_b32 v241, v243
	global_store_dwordx4 v[244:245], v[240:243], off
	s_and_saveexec_b64 s[30:31], s[6:7]
	s_cbranch_execz .LBB0_2171
	v_lshlrev_b64 v[82:83], 6, v[114:115]
	v_lshl_add_u64 v[82:83], s[4:5], 0, v[82:83]
	v_lshl_add_u64 v[82:83], s[28:29], 2, v[82:83]
	s_lshl_b32 s12, s53, 2
	v_lshl_add_u64 v[82:83], v[82:83], 0, s[12:13]
	s_waitcnt lgkmcnt(0)
	v_add_f32_e32 v80, v80, v81
	flat_store_dword v[82:83], v80
.LBB0_2171:
	s_or_b64 exec, exec, s[30:31]
	s_waitcnt lgkmcnt(0)
	v_lshlrev_b64 v[80:81], 10, v[112:113]
	v_lshl_add_u64 v[80:81], v[80:81], 0, v[162:163]
	v_lshl_add_u64 v[82:83], v[80:81], 2, s[78:79]
	v_lshlrev_b64 v[80:81], 1, v[80:81]
	v_pk_add_f32 v[78:79], v[78:79], v[110:111]
	v_pk_add_f32 v[76:77], v[76:77], v[108:109]
	v_lshl_add_u64 v[84:85], s[2:3], 0, v[80:81]
	global_store_dwordx4 v[82:83], v[76:79], off
	v_cvt_pk_bf16_f32 v86, v76, v77
	v_cvt_pk_bf16_f32 v87, v78, v79
	s_nop 1
	v_mov_b32_e32 v240, v86
	v_mov_b32_e32 v241, v87
	v_lshl_add_u64 v[244:245], v[84:85], 0, v[246:247]
	v_mul_f32_e32 v84, v76, v76
	v_fmac_f32_e32 v84, v77, v77
	v_pk_add_f32 v[74:75], v[74:75], v[106:107]
	v_pk_add_f32 v[72:73], v[72:73], v[104:105]
	v_fmac_f32_e32 v84, v78, v78
	global_store_dwordx4 v[82:83], v[72:75], off offset:64
	v_or_b32_e32 v76, 32, v80
	v_mov_b32_e32 v77, v81
	v_cvt_pk_bf16_f32 v78, v72, v73
	v_mul_f32_e32 v72, v72, v72
	v_lshl_add_u64 v[76:77], s[2:3], 0, v[76:77]
	v_fmac_f32_e32 v72, v73, v73
	v_pk_add_f32 v[70:71], v[70:71], v[102:103]
	v_pk_add_f32 v[68:69], v[68:69], v[100:101]
	v_fmac_f32_e32 v84, v79, v79
	v_cvt_pk_bf16_f32 v79, v74, v75
	v_mov_b32_e32 v242, v78
	v_mov_b32_e32 v243, v79
	s_nop 1
	v_permlane16_swap_b32 v240, v242
	v_permlane16_swap_b32 v241, v243
	global_store_dwordx4 v[244:245], v[240:243], off
	v_fmac_f32_e32 v72, v74, v74
	global_store_dwordx4 v[82:83], v[68:71], off offset:512
	v_cvt_pk_bf16_f32 v74, v68, v69
	v_fmac_f32_e32 v72, v75, v75
	v_add_f32_e32 v75, v84, v72
	v_mul_f32_e32 v68, v68, v68
	v_fmac_f32_e32 v68, v69, v69
	v_fmac_f32_e32 v68, v70, v70
	v_fmac_f32_e32 v68, v71, v71
	v_add_f32_e32 v75, v75, v68
	v_pk_add_f32 v[68:69], v[66:67], v[98:99]
	v_pk_add_f32 v[66:67], v[64:65], v[96:97]
	v_or_b32_e32 v72, 0x100, v80
	v_mul_f32_e32 v64, v66, v66
	v_fmac_f32_e32 v64, v67, v67
	v_fmac_f32_e32 v64, v68, v68
	v_fmac_f32_e32 v64, v69, v69
	v_add_f32_e32 v64, v75, v64
	ds_bpermute_b32 v65, v188, v64
	v_mov_b32_e32 v73, v81
	v_or_b32_e32 v80, 0x120, v80
	v_lshl_add_u64 v[72:73], s[2:3], 0, v[72:73]
	v_cvt_pk_bf16_f32 v75, v70, v71
	s_waitcnt lgkmcnt(0)
	v_add_f32_e32 v64, v64, v65
	ds_bpermute_b32 v65, v116, v64
	v_lshl_add_u64 v[70:71], s[2:3], 0, v[80:81]
	s_nop 1
	v_mov_b32_e32 v240, v74
	v_mov_b32_e32 v241, v75
	v_lshl_add_u64 v[244:245], v[72:73], 0, v[246:247]
	global_store_dwordx4 v[82:83], v[66:69], off offset:576
	s_nop 1
	v_cvt_pk_bf16_f32 v66, v66, v67
	v_cvt_pk_bf16_f32 v67, v68, v69
	v_mov_b32_e32 v242, v66
	v_mov_b32_e32 v243, v67
	s_nop 1
	v_permlane16_swap_b32 v240, v242
	v_permlane16_swap_b32 v241, v243
	global_store_dwordx4 v[244:245], v[240:243], off
	s_and_saveexec_b64 s[30:31], s[6:7]
	s_cbranch_execz .LBB0_2173
	v_lshlrev_b64 v[66:67], 6, v[112:113]
	v_lshl_add_u64 v[66:67], s[4:5], 0, v[66:67]
	v_lshl_add_u64 v[66:67], s[28:29], 2, v[66:67]
	s_lshl_b32 s12, s53, 2
	v_lshl_add_u64 v[66:67], v[66:67], 0, s[12:13]
	s_waitcnt lgkmcnt(0)
	v_add_f32_e32 v64, v64, v65
	flat_store_dword v[66:67], v64
.LBB0_2173:
	s_or_b64 exec, exec, s[30:31]
	v_lshl_add_u64 v[82:83], v[164:165], 0, s[10:11]
	s_waitcnt lgkmcnt(0)
	v_lshlrev_b64 v[64:65], 12, v[82:83]
	v_lshl_add_u64 v[64:65], v[166:167], 0, v[64:65]
	global_load_dwordx4 v[84:87], v[64:65], off
	global_load_dwordx4 v[88:91], v[64:65], off offset:64
	global_load_dwordx4 v[92:95], v[64:65], off offset:512
	global_load_dwordx4 v[96:99], v[64:65], off offset:576
	v_lshl_add_u64 v[80:81], v[164:165], 0, s[14:15]
	v_lshlrev_b64 v[64:65], 12, v[80:81]
	v_lshl_add_u64 v[64:65], v[166:167], 0, v[64:65]
	global_load_dwordx4 v[76:79], v[64:65], off
	global_load_dwordx4 v[72:75], v[64:65], off offset:64
	global_load_dwordx4 v[68:71], v[64:65], off offset:512
	s_nop 0
	global_load_dwordx4 v[64:67], v[64:65], off offset:576
	v_lshlrev_b64 v[100:101], 10, v[82:83]
	v_lshl_add_u64 v[100:101], v[100:101], 0, v[162:163]
	v_lshl_add_u64 v[102:103], v[100:101], 2, s[78:79]
	v_lshlrev_b64 v[100:101], 1, v[100:101]
	v_lshl_add_u64 v[104:105], s[2:3], 0, v[100:101]
	s_waitcnt vmcnt(0)
	v_or_b32_e32 v106, 32, v100
	v_mov_b32_e32 v107, v101
	v_or_b32_e32 v108, 0x100, v100
	v_mov_b32_e32 v109, v101
	v_or_b32_e32 v100, 0x120, v100
	v_lshl_add_u64 v[106:107], s[2:3], 0, v[106:107]
	v_lshl_add_u64 v[108:109], s[2:3], 0, v[108:109]
	s_waitcnt vmcnt(0)
	v_pk_add_f32 v[60:61], v[60:61], v[84:85]
	v_pk_add_f32 v[56:57], v[56:57], v[88:89]
	v_pk_add_f32 v[52:53], v[52:53], v[92:93]
	v_mul_f32_e32 v88, v60, v60
	v_mul_f32_e32 v89, v56, v56
	v_pk_add_f32 v[62:63], v[62:63], v[86:87]
	v_pk_add_f32 v[58:59], v[58:59], v[90:91]
	v_pk_add_f32 v[84:85], v[48:49], v[96:97]
	v_mul_f32_e32 v90, v52, v52
	v_fmac_f32_e32 v88, v61, v61
	v_fmac_f32_e32 v89, v57, v57
	v_pk_add_f32 v[54:55], v[54:55], v[94:95]
	v_mul_f32_e32 v91, v84, v84
	v_fmac_f32_e32 v90, v53, v53
	v_fmac_f32_e32 v88, v62, v62
	v_fmac_f32_e32 v89, v58, v58
	v_pk_add_f32 v[86:87], v[50:51], v[98:99]
	v_cvt_pk_bf16_f32 v48, v60, v61
	v_fmac_f32_e32 v91, v85, v85
	v_fmac_f32_e32 v90, v54, v54
	v_fmac_f32_e32 v88, v63, v63
	v_fmac_f32_e32 v89, v59, v59
	global_store_dwordx4 v[102:103], v[60:63], off
	v_cvt_pk_bf16_f32 v49, v62, v63
	s_nop 1
	v_mov_b32_e32 v240, v48
	v_mov_b32_e32 v241, v49
	v_lshl_add_u64 v[244:245], v[104:105], 0, v[246:247]
	v_fmac_f32_e32 v91, v86, v86
	v_fmac_f32_e32 v90, v55, v55
	v_add_f32_e32 v48, v88, v89
	v_add_f32_e32 v48, v48, v90
	v_fmac_f32_e32 v91, v87, v87
	v_add_f32_e32 v48, v48, v91
	ds_bpermute_b32 v49, v188, v48
	v_cvt_pk_bf16_f32 v50, v56, v57
	v_cvt_pk_bf16_f32 v51, v58, v59
	v_cvt_pk_bf16_f32 v60, v52, v53
	global_store_dwordx4 v[102:103], v[56:59], off offset:64
	v_mov_b32_e32 v242, v50
	v_mov_b32_e32 v243, v51
	s_nop 1
	v_permlane16_swap_b32 v240, v242
	v_permlane16_swap_b32 v241, v243
	global_store_dwordx4 v[244:245], v[240:243], off
	s_waitcnt lgkmcnt(0)
	v_add_f32_e32 v48, v48, v49
	ds_bpermute_b32 v49, v116, v48
	v_cvt_pk_bf16_f32 v61, v54, v55
	v_lshl_add_u64 v[50:51], s[2:3], 0, v[100:101]
	global_store_dwordx4 v[102:103], v[52:55], off offset:512
	s_nop 1
	v_mov_b32_e32 v240, v60
	v_mov_b32_e32 v241, v61
	v_lshl_add_u64 v[244:245], v[108:109], 0, v[246:247]
	global_store_dwordx4 v[102:103], v[84:87], off offset:576
	v_cvt_pk_bf16_f32 v52, v84, v85
	v_cvt_pk_bf16_f32 v53, v86, v87
	v_mov_b32_e32 v242, v52
	v_mov_b32_e32 v243, v53
	s_nop 1
	v_permlane16_swap_b32 v240, v242
	v_permlane16_swap_b32 v241, v243
	global_store_dwordx4 v[244:245], v[240:243], off
	s_and_saveexec_b64 s[30:31], s[6:7]
	s_cbranch_execz .LBB0_2175
	v_lshlrev_b64 v[50:51], 6, v[82:83]
	v_lshl_add_u64 v[50:51], s[4:5], 0, v[50:51]
	v_lshl_add_u64 v[50:51], s[28:29], 2, v[50:51]
	s_lshl_b32 s12, s53, 2
	v_lshl_add_u64 v[50:51], v[50:51], 0, s[12:13]
	s_waitcnt lgkmcnt(0)
	v_add_f32_e32 v48, v48, v49
	flat_store_dword v[50:51], v48
.LBB0_2175:
	s_or_b64 exec, exec, s[30:31]
	s_waitcnt lgkmcnt(0)
	v_lshlrev_b64 v[48:49], 10, v[80:81]
	v_lshl_add_u64 v[48:49], v[48:49], 0, v[162:163]
	v_lshl_add_u64 v[50:51], v[48:49], 2, s[78:79]
	v_lshlrev_b64 v[48:49], 1, v[48:49]
	v_pk_add_f32 v[46:47], v[46:47], v[78:79]
	v_pk_add_f32 v[44:45], v[44:45], v[76:77]
	v_lshl_add_u64 v[52:53], s[2:3], 0, v[48:49]
	global_store_dwordx4 v[50:51], v[44:47], off
	v_cvt_pk_bf16_f32 v54, v44, v45
	v_cvt_pk_bf16_f32 v55, v46, v47
	s_nop 1
	v_mov_b32_e32 v240, v54
	v_mov_b32_e32 v241, v55
	v_lshl_add_u64 v[244:245], v[52:53], 0, v[246:247]
	v_mul_f32_e32 v52, v44, v44
	v_fmac_f32_e32 v52, v45, v45
	v_pk_add_f32 v[42:43], v[42:43], v[74:75]
	v_pk_add_f32 v[40:41], v[40:41], v[72:73]
	v_fmac_f32_e32 v52, v46, v46
	global_store_dwordx4 v[50:51], v[40:43], off offset:64
	v_or_b32_e32 v44, 32, v48
	v_mov_b32_e32 v45, v49
	v_cvt_pk_bf16_f32 v46, v40, v41
	v_mul_f32_e32 v40, v40, v40
	v_lshl_add_u64 v[44:45], s[2:3], 0, v[44:45]
	v_fmac_f32_e32 v40, v41, v41
	v_pk_add_f32 v[38:39], v[38:39], v[70:71]
	v_pk_add_f32 v[36:37], v[36:37], v[68:69]
	v_fmac_f32_e32 v52, v47, v47
	v_cvt_pk_bf16_f32 v47, v42, v43
	v_mov_b32_e32 v242, v46
	v_mov_b32_e32 v243, v47
	s_nop 1
	v_permlane16_swap_b32 v240, v242
	v_permlane16_swap_b32 v241, v243
	global_store_dwordx4 v[244:245], v[240:243], off
	v_fmac_f32_e32 v40, v42, v42
	global_store_dwordx4 v[50:51], v[36:39], off offset:512
	v_cvt_pk_bf16_f32 v42, v36, v37
	v_fmac_f32_e32 v40, v43, v43
	v_add_f32_e32 v43, v52, v40
	v_mul_f32_e32 v36, v36, v36
	v_fmac_f32_e32 v36, v37, v37
	v_fmac_f32_e32 v36, v38, v38
	v_fmac_f32_e32 v36, v39, v39
	v_add_f32_e32 v43, v43, v36
	v_pk_add_f32 v[36:37], v[34:35], v[66:67]
	v_pk_add_f32 v[34:35], v[32:33], v[64:65]
	v_or_b32_e32 v40, 0x100, v48
	v_mul_f32_e32 v32, v34, v34
	v_fmac_f32_e32 v32, v35, v35
	v_fmac_f32_e32 v32, v36, v36
	v_fmac_f32_e32 v32, v37, v37
	v_add_f32_e32 v32, v43, v32
	ds_bpermute_b32 v33, v188, v32
	v_mov_b32_e32 v41, v49
	v_or_b32_e32 v48, 0x120, v48
	v_lshl_add_u64 v[40:41], s[2:3], 0, v[40:41]
	v_cvt_pk_bf16_f32 v43, v38, v39
	s_waitcnt lgkmcnt(0)
	v_add_f32_e32 v32, v32, v33
	ds_bpermute_b32 v33, v116, v32
	v_lshl_add_u64 v[38:39], s[2:3], 0, v[48:49]
	s_nop 1
	v_mov_b32_e32 v240, v42
	v_mov_b32_e32 v241, v43
	v_lshl_add_u64 v[244:245], v[40:41], 0, v[246:247]
	global_store_dwordx4 v[50:51], v[34:37], off offset:576
	s_nop 1
	v_cvt_pk_bf16_f32 v34, v34, v35
	v_cvt_pk_bf16_f32 v35, v36, v37
	v_mov_b32_e32 v242, v34
	v_mov_b32_e32 v243, v35
	s_nop 1
	v_permlane16_swap_b32 v240, v242
	v_permlane16_swap_b32 v241, v243
	global_store_dwordx4 v[244:245], v[240:243], off
	s_and_saveexec_b64 s[30:31], s[6:7]
	s_cbranch_execz .LBB0_2177
	v_lshlrev_b64 v[34:35], 6, v[80:81]
	v_lshl_add_u64 v[34:35], s[4:5], 0, v[34:35]
	v_lshl_add_u64 v[34:35], s[28:29], 2, v[34:35]
	s_lshl_b32 s12, s53, 2
	v_lshl_add_u64 v[34:35], v[34:35], 0, s[12:13]
	s_waitcnt lgkmcnt(0)
	v_add_f32_e32 v32, v32, v33
	flat_store_dword v[34:35], v32
.LBB0_2177:
	s_or_b64 exec, exec, s[30:31]
	v_lshl_add_u64 v[50:51], v[164:165], 0, s[16:17]
	s_waitcnt lgkmcnt(0)
	v_lshlrev_b64 v[32:33], 12, v[50:51]
	v_lshl_add_u64 v[32:33], v[166:167], 0, v[32:33]
	global_load_dwordx4 v[52:55], v[32:33], off
	global_load_dwordx4 v[56:59], v[32:33], off offset:64
	global_load_dwordx4 v[60:63], v[32:33], off offset:512
	global_load_dwordx4 v[64:67], v[32:33], off offset:576
	v_lshl_add_u64 v[48:49], v[164:165], 0, s[18:19]
	v_lshlrev_b64 v[32:33], 12, v[48:49]
	v_lshl_add_u64 v[32:33], v[166:167], 0, v[32:33]
	global_load_dwordx4 v[44:47], v[32:33], off
	global_load_dwordx4 v[40:43], v[32:33], off offset:64
	global_load_dwordx4 v[36:39], v[32:33], off offset:512
	s_nop 0
	global_load_dwordx4 v[32:35], v[32:33], off offset:576
	v_lshlrev_b64 v[68:69], 10, v[50:51]
	v_lshl_add_u64 v[68:69], v[68:69], 0, v[162:163]
	v_lshl_add_u64 v[70:71], v[68:69], 2, s[78:79]
	v_lshlrev_b64 v[68:69], 1, v[68:69]
	v_lshl_add_u64 v[72:73], s[2:3], 0, v[68:69]
	s_waitcnt vmcnt(0)
	v_or_b32_e32 v74, 32, v68
	v_mov_b32_e32 v75, v69
	v_or_b32_e32 v76, 0x100, v68
	v_mov_b32_e32 v77, v69
	v_or_b32_e32 v68, 0x120, v68
	v_lshl_add_u64 v[74:75], s[2:3], 0, v[74:75]
	v_lshl_add_u64 v[76:77], s[2:3], 0, v[76:77]
	s_waitcnt vmcnt(0)
	v_pk_add_f32 v[28:29], v[28:29], v[52:53]
	v_pk_add_f32 v[24:25], v[24:25], v[56:57]
	v_pk_add_f32 v[20:21], v[20:21], v[60:61]
	v_mul_f32_e32 v56, v28, v28
	v_mul_f32_e32 v57, v24, v24
	v_pk_add_f32 v[30:31], v[30:31], v[54:55]
	v_pk_add_f32 v[26:27], v[26:27], v[58:59]
	v_pk_add_f32 v[52:53], v[16:17], v[64:65]
	v_mul_f32_e32 v58, v20, v20
	v_fmac_f32_e32 v56, v29, v29
	v_fmac_f32_e32 v57, v25, v25
	v_pk_add_f32 v[22:23], v[22:23], v[62:63]
	v_mul_f32_e32 v59, v52, v52
	v_fmac_f32_e32 v58, v21, v21
	v_fmac_f32_e32 v56, v30, v30
	v_fmac_f32_e32 v57, v26, v26
	v_pk_add_f32 v[54:55], v[18:19], v[66:67]
	v_cvt_pk_bf16_f32 v16, v28, v29
	v_fmac_f32_e32 v59, v53, v53
	v_fmac_f32_e32 v58, v22, v22
	v_fmac_f32_e32 v56, v31, v31
	v_fmac_f32_e32 v57, v27, v27
	global_store_dwordx4 v[70:71], v[28:31], off
	v_cvt_pk_bf16_f32 v17, v30, v31
	s_nop 1
	v_mov_b32_e32 v240, v16
	v_mov_b32_e32 v241, v17
	v_lshl_add_u64 v[244:245], v[72:73], 0, v[246:247]
	v_fmac_f32_e32 v59, v54, v54
	v_fmac_f32_e32 v58, v23, v23
	v_add_f32_e32 v16, v56, v57
	v_add_f32_e32 v16, v16, v58
	v_fmac_f32_e32 v59, v55, v55
	v_add_f32_e32 v16, v16, v59
	ds_bpermute_b32 v17, v188, v16
	v_cvt_pk_bf16_f32 v18, v24, v25
	v_cvt_pk_bf16_f32 v19, v26, v27
	v_cvt_pk_bf16_f32 v28, v20, v21
	global_store_dwordx4 v[70:71], v[24:27], off offset:64
	v_mov_b32_e32 v242, v18
	v_mov_b32_e32 v243, v19
	s_nop 1
	v_permlane16_swap_b32 v240, v242
	v_permlane16_swap_b32 v241, v243
	global_store_dwordx4 v[244:245], v[240:243], off
	s_waitcnt lgkmcnt(0)
	v_add_f32_e32 v16, v16, v17
	ds_bpermute_b32 v17, v116, v16
	v_cvt_pk_bf16_f32 v29, v22, v23
	v_lshl_add_u64 v[18:19], s[2:3], 0, v[68:69]
	global_store_dwordx4 v[70:71], v[20:23], off offset:512
	s_nop 1
	v_mov_b32_e32 v240, v28
	v_mov_b32_e32 v241, v29
	v_lshl_add_u64 v[244:245], v[76:77], 0, v[246:247]
	global_store_dwordx4 v[70:71], v[52:55], off offset:576
	v_cvt_pk_bf16_f32 v20, v52, v53
	v_cvt_pk_bf16_f32 v21, v54, v55
	v_mov_b32_e32 v242, v20
	v_mov_b32_e32 v243, v21
	s_nop 1
	v_permlane16_swap_b32 v240, v242
	v_permlane16_swap_b32 v241, v243
	global_store_dwordx4 v[244:245], v[240:243], off
	s_and_saveexec_b64 s[30:31], s[6:7]
	s_cbranch_execz .LBB0_2179
	v_lshlrev_b64 v[18:19], 6, v[50:51]
	v_lshl_add_u64 v[18:19], s[4:5], 0, v[18:19]
	v_lshl_add_u64 v[18:19], s[28:29], 2, v[18:19]
	s_lshl_b32 s12, s53, 2
	v_lshl_add_u64 v[18:19], v[18:19], 0, s[12:13]
	s_waitcnt lgkmcnt(0)
	v_add_f32_e32 v16, v16, v17
	flat_store_dword v[18:19], v16
.LBB0_2179:
	s_or_b64 exec, exec, s[30:31]
	s_waitcnt lgkmcnt(0)
	v_lshlrev_b64 v[16:17], 10, v[48:49]
	v_lshl_add_u64 v[16:17], v[16:17], 0, v[162:163]
	v_lshl_add_u64 v[18:19], v[16:17], 2, s[78:79]
	v_lshlrev_b64 v[16:17], 1, v[16:17]
	v_pk_add_f32 v[14:15], v[14:15], v[46:47]
	v_pk_add_f32 v[12:13], v[12:13], v[44:45]
	v_lshl_add_u64 v[20:21], s[2:3], 0, v[16:17]
	global_store_dwordx4 v[18:19], v[12:15], off
	v_cvt_pk_bf16_f32 v22, v12, v13
	v_cvt_pk_bf16_f32 v23, v14, v15
	s_nop 1
	v_mov_b32_e32 v240, v22
	v_mov_b32_e32 v241, v23
	v_lshl_add_u64 v[244:245], v[20:21], 0, v[246:247]
	v_mul_f32_e32 v20, v12, v12
	v_fmac_f32_e32 v20, v13, v13
	v_pk_add_f32 v[10:11], v[10:11], v[42:43]
	v_pk_add_f32 v[8:9], v[8:9], v[40:41]
	v_fmac_f32_e32 v20, v14, v14
	global_store_dwordx4 v[18:19], v[8:11], off offset:64
	v_or_b32_e32 v12, 32, v16
	v_mov_b32_e32 v13, v17
	v_cvt_pk_bf16_f32 v14, v8, v9
	v_mul_f32_e32 v8, v8, v8
	v_lshl_add_u64 v[12:13], s[2:3], 0, v[12:13]
	v_fmac_f32_e32 v8, v9, v9
	v_pk_add_f32 v[6:7], v[6:7], v[38:39]
	v_pk_add_f32 v[4:5], v[4:5], v[36:37]
	v_fmac_f32_e32 v20, v15, v15
	v_cvt_pk_bf16_f32 v15, v10, v11
	v_mov_b32_e32 v242, v14
	v_mov_b32_e32 v243, v15
	s_nop 1
	v_permlane16_swap_b32 v240, v242
	v_permlane16_swap_b32 v241, v243
	global_store_dwordx4 v[244:245], v[240:243], off
	v_fmac_f32_e32 v8, v10, v10
	global_store_dwordx4 v[18:19], v[4:7], off offset:512
	v_cvt_pk_bf16_f32 v10, v4, v5
	v_fmac_f32_e32 v8, v11, v11
	v_add_f32_e32 v11, v20, v8
	v_mul_f32_e32 v4, v4, v4
	v_fmac_f32_e32 v4, v5, v5
	v_fmac_f32_e32 v4, v6, v6
	v_fmac_f32_e32 v4, v7, v7
	v_add_f32_e32 v11, v11, v4
	v_pk_add_f32 v[4:5], v[2:3], v[34:35]
	v_pk_add_f32 v[2:3], v[0:1], v[32:33]
	v_or_b32_e32 v8, 0x100, v16
	v_mul_f32_e32 v0, v2, v2
	v_fmac_f32_e32 v0, v3, v3
	v_fmac_f32_e32 v0, v4, v4
	v_fmac_f32_e32 v0, v5, v5
	v_add_f32_e32 v0, v11, v0
	ds_bpermute_b32 v1, v188, v0
	v_mov_b32_e32 v9, v17
	v_or_b32_e32 v16, 0x120, v16
	v_lshl_add_u64 v[8:9], s[2:3], 0, v[8:9]
	v_cvt_pk_bf16_f32 v11, v6, v7
	s_waitcnt lgkmcnt(0)
	v_add_f32_e32 v0, v0, v1
	ds_bpermute_b32 v1, v116, v0
	v_lshl_add_u64 v[6:7], s[2:3], 0, v[16:17]
	s_nop 1
	v_mov_b32_e32 v240, v10
	v_mov_b32_e32 v241, v11
	v_lshl_add_u64 v[244:245], v[8:9], 0, v[246:247]
	global_store_dwordx4 v[18:19], v[2:5], off offset:576
	s_nop 1
	v_cvt_pk_bf16_f32 v2, v2, v3
	v_cvt_pk_bf16_f32 v3, v4, v5
	v_mov_b32_e32 v242, v2
	v_mov_b32_e32 v243, v3
	s_nop 1
	v_permlane16_swap_b32 v240, v242
	v_permlane16_swap_b32 v241, v243
	global_store_dwordx4 v[244:245], v[240:243], off
	s_and_saveexec_b64 s[30:31], s[6:7]
	s_cbranch_execz .LBB0_2156
	v_lshlrev_b64 v[2:3], 6, v[48:49]
	v_lshl_add_u64 v[2:3], s[4:5], 0, v[2:3]
	v_lshl_add_u64 v[2:3], s[28:29], 2, v[2:3]
	s_lshl_b32 s12, s53, 2
	v_lshl_add_u64 v[2:3], v[2:3], 0, s[12:13]
	s_waitcnt lgkmcnt(0)
	v_add_f32_e32 v0, v0, v1
	flat_store_dword v[2:3], v0
	s_branch .LBB0_2156
